# speedup vs baseline: 1.0006x; 1.0006x over previous
; #define PG8_STAGE(bufoff, gbase, voff) do { _Pragma("unroll") for (int _i = 0; _i < 2; ++_i) \
;         __builtin_amdgcn_global_load_lds((const unsigned*)((const char*)(gbase) + (voff)[_i]), (LAS unsigned*)(lds + (bufoff) + ldsw + _i * 8192), 16, 0, 0); } while (0)
; #define PG8_LDA(dst, b, h) do { _Pragma("unroll") for (int m = 0; m < 4; ++m) _Pragma("unroll") for (int k = 0; k < 2; ++k) dst[m][k] = *(const LAS bf16x8*)(lds + PG8_SA(b, h) + aoff + m * 2048 + k * 1024); } while (0)
; #define PG8_LDB(dst, b, h) do { _Pragma("unroll") for (int n = 0; n < 2; ++n) _Pragma("unroll") for (int k = 0; k < 2; ++k) dst[n][k] = *(const LAS bf16x8*)(lds + PG8_SB(b, h) + boff + n * 2048 + k * 1024); } while (0)
; #define PG8_MMA(ai, bj, At, Bt) do { __builtin_amdgcn_s_setprio(1); _Pragma("unroll") for (int m = 0; m < 4; ++m) _Pragma("unroll") for (int n = 0; n < 2; ++n) _Pragma("unroll") for (int k = 0; k < 2; ++k) \
;         acc[ai][bj][m][n] = __builtin_amdgcn_mfma_f32_16x16x32_bf16(Bt[n][k], At[m][k], acc[ai][bj][m][n], 0, 0, 0); __builtin_amdgcn_s_setprio(0); } while (0)
; #define PG8_WAIT_V(n) asm volatile("s_waitcnt vmcnt(" #n ")" ::: "memory")
; #define PG8_WAIT_L(n) asm volatile("s_waitcnt lgkmcnt(" #n ")" ::: "memory")
; #define PG8_BAR __builtin_amdgcn_s_barrier()
; #define PG8_SCHED __builtin_amdgcn_sched_barrier(0)
; template <class Epi>
; DEV void gemm_phase(LAS unsigned char* lds, const Gemm g, const StaticOrder& S, const Epi& E) {
;     ...
;             PG8_LDB(B0, 0, 0); PG8_SCHED; PG8_LDA(At, 0, 0); PG8_STAGE(PG8_SA(1, 1), a1 + hstep, voffA);
;             PG8_WAIT_L(8); PG8_BAR; PG8_WAIT_L(0); PG8_MMA(0, 0, At, B0); PG8_BAR; PG8_SCHED;
;             PG8_LDB(B1, 0, 1); PG8_STAGE(PG8_SB(0, 0), b2, voffB);
;             PG8_BAR; PG8_WAIT_L(0); PG8_MMA(0, 1, At, B1); PG8_BAR;
;             PG8_LDA(At, 0, 1); PG8_STAGE(PG8_SA(0, 0), a2, voffA);
;             PG8_BAR; PG8_WAIT_L(0); PG8_MMA(1, 0, At, B0); PG8_BAR; PG8_SCHED;
;             PG8_STAGE(PG8_SB(0, 1), b2 + hstep, voffB);
;             PG8_WAIT_V(6); PG8_BAR; PG8_MMA(1, 1, At, B1); PG8_BAR;
.LBB0_61:
	s_add_u32 s28, s26, 0xfff80080
	s_addc_u32 s29, s27, -1
	s_add_i32 s49, 0, 0x10000
	v_add_u32_e32 v140, s49, v178
	ds_read_b128 v[128:131], v140
	ds_read_b128 v[132:135], v140 offset:1024
	ds_read_b128 v[136:139], v140 offset:2048
	ds_read_b128 v[140:143], v140 offset:3072
	s_cmp_eq_u32 s48, 28
	s_cselect_b32 s31, s15, s29
	s_cselect_b32 s30, s19, s28
	s_cselect_b32 s29, s17, s47
	s_cselect_b32 s28, s25, s46
	s_add_i32 m0, s37, 0xc000
	ds_read_b128 v[154:157], v181
	ds_read_b128 v[174:177], v181 offset:1024
	ds_read_b128 v[182:185], v181 offset:2048
	ds_read_b128 v[186:189], v181 offset:3072
	ds_read_b128 v[190:193], v181 offset:4096
	ds_read_b128 v[194:197], v181 offset:5120
	ds_read_b128 v[214:217], v181 offset:6144
	ds_read_b128 v[218:221], v181 offset:7168
	global_load_lds_dwordx4 v150, s[26:27]
	s_add_i32 m0, s37, 0xe000
	s_nop 0
	global_load_lds_dwordx4 v152, s[26:27]
	s_waitcnt lgkmcnt(8)
	s_barrier
	s_waitcnt lgkmcnt(0)
	v_mfma_f32_16x16x32_bf16 v[124:127], v[128:131], v[154:157], v[124:127]
	v_mfma_f32_16x16x32_bf16 v[120:123], v[136:139], v[154:157], v[120:123]
	v_mfma_f32_16x16x32_bf16 v[108:111], v[128:131], v[182:185], v[108:111]
	v_mfma_f32_16x16x32_bf16 v[104:107], v[136:139], v[182:185], v[104:107]
	v_mfma_f32_16x16x32_bf16 v[92:95], v[128:131], v[190:193], v[92:95]
	v_mfma_f32_16x16x32_bf16 v[88:91], v[136:139], v[190:193], v[88:91]
	v_mfma_f32_16x16x32_bf16 v[76:79], v[128:131], v[214:217], v[76:79]
	v_mfma_f32_16x16x32_bf16 v[72:75], v[136:139], v[214:217], v[72:75]
	v_mfma_f32_16x16x32_bf16 v[124:127], v[132:135], v[174:177], v[124:127]
	v_mfma_f32_16x16x32_bf16 v[120:123], v[140:143], v[174:177], v[120:123]
	v_mfma_f32_16x16x32_bf16 v[108:111], v[132:135], v[186:189], v[108:111]
	v_mfma_f32_16x16x32_bf16 v[104:107], v[140:143], v[186:189], v[104:107]
	v_mfma_f32_16x16x32_bf16 v[92:95], v[132:135], v[194:197], v[92:95]
	v_mfma_f32_16x16x32_bf16 v[88:91], v[140:143], v[194:197], v[88:91]
	v_mfma_f32_16x16x32_bf16 v[76:79], v[132:135], v[218:221], v[76:79]
	v_mfma_f32_16x16x32_bf16 v[72:75], v[140:143], v[218:221], v[72:75]
	s_barrier
	s_add_i32 s52, 0, 0x14000
	v_add_u32_e32 v158, s52, v178
	s_add_i32 s49, s49, s36
	ds_read_b128 v[222:225], v158
	ds_read_b128 v[226:229], v158 offset:1024
	ds_read_b128 v[230:233], v158 offset:2048
	ds_read_b128 v[234:237], v158 offset:3072
	v_lshl_add_u64 v[158:159], s[28:29], 0, v[160:161]
	s_mov_b32 m0, s49
	v_lshl_add_u64 v[238:239], s[28:29], 0, v[148:149]
	global_load_lds_dwordx4 v160, s[28:29]
	s_add_i32 m0, s49, 0x2000
	s_nop 0
	global_load_lds_dwordx4 v148, s[28:29]
	s_barrier
	s_waitcnt lgkmcnt(0)
	v_mfma_f32_16x16x32_bf16 v[116:119], v[222:225], v[154:157], v[116:119]
	v_mfma_f32_16x16x32_bf16 v[112:115], v[230:233], v[154:157], v[112:115]
	v_mfma_f32_16x16x32_bf16 v[100:103], v[222:225], v[182:185], v[100:103]
	v_mfma_f32_16x16x32_bf16 v[96:99], v[230:233], v[182:185], v[96:99]
	v_mfma_f32_16x16x32_bf16 v[84:87], v[222:225], v[190:193], v[84:87]
	v_mfma_f32_16x16x32_bf16 v[80:83], v[230:233], v[190:193], v[80:83]
	v_mfma_f32_16x16x32_bf16 v[68:71], v[222:225], v[214:217], v[68:71]
	v_mfma_f32_16x16x32_bf16 v[64:67], v[230:233], v[214:217], v[64:67]
	v_mfma_f32_16x16x32_bf16 v[116:119], v[226:229], v[174:177], v[116:119]
	v_mfma_f32_16x16x32_bf16 v[112:115], v[234:237], v[174:177], v[112:115]
	v_mfma_f32_16x16x32_bf16 v[100:103], v[226:229], v[186:189], v[100:103]
	v_mfma_f32_16x16x32_bf16 v[96:99], v[234:237], v[186:189], v[96:99]
	v_mfma_f32_16x16x32_bf16 v[84:87], v[226:229], v[194:197], v[84:87]
	v_mfma_f32_16x16x32_bf16 v[80:83], v[234:237], v[194:197], v[80:83]
	v_mfma_f32_16x16x32_bf16 v[68:71], v[226:229], v[218:221], v[68:71]
	v_mfma_f32_16x16x32_bf16 v[64:67], v[234:237], v[218:221], v[64:67]
	s_barrier
	s_mov_b32 m0, s37
	v_lshl_add_u64 v[240:241], s[30:31], 0, v[144:145]
	ds_read_b128 v[154:157], v181 offset:16384
	ds_read_b128 v[174:177], v181 offset:17408
	ds_read_b128 v[182:185], v181 offset:18432
	ds_read_b128 v[186:189], v181 offset:19456
	ds_read_b128 v[190:193], v181 offset:20480
	ds_read_b128 v[194:197], v181 offset:21504
	ds_read_b128 v[214:217], v181 offset:22528
	ds_read_b128 v[218:221], v181 offset:23552
	global_load_lds_dwordx4 v144, s[30:31]
	v_lshl_add_u64 v[242:243], s[30:31], 0, v[146:147]
	s_mov_b32 m0, s38
	s_nop 0
	global_load_lds_dwordx4 v146, s[30:31]
	s_barrier
	s_waitcnt lgkmcnt(0)
	v_mfma_f32_16x16x32_bf16 v[60:63], v[128:131], v[154:157], v[60:63]
	v_mfma_f32_16x16x32_bf16 v[56:59], v[136:139], v[154:157], v[56:59]
	v_mfma_f32_16x16x32_bf16 v[44:47], v[128:131], v[182:185], v[44:47]
	v_mfma_f32_16x16x32_bf16 v[40:43], v[136:139], v[182:185], v[40:43]
	v_mfma_f32_16x16x32_bf16 v[28:31], v[128:131], v[190:193], v[28:31]
	v_mfma_f32_16x16x32_bf16 v[24:27], v[136:139], v[190:193], v[24:27]
	v_mfma_f32_16x16x32_bf16 v[12:15], v[128:131], v[214:217], v[12:15]
	v_mfma_f32_16x16x32_bf16 v[8:11], v[136:139], v[214:217], v[8:11]
	v_mfma_f32_16x16x32_bf16 v[60:63], v[132:135], v[174:177], v[60:63]
	v_mfma_f32_16x16x32_bf16 v[56:59], v[140:143], v[174:177], v[56:59]
	v_mfma_f32_16x16x32_bf16 v[44:47], v[132:135], v[186:189], v[44:47]
	v_mfma_f32_16x16x32_bf16 v[40:43], v[140:143], v[186:189], v[40:43]
	v_mfma_f32_16x16x32_bf16 v[28:31], v[132:135], v[194:197], v[28:31]
	v_mfma_f32_16x16x32_bf16 v[24:27], v[140:143], v[194:197], v[24:27]
	v_mfma_f32_16x16x32_bf16 v[12:15], v[132:135], v[218:221], v[12:15]
	v_mfma_f32_16x16x32_bf16 v[8:11], v[140:143], v[218:221], v[8:11]
	s_barrier
	s_add_u32 s50, s28, 0x80000
	s_addc_u32 s51, s29, 0
	s_add_i32 s49, s52, s36
	s_mov_b32 m0, s49
	s_nop 0
	global_load_lds_dwordx4 v160, s[50:51]
	s_add_i32 m0, s49, 0x2000
	s_nop 0
	global_load_lds_dwordx4 v148, s[50:51]
	s_waitcnt vmcnt(6)
	s_barrier
; #define PG8_STAGE(bufoff, gbase, voff) do { _Pragma("unroll") for (int _i = 0; _i < 2; ++_i) \
;         __builtin_amdgcn_global_load_lds((const unsigned*)((const char*)(gbase) + (voff)[_i]), (LAS unsigned*)(lds + (bufoff) + ldsw + _i * 8192), 16, 0, 0); } while (0)
; #define PG8_LDA(dst, b, h) do { _Pragma("unroll") for (int m = 0; m < 4; ++m) _Pragma("unroll") for (int k = 0; k < 2; ++k) dst[m][k] = *(const LAS bf16x8*)(lds + PG8_SA(b, h) + aoff + m * 2048 + k * 1024); } while (0)
; #define PG8_LDB(dst, b, h) do { _Pragma("unroll") for (int n = 0; n < 2; ++n) _Pragma("unroll") for (int k = 0; k < 2; ++k) dst[n][k] = *(const LAS bf16x8*)(lds + PG8_SB(b, h) + boff + n * 2048 + k * 1024); } while (0)
; #define PG8_MMA(ai, bj, At, Bt) do { __builtin_amdgcn_s_setprio(1); _Pragma("unroll") for (int m = 0; m < 4; ++m) _Pragma("unroll") for (int n = 0; n < 2; ++n) _Pragma("unroll") for (int k = 0; k < 2; ++k) \
;         acc[ai][bj][m][n] = __builtin_amdgcn_mfma_f32_16x16x32_bf16(Bt[n][k], At[m][k], acc[ai][bj][m][n], 0, 0, 0); __builtin_amdgcn_s_setprio(0); } while (0)
; #define PG8_WAIT_V(n) asm volatile("s_waitcnt vmcnt(" #n ")" ::: "memory")
; #define PG8_WAIT_L(n) asm volatile("s_waitcnt lgkmcnt(" #n ")" ::: "memory")
; #define PG8_BAR __builtin_amdgcn_s_barrier()
; #define PG8_SCHED __builtin_amdgcn_sched_barrier(0)
; template <class Epi>
; DEV void gemm_phase(LAS unsigned char* lds, const Gemm g, const StaticOrder& S, const Epi& E) {
;     ...
;             PG8_WAIT_V(6); PG8_BAR; PG8_MMA(1, 1, At, B1); PG8_BAR;
;             PG8_LDB(B0, 1, 0); PG8_SCHED; PG8_LDA(At, 1, 0); PG8_STAGE(PG8_SA(0, 1), a2 + hstep, voffA);
;             PG8_WAIT_L(8); PG8_BAR; PG8_WAIT_L(0); PG8_MMA(0, 0, At, B0); PG8_BAR; PG8_SCHED;
;             PG8_LDB(B1, 1, 1); PG8_STAGE(PG8_SB(1, 0), b3, voffB);
;             PG8_BAR; PG8_WAIT_L(0); PG8_MMA(0, 1, At, B1); PG8_BAR;
;             PG8_LDA(At, 1, 1); PG8_STAGE(PG8_SA(1, 0), a3, voffA);
;             PG8_BAR; PG8_WAIT_L(0); PG8_MMA(1, 0, At, B0); PG8_BAR; PG8_SCHED;
;             PG8_STAGE(PG8_SB(1, 1), b3 + hstep, voffB);
	v_mfma_f32_16x16x32_bf16 v[52:55], v[222:225], v[154:157], v[52:55]
	v_mfma_f32_16x16x32_bf16 v[48:51], v[230:233], v[154:157], v[48:51]
	v_mfma_f32_16x16x32_bf16 v[36:39], v[222:225], v[182:185], v[36:39]
	v_mfma_f32_16x16x32_bf16 v[32:35], v[230:233], v[182:185], v[32:35]
	v_mfma_f32_16x16x32_bf16 v[20:23], v[222:225], v[190:193], v[20:23]
	v_mfma_f32_16x16x32_bf16 v[16:19], v[230:233], v[190:193], v[16:19]
	v_mfma_f32_16x16x32_bf16 v[4:7], v[222:225], v[214:217], v[4:7]
	v_mfma_f32_16x16x32_bf16 v[0:3], v[230:233], v[214:217], v[0:3]
	v_mfma_f32_16x16x32_bf16 v[52:55], v[226:229], v[174:177], v[52:55]
	v_mfma_f32_16x16x32_bf16 v[48:51], v[234:237], v[174:177], v[48:51]
	v_mfma_f32_16x16x32_bf16 v[36:39], v[226:229], v[186:189], v[36:39]
	v_mfma_f32_16x16x32_bf16 v[32:35], v[234:237], v[186:189], v[32:35]
	v_mfma_f32_16x16x32_bf16 v[20:23], v[226:229], v[194:197], v[20:23]
	v_mfma_f32_16x16x32_bf16 v[16:19], v[234:237], v[194:197], v[16:19]
	v_mfma_f32_16x16x32_bf16 v[4:7], v[226:229], v[218:221], v[4:7]
	v_mfma_f32_16x16x32_bf16 v[0:3], v[234:237], v[218:221], v[0:3]
	s_barrier
	s_add_i32 s49, 0, 0x18000
	v_add_u32_e32 v140, s49, v178
	ds_read_b128 v[128:131], v140
	ds_read_b128 v[132:135], v140 offset:1024
	ds_read_b128 v[136:139], v140 offset:2048
	ds_read_b128 v[140:143], v140 offset:3072
	s_add_u32 s30, s30, 0x80000
	s_addc_u32 s31, s31, 0
	s_mov_b32 m0, s39
	ds_read_b128 v[154:157], v181 offset:32768
	ds_read_b128 v[174:177], v181 offset:33792
	ds_read_b128 v[182:185], v181 offset:34816
	ds_read_b128 v[186:189], v181 offset:35840
	ds_read_b128 v[190:193], v181 offset:36864
	ds_read_b128 v[194:197], v181 offset:37888
	ds_read_b128 v[214:217], v181 offset:38912
	ds_read_b128 v[218:221], v181 offset:39936
	global_load_lds_dwordx4 v144, s[30:31]
	s_mov_b32 m0, s40
	s_nop 0
	global_load_lds_dwordx4 v146, s[30:31]
	s_waitcnt lgkmcnt(8)
	s_barrier
	s_waitcnt lgkmcnt(0)
	v_mfma_f32_16x16x32_bf16 v[124:127], v[128:131], v[154:157], v[124:127]
	v_mfma_f32_16x16x32_bf16 v[120:123], v[136:139], v[154:157], v[120:123]
	v_mfma_f32_16x16x32_bf16 v[108:111], v[128:131], v[182:185], v[108:111]
	v_mfma_f32_16x16x32_bf16 v[104:107], v[136:139], v[182:185], v[104:107]
	v_mfma_f32_16x16x32_bf16 v[92:95], v[128:131], v[190:193], v[92:95]
	v_mfma_f32_16x16x32_bf16 v[88:91], v[136:139], v[190:193], v[88:91]
	v_mfma_f32_16x16x32_bf16 v[76:79], v[128:131], v[214:217], v[76:79]
	v_mfma_f32_16x16x32_bf16 v[72:75], v[136:139], v[214:217], v[72:75]
	v_mfma_f32_16x16x32_bf16 v[124:127], v[132:135], v[174:177], v[124:127]
	v_mfma_f32_16x16x32_bf16 v[120:123], v[140:143], v[174:177], v[120:123]
	v_mfma_f32_16x16x32_bf16 v[108:111], v[132:135], v[186:189], v[108:111]
	v_mfma_f32_16x16x32_bf16 v[104:107], v[140:143], v[186:189], v[104:107]
	v_mfma_f32_16x16x32_bf16 v[92:95], v[132:135], v[194:197], v[92:95]
	v_mfma_f32_16x16x32_bf16 v[88:91], v[140:143], v[194:197], v[88:91]
	v_mfma_f32_16x16x32_bf16 v[76:79], v[132:135], v[218:221], v[76:79]
	v_mfma_f32_16x16x32_bf16 v[72:75], v[140:143], v[218:221], v[72:75]
	s_barrier
	s_add_i32 s30, 0, 0x1c000
	s_add_i32 s31, s49, s36
	v_add_u32_e32 v234, s30, v178
	v_lshl_add_u64 v[158:159], v[158:159], 0, s[2:3]
	s_mov_b32 m0, s31
	ds_read_b128 v[222:225], v234
	ds_read_b128 v[226:229], v234 offset:1024
	ds_read_b128 v[230:233], v234 offset:2048
	ds_read_b128 v[234:237], v234 offset:3072
	global_load_lds_dwordx4 v[158:159], off
	v_lshl_add_u64 v[158:159], v[238:239], 0, s[2:3]
	s_add_i32 m0, s31, 0x2000
	s_nop 0
	global_load_lds_dwordx4 v[158:159], off
	s_barrier
	s_waitcnt lgkmcnt(0)
	v_mfma_f32_16x16x32_bf16 v[116:119], v[222:225], v[154:157], v[116:119]
	v_mfma_f32_16x16x32_bf16 v[112:115], v[230:233], v[154:157], v[112:115]
	v_mfma_f32_16x16x32_bf16 v[100:103], v[222:225], v[182:185], v[100:103]
	v_mfma_f32_16x16x32_bf16 v[96:99], v[230:233], v[182:185], v[96:99]
	v_mfma_f32_16x16x32_bf16 v[84:87], v[222:225], v[190:193], v[84:87]
	v_mfma_f32_16x16x32_bf16 v[80:83], v[230:233], v[190:193], v[80:83]
	v_mfma_f32_16x16x32_bf16 v[68:71], v[222:225], v[214:217], v[68:71]
	v_mfma_f32_16x16x32_bf16 v[64:67], v[230:233], v[214:217], v[64:67]
	v_mfma_f32_16x16x32_bf16 v[116:119], v[226:229], v[174:177], v[116:119]
	v_mfma_f32_16x16x32_bf16 v[112:115], v[234:237], v[174:177], v[112:115]
	v_mfma_f32_16x16x32_bf16 v[100:103], v[226:229], v[186:189], v[100:103]
	v_mfma_f32_16x16x32_bf16 v[96:99], v[234:237], v[186:189], v[96:99]
	v_mfma_f32_16x16x32_bf16 v[84:87], v[226:229], v[194:197], v[84:87]
	v_mfma_f32_16x16x32_bf16 v[80:83], v[234:237], v[194:197], v[80:83]
	v_mfma_f32_16x16x32_bf16 v[68:71], v[226:229], v[218:221], v[68:71]
	v_mfma_f32_16x16x32_bf16 v[64:67], v[234:237], v[218:221], v[64:67]
	s_barrier
	s_mov_b32 m0, s41
	v_lshl_add_u64 v[158:159], v[240:241], 0, s[2:3]
	ds_read_b128 v[154:157], v181 offset:49152
	ds_read_b128 v[174:177], v181 offset:50176
	ds_read_b128 v[182:185], v181 offset:51200
	ds_read_b128 v[186:189], v181 offset:52224
	ds_read_b128 v[190:193], v181 offset:53248
	ds_read_b128 v[194:197], v181 offset:54272
	ds_read_b128 v[214:217], v181 offset:55296
	ds_read_b128 v[218:221], v181 offset:56320
	global_load_lds_dwordx4 v[158:159], off
	v_lshl_add_u64 v[158:159], v[242:243], 0, s[2:3]
	s_mov_b32 m0, s42
	s_nop 0
	global_load_lds_dwordx4 v[158:159], off
	s_barrier
; DEV bf16x8 pack8(f32x4 a, f32x4 b) { u32x4 w; w.x = cvt_pk_bf16(a[0], a[1]); w.y = cvt_pk_bf16(a[2], a[3]); w.z = cvt_pk_bf16(b[0], b[1]); w.w = cvt_pk_bf16(b[2], b[3]); return __builtin_bit_cast(bf16x8, w); }
; #define PG8_WAIT_V(n) asm volatile("s_waitcnt vmcnt(" #n ")" ::: "memory")
; #define PG8_WAIT_L(n) asm volatile("s_waitcnt lgkmcnt(" #n ")" ::: "memory")
; #define PG8_BAR __builtin_amdgcn_s_barrier()
; #define PG8_SCHED __builtin_amdgcn_sched_barrier(0)
; template <class Epi>
; DEV void gemm_phase(LAS unsigned char* lds, const Gemm g, const StaticOrder& S, const Epi& E) {
;     ...
;             PG8_BAR; PG8_WAIT_L(0); PG8_MMA(1, 0, At, B0); PG8_BAR; PG8_SCHED;
;             PG8_STAGE(PG8_SB(1, 1), b3 + hstep, voffB);
;             PG8_WAIT_V(6); PG8_BAR; PG8_MMA(1, 1, At, B1); PG8_BAR;
;     DEV void operator()(AccRef acc, const pg8::Unit& u, int wr, int wc, int fr, int fq) const {
;         const int row0 = u.pm * 256 + wr * 64 + fr, col0 = u.pn * 256 + wc * 32 + 8 * fq;
; #pragma unroll
;         for (int am = 0; am < 4; ++am) { const int ai = am >> 1, m0 = (am & 1) * 2;
;             f32x4 bv[4][2][2];
; #pragma unroll
;             for (int m = m0; m < m0 + 2; ++m)
; #pragma unroll
;                 for (int bj = 0; bj < 2; ++bj)
; #pragma unroll
;                     for (int n = 0; n < 2; ++n) bv[m][bj][n] = *(const f32x4*)(base + (size_t)(row0 + ai * 128 + m * 16) * 2048 + col0 + bj * 128 + n * 4);
; #pragma unroll
;             for (int m = m0; m < m0 + 2; ++m) { const size_t off = (size_t)(row0 + ai * 128 + m * 16) * 2048 + col0; float sq = 0.f;
; #pragma unroll
;                 for (int bj = 0; bj < 2; ++bj) { const f32x4 o0 = bv[m][bj][0] + scale * acc[ai][bj][m][0], o1 = bv[m][bj][1] + scale * acc[ai][bj][m][1];
;                     *(f32x4*)(out + off + bj * 128) = o0; *(f32x4*)(out + off + bj * 128 + 4) = o1;
;                     if (xb) { *(u32x4*)(xb + off + bj * 128) = __builtin_bit_cast(u32x4, pack8(o0, o1));
;                         sq += (o0[0] * o0[0] + o0[1] * o0[1] + o0[2] * o0[2] + o0[3] * o0[3]) + (o1[0] * o1[0] + o1[1] * o1[1] + o1[2] * o1[2] + o1[3] * o1[3]); } }
;                 if (ssout) { sq += __shfl_xor(sq, 16); sq += __shfl_xor(sq, 32);
;                     if (fq == 0) { if (red) red[(ai * 128 + wr * 64 + m * 16 + fr) * 4 + wc] = sq; else atomicAdd(ssout + (size_t)(row0 + ai * 128 + m * 16) * 8 + u.pn, sq); } } }
	s_waitcnt lgkmcnt(0)
	v_mfma_f32_16x16x32_bf16 v[60:63], v[128:131], v[154:157], v[60:63]
	v_mfma_f32_16x16x32_bf16 v[56:59], v[136:139], v[154:157], v[56:59]
	v_mfma_f32_16x16x32_bf16 v[44:47], v[128:131], v[182:185], v[44:47]
	v_mfma_f32_16x16x32_bf16 v[40:43], v[136:139], v[182:185], v[40:43]
	v_mfma_f32_16x16x32_bf16 v[28:31], v[128:131], v[190:193], v[28:31]
	v_mfma_f32_16x16x32_bf16 v[24:27], v[136:139], v[190:193], v[24:27]
	v_mfma_f32_16x16x32_bf16 v[12:15], v[128:131], v[214:217], v[12:15]
	v_mfma_f32_16x16x32_bf16 v[8:11], v[136:139], v[214:217], v[8:11]
	v_mfma_f32_16x16x32_bf16 v[60:63], v[132:135], v[174:177], v[60:63]
	v_mfma_f32_16x16x32_bf16 v[56:59], v[140:143], v[174:177], v[56:59]
	v_mfma_f32_16x16x32_bf16 v[44:47], v[132:135], v[186:189], v[44:47]
	v_mfma_f32_16x16x32_bf16 v[40:43], v[140:143], v[186:189], v[40:43]
	v_mfma_f32_16x16x32_bf16 v[28:31], v[132:135], v[194:197], v[28:31]
	v_mfma_f32_16x16x32_bf16 v[24:27], v[140:143], v[194:197], v[24:27]
	v_mfma_f32_16x16x32_bf16 v[12:15], v[132:135], v[218:221], v[12:15]
	v_mfma_f32_16x16x32_bf16 v[8:11], v[140:143], v[218:221], v[8:11]
	s_barrier
	s_add_u32 s28, s28, 0x80080
	s_addc_u32 s29, s29, 0
	s_add_i32 s30, s30, s36
	s_mov_b32 m0, s30
	s_nop 0
	global_load_lds_dwordx4 v160, s[28:29]
	s_add_i32 m0, s30, 0x2000
	s_nop 0
	global_load_lds_dwordx4 v148, s[28:29]
	s_waitcnt vmcnt(6)
	s_barrier
	v_mfma_f32_16x16x32_bf16 v[52:55], v[222:225], v[154:157], v[52:55]
	v_mfma_f32_16x16x32_bf16 v[48:51], v[230:233], v[154:157], v[48:51]
	v_mfma_f32_16x16x32_bf16 v[36:39], v[222:225], v[182:185], v[36:39]
	v_mfma_f32_16x16x32_bf16 v[32:35], v[230:233], v[182:185], v[32:35]
	v_mfma_f32_16x16x32_bf16 v[20:23], v[222:225], v[190:193], v[20:23]
	v_mfma_f32_16x16x32_bf16 v[16:19], v[230:233], v[190:193], v[16:19]
	v_mfma_f32_16x16x32_bf16 v[4:7], v[222:225], v[214:217], v[4:7]
	v_mfma_f32_16x16x32_bf16 v[0:3], v[230:233], v[214:217], v[0:3]
	v_mfma_f32_16x16x32_bf16 v[52:55], v[226:229], v[174:177], v[52:55]
	v_mfma_f32_16x16x32_bf16 v[48:51], v[234:237], v[174:177], v[48:51]
	v_mfma_f32_16x16x32_bf16 v[36:39], v[226:229], v[186:189], v[36:39]
	v_mfma_f32_16x16x32_bf16 v[32:35], v[234:237], v[186:189], v[32:35]
	v_mfma_f32_16x16x32_bf16 v[20:23], v[226:229], v[194:197], v[20:23]
	v_mfma_f32_16x16x32_bf16 v[16:19], v[234:237], v[194:197], v[16:19]
	v_mfma_f32_16x16x32_bf16 v[4:7], v[226:229], v[218:221], v[4:7]
	v_mfma_f32_16x16x32_bf16 v[0:3], v[234:237], v[218:221], v[0:3]
	s_add_i32 s48, s48, 2
	s_add_u32 s26, s26, 0x100
	s_addc_u32 s27, s27, 0
	s_add_u32 s46, s46, 0x100
	s_addc_u32 s47, s47, 0
	s_cmp_gt_u32 s48, 29
	s_barrier
	s_cbranch_scc0 .LBB0_61
	v_lshl_add_u32 v156, s24, 8, v167
	v_lshl_or_b32 v154, s14, 8, v179
	v_readlane_b32 s24, v254, 16
	v_ashrrev_i32_e32 v155, 31, v154
	v_readlane_b32 s25, v254, 17
	v_ashrrev_i32_e32 v157, 31, v156
	v_lshlrev_b64 v[128:129], 13, v[156:157]
	v_lshl_add_u64 v[158:159], v[154:155], 2, s[24:25]
	v_lshl_add_u64 v[214:215], v[158:159], 0, v[128:129]
	global_load_dwordx4 v[182:185], v[214:215], off offset:16
	global_load_dwordx4 v[186:189], v[214:215], off
	global_load_dwordx4 v[190:193], v[214:215], off offset:528
	global_load_dwordx4 v[194:197], v[214:215], off offset:512
	v_or_b32_e32 v174, 16, v156
	v_ashrrev_i32_e32 v175, 31, v174
	v_lshlrev_b64 v[128:129], 13, v[174:175]
	v_lshl_add_u64 v[176:177], v[158:159], 0, v[128:129]
	global_load_dwordx4 v[136:139], v[176:177], off offset:16
	global_load_dwordx4 v[140:143], v[176:177], off
	global_load_dwordx4 v[128:131], v[176:177], off offset:528
	global_load_dwordx4 v[132:135], v[176:177], off offset:512
	v_lshlrev_b64 v[216:217], 11, v[156:157]
	v_readlane_b32 s24, v250, 9
	v_lshl_add_u64 v[216:217], v[216:217], 0, v[154:155]
	v_readlane_b32 s25, v250, 10
	v_cmp_lt_i32_e32 vcc, v208, v206
	s_ashr_i32 s15, s14, 31
	s_waitcnt vmcnt(0)
	v_pk_add_f32 v[120:121], v[120:121], v[182:183]
	v_pk_add_f32 v[126:127], v[126:127], v[188:189]
	v_pk_add_f32 v[124:125], v[124:125], v[186:187]
	v_pk_add_f32 v[122:123], v[122:123], v[184:185]
	global_store_dwordx4 v[214:215], v[124:127], off
	global_store_dwordx4 v[214:215], v[120:123], off offset:16
	v_cvt_pk_bf16_f32 v184, v120, v121
	v_cvt_pk_bf16_f32 v182, v124, v125
	v_mul_f32_e32 v121, v121, v121
	v_cvt_pk_bf16_f32 v183, v126, v127
	v_cvt_pk_bf16_f32 v185, v122, v123
	v_lshl_add_u64 v[186:187], v[216:217], 1, s[24:25]
	v_fmac_f32_e32 v121, v120, v120
	v_pk_add_f32 v[118:119], v[118:119], v[196:197]
	v_pk_add_f32 v[116:117], v[116:117], v[194:195]
	v_pk_add_f32 v[112:113], v[112:113], v[190:191]
	global_store_dwordx4 v[186:187], v[182:185], off
	v_mul_f32_e32 v125, v125, v125
	v_fmac_f32_e32 v121, v122, v122
	v_pk_add_f32 v[114:115], v[114:115], v[192:193]
	global_store_dwordx4 v[214:215], v[116:119], off offset:512
	global_store_dwordx4 v[214:215], v[112:115], off offset:528
	v_cvt_pk_bf16_f32 v120, v116, v117
	v_cvt_pk_bf16_f32 v122, v112, v113
	v_mul_f32_e32 v117, v117, v117
	v_mul_f32_e32 v113, v113, v113
	v_fmac_f32_e32 v125, v124, v124
	v_fmac_f32_e32 v117, v116, v116
	v_fmac_f32_e32 v113, v112, v112
	v_fmac_f32_e32 v125, v126, v126
	v_fmac_f32_e32 v117, v118, v118
	v_fmac_f32_e32 v113, v114, v114
	v_fmac_f32_e32 v125, v127, v127
	v_fmac_f32_e32 v121, v123, v123
	v_fmac_f32_e32 v117, v119, v119
	v_fmac_f32_e32 v113, v115, v115
	v_add_f32_e32 v124, v125, v121
	v_add_f32_e32 v112, v117, v113
	v_cndmask_b32_e32 v113, v204, v208, vcc
	v_cvt_pk_bf16_f32 v121, v118, v119
	v_add_f32_e32 v112, v124, v112
	v_lshlrev_b32_e32 v118, 2, v113
	ds_bpermute_b32 v113, v118, v112
	v_cmp_lt_i32_e32 vcc, v207, v206
	v_cvt_pk_bf16_f32 v123, v114, v115
	global_store_dwordx4 v[186:187], v[120:123], off offset:256
	s_waitcnt lgkmcnt(0)
	v_add_f32_e32 v112, v112, v113
	v_cndmask_b32_e32 v113, v204, v207, vcc
	v_lshlrev_b32_e32 v119, 2, v113
	ds_bpermute_b32 v113, v119, v112
	s_and_saveexec_b64 s[24:25], s[6:7]
	s_cbranch_execz .LBB0_67
	s_waitcnt lgkmcnt(0)
	v_add_f32_e32 v112, v112, v113
	s_mov_b64 s[26:27], -1
	s_and_b64 vcc, exec, s[12:13]
	s_cbranch_vccz .LBB0_65
	v_readlane_b32 s26, v250, 37
	v_lshlrev_b64 v[114:115], 5, v[156:157]
	v_readlane_b32 s27, v250, 38
	s_nop 1
	v_lshl_add_u64 v[114:115], s[26:27], 0, v[114:115]
	v_lshl_add_u64 v[114:115], s[14:15], 2, v[114:115]
	global_atomic_add_f32 v[114:115], v112, off
	s_mov_b64 s[26:27], 0

; #define PG8_STAGE(bufoff, gbase, voff) do { _Pragma("unroll") for (int _i = 0; _i < 2; ++_i) \
;         __builtin_amdgcn_global_load_lds((const unsigned*)((const char*)(gbase) + (voff)[_i]), (LAS unsigned*)(lds + (bufoff) + ldsw + _i * 8192), 16, 0, 0); } while (0)
; #define PG8_LDA(dst, b, h) do { _Pragma("unroll") for (int m = 0; m < 4; ++m) _Pragma("unroll") for (int k = 0; k < 2; ++k) dst[m][k] = *(const LAS bf16x8*)(lds + PG8_SA(b, h) + aoff + m * 2048 + k * 1024); } while (0)
; #define PG8_LDB(dst, b, h) do { _Pragma("unroll") for (int n = 0; n < 2; ++n) _Pragma("unroll") for (int k = 0; k < 2; ++k) dst[n][k] = *(const LAS bf16x8*)(lds + PG8_SB(b, h) + boff + n * 2048 + k * 1024); } while (0)
; #define PG8_MMA(ai, bj, At, Bt) do { __builtin_amdgcn_s_setprio(1); _Pragma("unroll") for (int m = 0; m < 4; ++m) _Pragma("unroll") for (int n = 0; n < 2; ++n) _Pragma("unroll") for (int k = 0; k < 2; ++k) \
;         acc[ai][bj][m][n] = __builtin_amdgcn_mfma_f32_16x16x32_bf16(Bt[n][k], At[m][k], acc[ai][bj][m][n], 0, 0, 0); __builtin_amdgcn_s_setprio(0); } while (0)
; #define PG8_WAIT_V(n) asm volatile("s_waitcnt vmcnt(" #n ")" ::: "memory")
; #define PG8_WAIT_L(n) asm volatile("s_waitcnt lgkmcnt(" #n ")" ::: "memory")
; #define PG8_BAR __builtin_amdgcn_s_barrier()
; #define PG8_SCHED __builtin_amdgcn_sched_barrier(0)
; template <class Epi>
; DEV void gemm_phase(LAS unsigned char* lds, const Gemm g, const StaticOrder& S, const Epi& E) {
;     ...
;             PG8_LDB(B0, 0, 0); PG8_SCHED; PG8_LDA(At, 0, 0); PG8_STAGE(PG8_SA(1, 1), a1 + hstep, voffA);
;             PG8_WAIT_L(8); PG8_BAR; PG8_WAIT_L(0); PG8_MMA(0, 0, At, B0); PG8_BAR; PG8_SCHED;
;             PG8_LDB(B1, 0, 1); PG8_STAGE(PG8_SB(0, 0), b2, voffB);
;             PG8_BAR; PG8_WAIT_L(0); PG8_MMA(0, 1, At, B1); PG8_BAR;
;             PG8_LDA(At, 0, 1); PG8_STAGE(PG8_SA(0, 0), a2, voffA);
;             PG8_BAR; PG8_WAIT_L(0); PG8_MMA(1, 0, At, B0); PG8_BAR; PG8_SCHED;
;             PG8_STAGE(PG8_SB(0, 1), b2 + hstep, voffB);
;             PG8_WAIT_V(6); PG8_BAR; PG8_MMA(1, 1, At, B1); PG8_BAR;
.LBB0_152:
	s_add_u32 s20, s18, 0xfff80080
	s_addc_u32 s21, s19, -1
	s_add_i32 s41, 0, 0x10000
	v_add_u32_e32 v140, s41, v176
	ds_read_b128 v[128:131], v140
	ds_read_b128 v[132:135], v140 offset:1024
	ds_read_b128 v[136:139], v140 offset:2048
	ds_read_b128 v[140:143], v140 offset:3072
	s_cmp_eq_u32 s40, 28
	s_cselect_b32 s23, s5, s21
	s_cselect_b32 s22, s11, s20
	s_cselect_b32 s21, s9, s39
	s_cselect_b32 s20, s37, s38
	s_add_i32 m0, s17, 0xc000
	ds_read_b128 v[180:183], v178
	ds_read_b128 v[184:187], v178 offset:1024
	ds_read_b128 v[188:191], v178 offset:2048
	ds_read_b128 v[192:195], v178 offset:3072
	ds_read_b128 v[214:217], v178 offset:4096
	ds_read_b128 v[218:221], v178 offset:5120
	ds_read_b128 v[222:225], v178 offset:6144
	ds_read_b128 v[226:229], v178 offset:7168
	global_load_lds_dwordx4 v154, s[18:19]
	s_add_i32 m0, s17, 0xe000
	s_nop 0
	global_load_lds_dwordx4 v156, s[18:19]
	s_waitcnt lgkmcnt(8)
	s_barrier
	s_waitcnt lgkmcnt(0)
	v_mfma_f32_16x16x32_bf16 v[124:127], v[128:131], v[180:183], v[124:127]
	v_mfma_f32_16x16x32_bf16 v[120:123], v[136:139], v[180:183], v[120:123]
	v_mfma_f32_16x16x32_bf16 v[108:111], v[128:131], v[188:191], v[108:111]
	v_mfma_f32_16x16x32_bf16 v[104:107], v[136:139], v[188:191], v[104:107]
	v_mfma_f32_16x16x32_bf16 v[92:95], v[128:131], v[214:217], v[92:95]
	v_mfma_f32_16x16x32_bf16 v[88:91], v[136:139], v[214:217], v[88:91]
	v_mfma_f32_16x16x32_bf16 v[76:79], v[128:131], v[222:225], v[76:79]
	v_mfma_f32_16x16x32_bf16 v[72:75], v[136:139], v[222:225], v[72:75]
	v_mfma_f32_16x16x32_bf16 v[124:127], v[132:135], v[184:187], v[124:127]
	v_mfma_f32_16x16x32_bf16 v[120:123], v[140:143], v[184:187], v[120:123]
	v_mfma_f32_16x16x32_bf16 v[108:111], v[132:135], v[192:195], v[108:111]
	v_mfma_f32_16x16x32_bf16 v[104:107], v[140:143], v[192:195], v[104:107]
	v_mfma_f32_16x16x32_bf16 v[92:95], v[132:135], v[218:221], v[92:95]
	v_mfma_f32_16x16x32_bf16 v[88:91], v[140:143], v[218:221], v[88:91]
	v_mfma_f32_16x16x32_bf16 v[76:79], v[132:135], v[226:229], v[76:79]
	v_mfma_f32_16x16x32_bf16 v[72:75], v[140:143], v[226:229], v[72:75]
	s_barrier
	s_add_i32 s44, 0, 0x14000
	v_add_u32_e32 v158, s44, v176
	s_add_i32 s41, s41, s26
	ds_read_b128 v[230:233], v158
	ds_read_b128 v[234:237], v158 offset:1024
	ds_read_b128 v[238:241], v158 offset:2048
	ds_read_b128 v[242:245], v158 offset:3072
	v_lshl_add_u64 v[158:159], s[20:21], 0, v[160:161]
	s_mov_b32 m0, s41
	v_lshl_add_u64 v[174:175], s[20:21], 0, v[144:145]
	global_load_lds_dwordx4 v160, s[20:21]
	s_add_i32 m0, s41, 0x2000
	s_nop 0
	global_load_lds_dwordx4 v144, s[20:21]
	s_barrier
	s_waitcnt lgkmcnt(0)
	v_mfma_f32_16x16x32_bf16 v[116:119], v[230:233], v[180:183], v[116:119]
	v_mfma_f32_16x16x32_bf16 v[112:115], v[238:241], v[180:183], v[112:115]
	v_mfma_f32_16x16x32_bf16 v[100:103], v[230:233], v[188:191], v[100:103]
	v_mfma_f32_16x16x32_bf16 v[96:99], v[238:241], v[188:191], v[96:99]
	v_mfma_f32_16x16x32_bf16 v[84:87], v[230:233], v[214:217], v[84:87]
	v_mfma_f32_16x16x32_bf16 v[80:83], v[238:241], v[214:217], v[80:83]
	v_mfma_f32_16x16x32_bf16 v[68:71], v[230:233], v[222:225], v[68:71]
	v_mfma_f32_16x16x32_bf16 v[64:67], v[238:241], v[222:225], v[64:67]
	v_mfma_f32_16x16x32_bf16 v[116:119], v[234:237], v[184:187], v[116:119]
	v_mfma_f32_16x16x32_bf16 v[112:115], v[242:245], v[184:187], v[112:115]
	v_mfma_f32_16x16x32_bf16 v[100:103], v[234:237], v[192:195], v[100:103]
	v_mfma_f32_16x16x32_bf16 v[96:99], v[242:245], v[192:195], v[96:99]
	v_mfma_f32_16x16x32_bf16 v[84:87], v[234:237], v[218:221], v[84:87]
	v_mfma_f32_16x16x32_bf16 v[80:83], v[242:245], v[218:221], v[80:83]
	v_mfma_f32_16x16x32_bf16 v[68:71], v[234:237], v[226:229], v[68:71]
	v_mfma_f32_16x16x32_bf16 v[64:67], v[242:245], v[226:229], v[64:67]
	s_barrier
	s_mov_b32 m0, s17
	v_lshl_add_u64 v[196:197], s[22:23], 0, v[160:161]
	ds_read_b128 v[180:183], v178 offset:16384
	ds_read_b128 v[184:187], v178 offset:17408
	ds_read_b128 v[188:191], v178 offset:18432
	ds_read_b128 v[192:195], v178 offset:19456
	ds_read_b128 v[214:217], v178 offset:20480
	ds_read_b128 v[218:221], v178 offset:21504
	ds_read_b128 v[222:225], v178 offset:22528
	ds_read_b128 v[226:229], v178 offset:23552
	global_load_lds_dwordx4 v160, s[22:23]
	v_lshl_add_u64 v[246:247], s[22:23], 0, v[144:145]
	s_mov_b32 m0, s27
	s_nop 0
	global_load_lds_dwordx4 v144, s[22:23]
	s_barrier
	s_waitcnt lgkmcnt(0)
	v_mfma_f32_16x16x32_bf16 v[60:63], v[128:131], v[180:183], v[60:63]
	v_mfma_f32_16x16x32_bf16 v[56:59], v[136:139], v[180:183], v[56:59]
	v_mfma_f32_16x16x32_bf16 v[44:47], v[128:131], v[188:191], v[44:47]
	v_mfma_f32_16x16x32_bf16 v[40:43], v[136:139], v[188:191], v[40:43]
	v_mfma_f32_16x16x32_bf16 v[28:31], v[128:131], v[214:217], v[28:31]
	v_mfma_f32_16x16x32_bf16 v[24:27], v[136:139], v[214:217], v[24:27]
	v_mfma_f32_16x16x32_bf16 v[12:15], v[128:131], v[222:225], v[12:15]
	v_mfma_f32_16x16x32_bf16 v[8:11], v[136:139], v[222:225], v[8:11]
	v_mfma_f32_16x16x32_bf16 v[60:63], v[132:135], v[184:187], v[60:63]
	v_mfma_f32_16x16x32_bf16 v[56:59], v[140:143], v[184:187], v[56:59]
	v_mfma_f32_16x16x32_bf16 v[44:47], v[132:135], v[192:195], v[44:47]
	v_mfma_f32_16x16x32_bf16 v[40:43], v[140:143], v[192:195], v[40:43]
	v_mfma_f32_16x16x32_bf16 v[28:31], v[132:135], v[218:221], v[28:31]
	v_mfma_f32_16x16x32_bf16 v[24:27], v[140:143], v[218:221], v[24:27]
	v_mfma_f32_16x16x32_bf16 v[12:15], v[132:135], v[226:229], v[12:15]
	v_mfma_f32_16x16x32_bf16 v[8:11], v[140:143], v[226:229], v[8:11]
	s_barrier
	s_add_u32 s42, s20, 0x80000
	s_addc_u32 s43, s21, 0
	s_add_i32 s41, s44, s26
	s_mov_b32 m0, s41
	s_nop 0
	global_load_lds_dwordx4 v160, s[42:43]
	s_add_i32 m0, s41, 0x2000
	s_nop 0
	global_load_lds_dwordx4 v144, s[42:43]
	s_waitcnt vmcnt(6)
	s_barrier
; #define PG8_STAGE(bufoff, gbase, voff) do { _Pragma("unroll") for (int _i = 0; _i < 2; ++_i) \
;         __builtin_amdgcn_global_load_lds((const unsigned*)((const char*)(gbase) + (voff)[_i]), (LAS unsigned*)(lds + (bufoff) + ldsw + _i * 8192), 16, 0, 0); } while (0)
; #define PG8_LDA(dst, b, h) do { _Pragma("unroll") for (int m = 0; m < 4; ++m) _Pragma("unroll") for (int k = 0; k < 2; ++k) dst[m][k] = *(const LAS bf16x8*)(lds + PG8_SA(b, h) + aoff + m * 2048 + k * 1024); } while (0)
; #define PG8_LDB(dst, b, h) do { _Pragma("unroll") for (int n = 0; n < 2; ++n) _Pragma("unroll") for (int k = 0; k < 2; ++k) dst[n][k] = *(const LAS bf16x8*)(lds + PG8_SB(b, h) + boff + n * 2048 + k * 1024); } while (0)
; #define PG8_MMA(ai, bj, At, Bt) do { __builtin_amdgcn_s_setprio(1); _Pragma("unroll") for (int m = 0; m < 4; ++m) _Pragma("unroll") for (int n = 0; n < 2; ++n) _Pragma("unroll") for (int k = 0; k < 2; ++k) \
;         acc[ai][bj][m][n] = __builtin_amdgcn_mfma_f32_16x16x32_bf16(Bt[n][k], At[m][k], acc[ai][bj][m][n], 0, 0, 0); __builtin_amdgcn_s_setprio(0); } while (0)
; #define PG8_WAIT_V(n) asm volatile("s_waitcnt vmcnt(" #n ")" ::: "memory")
; #define PG8_WAIT_L(n) asm volatile("s_waitcnt lgkmcnt(" #n ")" ::: "memory")
; #define PG8_BAR __builtin_amdgcn_s_barrier()
; #define PG8_SCHED __builtin_amdgcn_sched_barrier(0)
; template <class Epi>
; DEV void gemm_phase(LAS unsigned char* lds, const Gemm g, const StaticOrder& S, const Epi& E) {
;     ...
;             PG8_WAIT_V(6); PG8_BAR; PG8_MMA(1, 1, At, B1); PG8_BAR;
;             PG8_LDB(B0, 1, 0); PG8_SCHED; PG8_LDA(At, 1, 0); PG8_STAGE(PG8_SA(0, 1), a2 + hstep, voffA);
;             PG8_WAIT_L(8); PG8_BAR; PG8_WAIT_L(0); PG8_MMA(0, 0, At, B0); PG8_BAR; PG8_SCHED;
;             PG8_LDB(B1, 1, 1); PG8_STAGE(PG8_SB(1, 0), b3, voffB);
;             PG8_BAR; PG8_WAIT_L(0); PG8_MMA(0, 1, At, B1); PG8_BAR;
;             PG8_LDA(At, 1, 1); PG8_STAGE(PG8_SA(1, 0), a3, voffA);
;             PG8_BAR; PG8_WAIT_L(0); PG8_MMA(1, 0, At, B0); PG8_BAR; PG8_SCHED;
	v_mfma_f32_16x16x32_bf16 v[52:55], v[230:233], v[180:183], v[52:55]
	v_mfma_f32_16x16x32_bf16 v[48:51], v[238:241], v[180:183], v[48:51]
	v_mfma_f32_16x16x32_bf16 v[36:39], v[230:233], v[188:191], v[36:39]
	v_mfma_f32_16x16x32_bf16 v[32:35], v[238:241], v[188:191], v[32:35]
	v_mfma_f32_16x16x32_bf16 v[20:23], v[230:233], v[214:217], v[20:23]
	v_mfma_f32_16x16x32_bf16 v[16:19], v[238:241], v[214:217], v[16:19]
	v_mfma_f32_16x16x32_bf16 v[4:7], v[230:233], v[222:225], v[4:7]
	v_mfma_f32_16x16x32_bf16 v[0:3], v[238:241], v[222:225], v[0:3]
	v_mfma_f32_16x16x32_bf16 v[52:55], v[234:237], v[184:187], v[52:55]
	v_mfma_f32_16x16x32_bf16 v[48:51], v[242:245], v[184:187], v[48:51]
	v_mfma_f32_16x16x32_bf16 v[36:39], v[234:237], v[192:195], v[36:39]
	v_mfma_f32_16x16x32_bf16 v[32:35], v[242:245], v[192:195], v[32:35]
	v_mfma_f32_16x16x32_bf16 v[20:23], v[234:237], v[218:221], v[20:23]
	v_mfma_f32_16x16x32_bf16 v[16:19], v[242:245], v[218:221], v[16:19]
	v_mfma_f32_16x16x32_bf16 v[4:7], v[234:237], v[226:229], v[4:7]
	v_mfma_f32_16x16x32_bf16 v[0:3], v[242:245], v[226:229], v[0:3]
	s_barrier
	s_add_i32 s41, 0, 0x18000
	v_add_u32_e32 v140, s41, v176
	ds_read_b128 v[128:131], v140
	ds_read_b128 v[132:135], v140 offset:1024
	ds_read_b128 v[136:139], v140 offset:2048
	ds_read_b128 v[140:143], v140 offset:3072
	s_add_u32 s22, s22, 0x80000
	s_addc_u32 s23, s23, 0
	s_mov_b32 m0, s28
	ds_read_b128 v[180:183], v178 offset:32768
	ds_read_b128 v[184:187], v178 offset:33792
	ds_read_b128 v[188:191], v178 offset:34816
	ds_read_b128 v[192:195], v178 offset:35840
	ds_read_b128 v[214:217], v178 offset:36864
	ds_read_b128 v[218:221], v178 offset:37888
	ds_read_b128 v[222:225], v178 offset:38912
	ds_read_b128 v[226:229], v178 offset:39936
	global_load_lds_dwordx4 v160, s[22:23]
	s_mov_b32 m0, s29
	s_nop 0
	global_load_lds_dwordx4 v144, s[22:23]
	s_waitcnt lgkmcnt(8)
	s_barrier
	s_waitcnt lgkmcnt(0)
	v_mfma_f32_16x16x32_bf16 v[124:127], v[128:131], v[180:183], v[124:127]
	v_mfma_f32_16x16x32_bf16 v[120:123], v[136:139], v[180:183], v[120:123]
	v_mfma_f32_16x16x32_bf16 v[108:111], v[128:131], v[188:191], v[108:111]
	v_mfma_f32_16x16x32_bf16 v[104:107], v[136:139], v[188:191], v[104:107]
	v_mfma_f32_16x16x32_bf16 v[92:95], v[128:131], v[214:217], v[92:95]
	v_mfma_f32_16x16x32_bf16 v[88:91], v[136:139], v[214:217], v[88:91]
	v_mfma_f32_16x16x32_bf16 v[76:79], v[128:131], v[222:225], v[76:79]
	v_mfma_f32_16x16x32_bf16 v[72:75], v[136:139], v[222:225], v[72:75]
	v_mfma_f32_16x16x32_bf16 v[124:127], v[132:135], v[184:187], v[124:127]
	v_mfma_f32_16x16x32_bf16 v[120:123], v[140:143], v[184:187], v[120:123]
	v_mfma_f32_16x16x32_bf16 v[108:111], v[132:135], v[192:195], v[108:111]
	v_mfma_f32_16x16x32_bf16 v[104:107], v[140:143], v[192:195], v[104:107]
	v_mfma_f32_16x16x32_bf16 v[92:95], v[132:135], v[218:221], v[92:95]
	v_mfma_f32_16x16x32_bf16 v[88:91], v[140:143], v[218:221], v[88:91]
	v_mfma_f32_16x16x32_bf16 v[76:79], v[132:135], v[226:229], v[76:79]
	v_mfma_f32_16x16x32_bf16 v[72:75], v[140:143], v[226:229], v[72:75]
	s_barrier
	s_add_i32 s22, 0, 0x1c000
	s_add_i32 s23, s41, s26
	v_add_u32_e32 v179, s22, v176
	v_lshl_add_u64 v[158:159], v[158:159], 0, s[2:3]
	s_mov_b32 m0, s23
	ds_read_b128 v[230:233], v179
	ds_read_b128 v[234:237], v179 offset:1024
	ds_read_b128 v[238:241], v179 offset:2048
	ds_read_b128 v[242:245], v179 offset:3072
	global_load_lds_dwordx4 v[158:159], off
	v_lshl_add_u64 v[158:159], v[174:175], 0, s[2:3]
	s_add_i32 m0, s23, 0x2000
	s_nop 0
	global_load_lds_dwordx4 v[158:159], off
	s_barrier
	s_waitcnt lgkmcnt(0)
	v_mfma_f32_16x16x32_bf16 v[116:119], v[230:233], v[180:183], v[116:119]
	v_mfma_f32_16x16x32_bf16 v[112:115], v[238:241], v[180:183], v[112:115]
	v_mfma_f32_16x16x32_bf16 v[100:103], v[230:233], v[188:191], v[100:103]
	v_mfma_f32_16x16x32_bf16 v[96:99], v[238:241], v[188:191], v[96:99]
	v_mfma_f32_16x16x32_bf16 v[84:87], v[230:233], v[214:217], v[84:87]
	v_mfma_f32_16x16x32_bf16 v[80:83], v[238:241], v[214:217], v[80:83]
	v_mfma_f32_16x16x32_bf16 v[68:71], v[230:233], v[222:225], v[68:71]
	v_mfma_f32_16x16x32_bf16 v[64:67], v[238:241], v[222:225], v[64:67]
	v_mfma_f32_16x16x32_bf16 v[116:119], v[234:237], v[184:187], v[116:119]
	v_mfma_f32_16x16x32_bf16 v[112:115], v[242:245], v[184:187], v[112:115]
	v_mfma_f32_16x16x32_bf16 v[100:103], v[234:237], v[192:195], v[100:103]
	v_mfma_f32_16x16x32_bf16 v[96:99], v[242:245], v[192:195], v[96:99]
	v_mfma_f32_16x16x32_bf16 v[84:87], v[234:237], v[218:221], v[84:87]
	v_mfma_f32_16x16x32_bf16 v[80:83], v[242:245], v[218:221], v[80:83]
	v_mfma_f32_16x16x32_bf16 v[68:71], v[234:237], v[226:229], v[68:71]
	v_mfma_f32_16x16x32_bf16 v[64:67], v[242:245], v[226:229], v[64:67]
	s_barrier
; #define PG8_STAGE(bufoff, gbase, voff) do { _Pragma("unroll") for (int _i = 0; _i < 2; ++_i) \
;         __builtin_amdgcn_global_load_lds((const unsigned*)((const char*)(gbase) + (voff)[_i]), (LAS unsigned*)(lds + (bufoff) + ldsw + _i * 8192), 16, 0, 0); } while (0)
; #define PG8_LDA(dst, b, h) do { _Pragma("unroll") for (int m = 0; m < 4; ++m) _Pragma("unroll") for (int k = 0; k < 2; ++k) dst[m][k] = *(const LAS bf16x8*)(lds + PG8_SA(b, h) + aoff + m * 2048 + k * 1024); } while (0)
; #define PG8_MMA(ai, bj, At, Bt) do { __builtin_amdgcn_s_setprio(1); _Pragma("unroll") for (int m = 0; m < 4; ++m) _Pragma("unroll") for (int n = 0; n < 2; ++n) _Pragma("unroll") for (int k = 0; k < 2; ++k) \
;         acc[ai][bj][m][n] = __builtin_amdgcn_mfma_f32_16x16x32_bf16(Bt[n][k], At[m][k], acc[ai][bj][m][n], 0, 0, 0); __builtin_amdgcn_s_setprio(0); } while (0)
; #define PG8_WAIT_V(n) asm volatile("s_waitcnt vmcnt(" #n ")" ::: "memory")
; #define PG8_WAIT_L(n) asm volatile("s_waitcnt lgkmcnt(" #n ")" ::: "memory")
; #define PG8_BAR __builtin_amdgcn_s_barrier()
; #define PG8_SCHED __builtin_amdgcn_sched_barrier(0)
; template <class Epi>
; DEV void gemm_phase(LAS unsigned char* lds, const Gemm g, const StaticOrder& S, const Epi& E) {
;     ...
;             PG8_LDA(At, 1, 1); PG8_STAGE(PG8_SA(1, 0), a3, voffA);
;             PG8_BAR; PG8_WAIT_L(0); PG8_MMA(1, 0, At, B0); PG8_BAR; PG8_SCHED;
;             PG8_STAGE(PG8_SB(1, 1), b3 + hstep, voffB);
;             PG8_WAIT_V(6); PG8_BAR; PG8_MMA(1, 1, At, B1); PG8_BAR;
;     DEV void operator()(AccRef acc, const pg8::Unit& u, int wr, int wc, int fr, int fq) const {
;         const int row0 = u.pm * 256 + wr * 64 + fr, col0 = u.pn * 256 + wc * 32 + 4 * fq;
;         const bool rope = (u.pn < 9) && ((wc & 1) == 0);
; #pragma unroll
;         for (int ai = 0; ai < 2; ++ai)
; #pragma unroll
;             for (int m = 0; m < 4; ++m) { const int row = row0 + ai * 128 + m * 16; u16* rowp = O + (size_t)row * 2560 + col0; const float rs = rowscale(ss, row);
;                 f32x4 cs = (f32x4){1.f, 1.f, 1.f, 1.f}, sn = (f32x4){0.f, 0.f, 0.f, 0.f};
;                 if (rope) { cs = *(const f32x4*)(cosT + row * 8 + 4 * (fq & 1)); sn = *(const f32x4*)(sinT + row * 8 + 4 * (fq & 1)); }
	s_mov_b32 m0, s30
	v_lshl_add_u64 v[158:159], v[196:197], 0, s[2:3]
	ds_read_b128 v[180:183], v178 offset:49152
	ds_read_b128 v[184:187], v178 offset:50176
	ds_read_b128 v[188:191], v178 offset:51200
	ds_read_b128 v[192:195], v178 offset:52224
	ds_read_b128 v[214:217], v178 offset:53248
	ds_read_b128 v[218:221], v178 offset:54272
	ds_read_b128 v[222:225], v178 offset:55296
	ds_read_b128 v[226:229], v178 offset:56320
	global_load_lds_dwordx4 v[158:159], off
	v_lshl_add_u64 v[158:159], v[246:247], 0, s[2:3]
	s_mov_b32 m0, s31
	s_nop 0
	global_load_lds_dwordx4 v[158:159], off
	s_barrier
	s_waitcnt lgkmcnt(0)
	v_mfma_f32_16x16x32_bf16 v[60:63], v[128:131], v[180:183], v[60:63]
	v_mfma_f32_16x16x32_bf16 v[56:59], v[136:139], v[180:183], v[56:59]
	v_mfma_f32_16x16x32_bf16 v[44:47], v[128:131], v[188:191], v[44:47]
	v_mfma_f32_16x16x32_bf16 v[40:43], v[136:139], v[188:191], v[40:43]
	v_mfma_f32_16x16x32_bf16 v[28:31], v[128:131], v[214:217], v[28:31]
	v_mfma_f32_16x16x32_bf16 v[24:27], v[136:139], v[214:217], v[24:27]
	v_mfma_f32_16x16x32_bf16 v[12:15], v[128:131], v[222:225], v[12:15]
	v_mfma_f32_16x16x32_bf16 v[8:11], v[136:139], v[222:225], v[8:11]
	v_mfma_f32_16x16x32_bf16 v[60:63], v[132:135], v[184:187], v[60:63]
	v_mfma_f32_16x16x32_bf16 v[56:59], v[140:143], v[184:187], v[56:59]
	v_mfma_f32_16x16x32_bf16 v[44:47], v[132:135], v[192:195], v[44:47]
	v_mfma_f32_16x16x32_bf16 v[40:43], v[140:143], v[192:195], v[40:43]
	v_mfma_f32_16x16x32_bf16 v[28:31], v[132:135], v[218:221], v[28:31]
	v_mfma_f32_16x16x32_bf16 v[24:27], v[140:143], v[218:221], v[24:27]
	v_mfma_f32_16x16x32_bf16 v[12:15], v[132:135], v[226:229], v[12:15]
	v_mfma_f32_16x16x32_bf16 v[8:11], v[140:143], v[226:229], v[8:11]
	s_barrier
	s_add_u32 s20, s20, 0x80080
	s_addc_u32 s21, s21, 0
	s_add_i32 s22, s22, s26
	s_mov_b32 m0, s22
	s_nop 0
	global_load_lds_dwordx4 v160, s[20:21]
	s_add_i32 m0, s22, 0x2000
	s_nop 0
	global_load_lds_dwordx4 v144, s[20:21]
	s_waitcnt vmcnt(6)
	s_barrier
	v_mfma_f32_16x16x32_bf16 v[52:55], v[230:233], v[180:183], v[52:55]
	v_mfma_f32_16x16x32_bf16 v[48:51], v[238:241], v[180:183], v[48:51]
	v_mfma_f32_16x16x32_bf16 v[36:39], v[230:233], v[188:191], v[36:39]
	v_mfma_f32_16x16x32_bf16 v[32:35], v[238:241], v[188:191], v[32:35]
	v_mfma_f32_16x16x32_bf16 v[20:23], v[230:233], v[214:217], v[20:23]
	v_mfma_f32_16x16x32_bf16 v[16:19], v[238:241], v[214:217], v[16:19]
	v_mfma_f32_16x16x32_bf16 v[4:7], v[230:233], v[222:225], v[4:7]
	v_mfma_f32_16x16x32_bf16 v[0:3], v[238:241], v[222:225], v[0:3]
	v_mfma_f32_16x16x32_bf16 v[52:55], v[234:237], v[184:187], v[52:55]
	v_mfma_f32_16x16x32_bf16 v[48:51], v[242:245], v[184:187], v[48:51]
	v_mfma_f32_16x16x32_bf16 v[36:39], v[234:237], v[192:195], v[36:39]
	v_mfma_f32_16x16x32_bf16 v[32:35], v[242:245], v[192:195], v[32:35]
	v_mfma_f32_16x16x32_bf16 v[20:23], v[234:237], v[218:221], v[20:23]
	v_mfma_f32_16x16x32_bf16 v[16:19], v[242:245], v[218:221], v[16:19]
	v_mfma_f32_16x16x32_bf16 v[4:7], v[234:237], v[226:229], v[4:7]
	v_mfma_f32_16x16x32_bf16 v[0:3], v[242:245], v[226:229], v[0:3]
	s_add_i32 s40, s40, 2
	s_add_u32 s18, s18, 0x100
	s_addc_u32 s19, s19, 0
	s_add_u32 s38, s38, 0x100
	s_addc_u32 s39, s39, 0
	s_cmp_gt_u32 s40, 29
	s_barrier
	s_cbranch_scc0 .LBB0_152
	v_lshl_add_u32 v174, s4, 8, v167
	v_ashrrev_i32_e32 v175, 31, v174
	v_readlane_b32 s20, v250, 47
	v_lshlrev_b64 v[128:129], 5, v[174:175]
	v_readlane_b32 s21, v250, 48
	s_cmp_lt_i32 s16, 9
	s_cselect_b64 s[4:5], -1, 0
	v_lshl_add_u64 v[128:129], s[20:21], 0, v[128:129]
	global_load_dwordx4 v[136:139], v[128:129], off offset:16
	global_load_dwordx4 v[140:143], v[128:129], off
	s_and_b64 s[18:19], s[6:7], s[4:5]
	v_cndmask_b32_e64 v128, 0, 1, s[18:19]
	v_cmp_ne_u32_e64 s[4:5], 1, v128
	s_andn2_b64 vcc, exec, s[18:19]
	s_cbranch_vccnz .LBB0_155
	v_lshlrev_b32_e32 v128, 3, v174
	v_ashrrev_i32_e32 v129, 31, v128
	v_lshlrev_b64 v[128:129], 2, v[128:129]
	v_lshl_add_u64 v[130:131], v[152:153], 0, v[128:129]
	v_lshl_add_u64 v[132:133], v[150:151], 0, v[128:129]
	global_load_dwordx4 v[128:131], v[130:131], off
	s_nop 0
	global_load_dwordx4 v[132:135], v[132:133], off
	s_branch .LBB0_156

; #define PG8_STAGE(bufoff, gbase, voff) do { _Pragma("unroll") for (int _i = 0; _i < 2; ++_i) \
;         __builtin_amdgcn_global_load_lds((const unsigned*)((const char*)(gbase) + (voff)[_i]), (LAS unsigned*)(lds + (bufoff) + ldsw + _i * 8192), 16, 0, 0); } while (0)
; #define PG8_LDA(dst, b, h) do { _Pragma("unroll") for (int m = 0; m < 4; ++m) _Pragma("unroll") for (int k = 0; k < 2; ++k) dst[m][k] = *(const LAS bf16x8*)(lds + PG8_SA(b, h) + aoff + m * 2048 + k * 1024); } while (0)
; #define PG8_LDB(dst, b, h) do { _Pragma("unroll") for (int n = 0; n < 2; ++n) _Pragma("unroll") for (int k = 0; k < 2; ++k) dst[n][k] = *(const LAS bf16x8*)(lds + PG8_SB(b, h) + boff + n * 2048 + k * 1024); } while (0)
; #define PG8_MMA(ai, bj, At, Bt) do { __builtin_amdgcn_s_setprio(1); _Pragma("unroll") for (int m = 0; m < 4; ++m) _Pragma("unroll") for (int n = 0; n < 2; ++n) _Pragma("unroll") for (int k = 0; k < 2; ++k) \
;         acc[ai][bj][m][n] = __builtin_amdgcn_mfma_f32_16x16x32_bf16(Bt[n][k], At[m][k], acc[ai][bj][m][n], 0, 0, 0); __builtin_amdgcn_s_setprio(0); } while (0)
; #define PG8_WAIT_V(n) asm volatile("s_waitcnt vmcnt(" #n ")" ::: "memory")
; #define PG8_WAIT_L(n) asm volatile("s_waitcnt lgkmcnt(" #n ")" ::: "memory")
; #define PG8_BAR __builtin_amdgcn_s_barrier()
; #define PG8_SCHED __builtin_amdgcn_sched_barrier(0)
; template <class Epi>
; DEV void gemm_phase(LAS unsigned char* lds, const Gemm g, const StaticOrder& S, const Epi& E) {
;     ...
;             PG8_LDB(B0, 0, 0); PG8_SCHED; PG8_LDA(At, 0, 0); PG8_STAGE(PG8_SA(1, 1), a1 + hstep, voffA);
;             PG8_WAIT_L(8); PG8_BAR; PG8_WAIT_L(0); PG8_MMA(0, 0, At, B0); PG8_BAR; PG8_SCHED;
;             PG8_LDB(B1, 0, 1); PG8_STAGE(PG8_SB(0, 0), b2, voffB);
;             PG8_BAR; PG8_WAIT_L(0); PG8_MMA(0, 1, At, B1); PG8_BAR;
;             PG8_LDA(At, 0, 1); PG8_STAGE(PG8_SA(0, 0), a2, voffA);
;             PG8_BAR; PG8_WAIT_L(0); PG8_MMA(1, 0, At, B0); PG8_BAR; PG8_SCHED;
;             PG8_STAGE(PG8_SB(0, 1), b2 + hstep, voffB);
;             PG8_WAIT_V(6); PG8_BAR; PG8_MMA(1, 1, At, B1); PG8_BAR;
.LBB0_260:
	s_add_u32 s34, s30, 0xfffe0080
	s_addc_u32 s35, s31, -1
	s_add_i32 s55, 0, 0x10000
	v_add_u32_e32 v140, s55, v178
	ds_read_b128 v[128:131], v140
	ds_read_b128 v[132:135], v140 offset:1024
	ds_read_b128 v[136:139], v140 offset:2048
	ds_read_b128 v[140:143], v140 offset:3072
	s_cmp_eq_u32 s54, 4
	s_cselect_b32 s37, s19, s35
	s_cselect_b32 s36, s23, s34
	s_cselect_b32 s35, s21, s53
	s_cselect_b32 s34, s29, s52
	s_add_i32 m0, s43, 0xc000
	ds_read_b128 v[154:157], v181
	ds_read_b128 v[174:177], v181 offset:1024
	ds_read_b128 v[182:185], v181 offset:2048
	ds_read_b128 v[186:189], v181 offset:3072
	ds_read_b128 v[190:193], v181 offset:4096
	ds_read_b128 v[194:197], v181 offset:5120
	ds_read_b128 v[214:217], v181 offset:6144
	ds_read_b128 v[218:221], v181 offset:7168
	global_load_lds_dwordx4 v150, s[30:31]
	s_add_i32 m0, s43, 0xe000
	s_nop 0
	global_load_lds_dwordx4 v152, s[30:31]
	s_waitcnt lgkmcnt(8)
	s_barrier
	s_waitcnt lgkmcnt(0)
	v_mfma_f32_16x16x32_bf16 v[124:127], v[128:131], v[154:157], v[124:127]
	v_mfma_f32_16x16x32_bf16 v[120:123], v[136:139], v[154:157], v[120:123]
	v_mfma_f32_16x16x32_bf16 v[108:111], v[128:131], v[182:185], v[108:111]
	v_mfma_f32_16x16x32_bf16 v[104:107], v[136:139], v[182:185], v[104:107]
	v_mfma_f32_16x16x32_bf16 v[92:95], v[128:131], v[190:193], v[92:95]
	v_mfma_f32_16x16x32_bf16 v[88:91], v[136:139], v[190:193], v[88:91]
	v_mfma_f32_16x16x32_bf16 v[76:79], v[128:131], v[214:217], v[76:79]
	v_mfma_f32_16x16x32_bf16 v[72:75], v[136:139], v[214:217], v[72:75]
	v_mfma_f32_16x16x32_bf16 v[124:127], v[132:135], v[174:177], v[124:127]
	v_mfma_f32_16x16x32_bf16 v[120:123], v[140:143], v[174:177], v[120:123]
	v_mfma_f32_16x16x32_bf16 v[108:111], v[132:135], v[186:189], v[108:111]
	v_mfma_f32_16x16x32_bf16 v[104:107], v[140:143], v[186:189], v[104:107]
	v_mfma_f32_16x16x32_bf16 v[92:95], v[132:135], v[194:197], v[92:95]
	v_mfma_f32_16x16x32_bf16 v[88:91], v[140:143], v[194:197], v[88:91]
	v_mfma_f32_16x16x32_bf16 v[76:79], v[132:135], v[218:221], v[76:79]
	v_mfma_f32_16x16x32_bf16 v[72:75], v[140:143], v[218:221], v[72:75]
	s_barrier
	s_add_i32 s58, 0, 0x14000
	v_add_u32_e32 v158, s58, v178
	s_add_i32 s55, s55, s42
	ds_read_b128 v[222:225], v158
	ds_read_b128 v[226:229], v158 offset:1024
	ds_read_b128 v[230:233], v158 offset:2048
	ds_read_b128 v[234:237], v158 offset:3072
	v_lshl_add_u64 v[158:159], s[34:35], 0, v[160:161]
	s_mov_b32 m0, s55
	v_lshl_add_u64 v[238:239], s[34:35], 0, v[148:149]
	global_load_lds_dwordx4 v160, s[34:35]
	s_add_i32 m0, s55, 0x2000
	s_nop 0
	global_load_lds_dwordx4 v148, s[34:35]
	s_barrier
	s_waitcnt lgkmcnt(0)
	v_mfma_f32_16x16x32_bf16 v[116:119], v[222:225], v[154:157], v[116:119]
	v_mfma_f32_16x16x32_bf16 v[112:115], v[230:233], v[154:157], v[112:115]
	v_mfma_f32_16x16x32_bf16 v[100:103], v[222:225], v[182:185], v[100:103]
	v_mfma_f32_16x16x32_bf16 v[96:99], v[230:233], v[182:185], v[96:99]
	v_mfma_f32_16x16x32_bf16 v[84:87], v[222:225], v[190:193], v[84:87]
	v_mfma_f32_16x16x32_bf16 v[80:83], v[230:233], v[190:193], v[80:83]
	v_mfma_f32_16x16x32_bf16 v[68:71], v[222:225], v[214:217], v[68:71]
	v_mfma_f32_16x16x32_bf16 v[64:67], v[230:233], v[214:217], v[64:67]
	v_mfma_f32_16x16x32_bf16 v[116:119], v[226:229], v[174:177], v[116:119]
	v_mfma_f32_16x16x32_bf16 v[112:115], v[234:237], v[174:177], v[112:115]
	v_mfma_f32_16x16x32_bf16 v[100:103], v[226:229], v[186:189], v[100:103]
	v_mfma_f32_16x16x32_bf16 v[96:99], v[234:237], v[186:189], v[96:99]
	v_mfma_f32_16x16x32_bf16 v[84:87], v[226:229], v[194:197], v[84:87]
	v_mfma_f32_16x16x32_bf16 v[80:83], v[234:237], v[194:197], v[80:83]
	v_mfma_f32_16x16x32_bf16 v[68:71], v[226:229], v[218:221], v[68:71]
	v_mfma_f32_16x16x32_bf16 v[64:67], v[234:237], v[218:221], v[64:67]
	s_barrier
	s_mov_b32 m0, s43
	v_lshl_add_u64 v[240:241], s[36:37], 0, v[144:145]
	ds_read_b128 v[154:157], v181 offset:16384
	ds_read_b128 v[174:177], v181 offset:17408
	ds_read_b128 v[182:185], v181 offset:18432
	ds_read_b128 v[186:189], v181 offset:19456
	ds_read_b128 v[190:193], v181 offset:20480
	ds_read_b128 v[194:197], v181 offset:21504
	ds_read_b128 v[214:217], v181 offset:22528
	ds_read_b128 v[218:221], v181 offset:23552
	global_load_lds_dwordx4 v144, s[36:37]
	v_lshl_add_u64 v[242:243], s[36:37], 0, v[146:147]
	s_mov_b32 m0, s44
	s_nop 0
	global_load_lds_dwordx4 v146, s[36:37]
	s_barrier
	s_waitcnt lgkmcnt(0)
	v_mfma_f32_16x16x32_bf16 v[60:63], v[128:131], v[154:157], v[60:63]
	v_mfma_f32_16x16x32_bf16 v[56:59], v[136:139], v[154:157], v[56:59]
	v_mfma_f32_16x16x32_bf16 v[44:47], v[128:131], v[182:185], v[44:47]
	v_mfma_f32_16x16x32_bf16 v[40:43], v[136:139], v[182:185], v[40:43]
	v_mfma_f32_16x16x32_bf16 v[28:31], v[128:131], v[190:193], v[28:31]
	v_mfma_f32_16x16x32_bf16 v[24:27], v[136:139], v[190:193], v[24:27]
	v_mfma_f32_16x16x32_bf16 v[12:15], v[128:131], v[214:217], v[12:15]
	v_mfma_f32_16x16x32_bf16 v[8:11], v[136:139], v[214:217], v[8:11]
	v_mfma_f32_16x16x32_bf16 v[60:63], v[132:135], v[174:177], v[60:63]
	v_mfma_f32_16x16x32_bf16 v[56:59], v[140:143], v[174:177], v[56:59]
	v_mfma_f32_16x16x32_bf16 v[44:47], v[132:135], v[186:189], v[44:47]
	v_mfma_f32_16x16x32_bf16 v[40:43], v[140:143], v[186:189], v[40:43]
	v_mfma_f32_16x16x32_bf16 v[28:31], v[132:135], v[194:197], v[28:31]
	v_mfma_f32_16x16x32_bf16 v[24:27], v[140:143], v[194:197], v[24:27]
	v_mfma_f32_16x16x32_bf16 v[12:15], v[132:135], v[218:221], v[12:15]
	v_mfma_f32_16x16x32_bf16 v[8:11], v[140:143], v[218:221], v[8:11]
	s_barrier
	s_add_u32 s56, s34, 0x20000
	s_addc_u32 s57, s35, 0
	s_add_i32 s55, s58, s42
	s_mov_b32 m0, s55
	s_nop 0
	global_load_lds_dwordx4 v160, s[56:57]
	s_add_i32 m0, s55, 0x2000
	s_nop 0
	global_load_lds_dwordx4 v148, s[56:57]
	s_waitcnt vmcnt(6)
	s_barrier
; #define PG8_STAGE(bufoff, gbase, voff) do { _Pragma("unroll") for (int _i = 0; _i < 2; ++_i) \
;         __builtin_amdgcn_global_load_lds((const unsigned*)((const char*)(gbase) + (voff)[_i]), (LAS unsigned*)(lds + (bufoff) + ldsw + _i * 8192), 16, 0, 0); } while (0)
; #define PG8_LDA(dst, b, h) do { _Pragma("unroll") for (int m = 0; m < 4; ++m) _Pragma("unroll") for (int k = 0; k < 2; ++k) dst[m][k] = *(const LAS bf16x8*)(lds + PG8_SA(b, h) + aoff + m * 2048 + k * 1024); } while (0)
; #define PG8_LDB(dst, b, h) do { _Pragma("unroll") for (int n = 0; n < 2; ++n) _Pragma("unroll") for (int k = 0; k < 2; ++k) dst[n][k] = *(const LAS bf16x8*)(lds + PG8_SB(b, h) + boff + n * 2048 + k * 1024); } while (0)
; #define PG8_MMA(ai, bj, At, Bt) do { __builtin_amdgcn_s_setprio(1); _Pragma("unroll") for (int m = 0; m < 4; ++m) _Pragma("unroll") for (int n = 0; n < 2; ++n) _Pragma("unroll") for (int k = 0; k < 2; ++k) \
;         acc[ai][bj][m][n] = __builtin_amdgcn_mfma_f32_16x16x32_bf16(Bt[n][k], At[m][k], acc[ai][bj][m][n], 0, 0, 0); __builtin_amdgcn_s_setprio(0); } while (0)
; #define PG8_WAIT_V(n) asm volatile("s_waitcnt vmcnt(" #n ")" ::: "memory")
; #define PG8_WAIT_L(n) asm volatile("s_waitcnt lgkmcnt(" #n ")" ::: "memory")
; #define PG8_BAR __builtin_amdgcn_s_barrier()
; #define PG8_SCHED __builtin_amdgcn_sched_barrier(0)
; template <class Epi>
; DEV void gemm_phase(LAS unsigned char* lds, const Gemm g, const StaticOrder& S, const Epi& E) {
;     ...
;             PG8_WAIT_V(6); PG8_BAR; PG8_MMA(1, 1, At, B1); PG8_BAR;
;             PG8_LDB(B0, 1, 0); PG8_SCHED; PG8_LDA(At, 1, 0); PG8_STAGE(PG8_SA(0, 1), a2 + hstep, voffA);
;             PG8_WAIT_L(8); PG8_BAR; PG8_WAIT_L(0); PG8_MMA(0, 0, At, B0); PG8_BAR; PG8_SCHED;
;             PG8_LDB(B1, 1, 1); PG8_STAGE(PG8_SB(1, 0), b3, voffB);
;             PG8_BAR; PG8_WAIT_L(0); PG8_MMA(0, 1, At, B1); PG8_BAR;
;             PG8_LDA(At, 1, 1); PG8_STAGE(PG8_SA(1, 0), a3, voffA);
	v_mfma_f32_16x16x32_bf16 v[52:55], v[222:225], v[154:157], v[52:55]
	v_mfma_f32_16x16x32_bf16 v[48:51], v[230:233], v[154:157], v[48:51]
	v_mfma_f32_16x16x32_bf16 v[36:39], v[222:225], v[182:185], v[36:39]
	v_mfma_f32_16x16x32_bf16 v[32:35], v[230:233], v[182:185], v[32:35]
	v_mfma_f32_16x16x32_bf16 v[20:23], v[222:225], v[190:193], v[20:23]
	v_mfma_f32_16x16x32_bf16 v[16:19], v[230:233], v[190:193], v[16:19]
	v_mfma_f32_16x16x32_bf16 v[4:7], v[222:225], v[214:217], v[4:7]
	v_mfma_f32_16x16x32_bf16 v[0:3], v[230:233], v[214:217], v[0:3]
	v_mfma_f32_16x16x32_bf16 v[52:55], v[226:229], v[174:177], v[52:55]
	v_mfma_f32_16x16x32_bf16 v[48:51], v[234:237], v[174:177], v[48:51]
	v_mfma_f32_16x16x32_bf16 v[36:39], v[226:229], v[186:189], v[36:39]
	v_mfma_f32_16x16x32_bf16 v[32:35], v[234:237], v[186:189], v[32:35]
	v_mfma_f32_16x16x32_bf16 v[20:23], v[226:229], v[194:197], v[20:23]
	v_mfma_f32_16x16x32_bf16 v[16:19], v[234:237], v[194:197], v[16:19]
	v_mfma_f32_16x16x32_bf16 v[4:7], v[226:229], v[218:221], v[4:7]
	v_mfma_f32_16x16x32_bf16 v[0:3], v[234:237], v[218:221], v[0:3]
	s_barrier
	s_add_i32 s55, 0, 0x18000
	v_add_u32_e32 v140, s55, v178
	ds_read_b128 v[128:131], v140
	ds_read_b128 v[132:135], v140 offset:1024
	ds_read_b128 v[136:139], v140 offset:2048
	ds_read_b128 v[140:143], v140 offset:3072
	s_add_u32 s36, s36, 0x20000
	s_addc_u32 s37, s37, 0
	s_mov_b32 m0, s45
	ds_read_b128 v[154:157], v181 offset:32768
	ds_read_b128 v[174:177], v181 offset:33792
	ds_read_b128 v[182:185], v181 offset:34816
	ds_read_b128 v[186:189], v181 offset:35840
	ds_read_b128 v[190:193], v181 offset:36864
	ds_read_b128 v[194:197], v181 offset:37888
	ds_read_b128 v[214:217], v181 offset:38912
	ds_read_b128 v[218:221], v181 offset:39936
	global_load_lds_dwordx4 v144, s[36:37]
	s_mov_b32 m0, s46
	s_nop 0
	global_load_lds_dwordx4 v146, s[36:37]
	s_waitcnt lgkmcnt(8)
	s_barrier
	s_waitcnt lgkmcnt(0)
	v_mfma_f32_16x16x32_bf16 v[124:127], v[128:131], v[154:157], v[124:127]
	v_mfma_f32_16x16x32_bf16 v[120:123], v[136:139], v[154:157], v[120:123]
	v_mfma_f32_16x16x32_bf16 v[108:111], v[128:131], v[182:185], v[108:111]
	v_mfma_f32_16x16x32_bf16 v[104:107], v[136:139], v[182:185], v[104:107]
	v_mfma_f32_16x16x32_bf16 v[92:95], v[128:131], v[190:193], v[92:95]
	v_mfma_f32_16x16x32_bf16 v[88:91], v[136:139], v[190:193], v[88:91]
	v_mfma_f32_16x16x32_bf16 v[76:79], v[128:131], v[214:217], v[76:79]
	v_mfma_f32_16x16x32_bf16 v[72:75], v[136:139], v[214:217], v[72:75]
	v_mfma_f32_16x16x32_bf16 v[124:127], v[132:135], v[174:177], v[124:127]
	v_mfma_f32_16x16x32_bf16 v[120:123], v[140:143], v[174:177], v[120:123]
	v_mfma_f32_16x16x32_bf16 v[108:111], v[132:135], v[186:189], v[108:111]
	v_mfma_f32_16x16x32_bf16 v[104:107], v[140:143], v[186:189], v[104:107]
	v_mfma_f32_16x16x32_bf16 v[92:95], v[132:135], v[194:197], v[92:95]
	v_mfma_f32_16x16x32_bf16 v[88:91], v[140:143], v[194:197], v[88:91]
	v_mfma_f32_16x16x32_bf16 v[76:79], v[132:135], v[218:221], v[76:79]
	v_mfma_f32_16x16x32_bf16 v[72:75], v[140:143], v[218:221], v[72:75]
	s_barrier
	s_add_i32 s36, 0, 0x1c000
	s_add_i32 s37, s55, s42
	v_add_u32_e32 v234, s36, v178
	v_lshl_add_u64 v[158:159], v[158:159], 0, s[2:3]
	s_mov_b32 m0, s37
	ds_read_b128 v[222:225], v234
	ds_read_b128 v[226:229], v234 offset:1024
	ds_read_b128 v[230:233], v234 offset:2048
	ds_read_b128 v[234:237], v234 offset:3072
	global_load_lds_dwordx4 v[158:159], off
	v_lshl_add_u64 v[158:159], v[238:239], 0, s[2:3]
	s_add_i32 m0, s37, 0x2000
	s_nop 0
	global_load_lds_dwordx4 v[158:159], off
	s_barrier
	s_waitcnt lgkmcnt(0)
	v_mfma_f32_16x16x32_bf16 v[116:119], v[222:225], v[154:157], v[116:119]
	v_mfma_f32_16x16x32_bf16 v[112:115], v[230:233], v[154:157], v[112:115]
	v_mfma_f32_16x16x32_bf16 v[100:103], v[222:225], v[182:185], v[100:103]
	v_mfma_f32_16x16x32_bf16 v[96:99], v[230:233], v[182:185], v[96:99]
	v_mfma_f32_16x16x32_bf16 v[84:87], v[222:225], v[190:193], v[84:87]
	v_mfma_f32_16x16x32_bf16 v[80:83], v[230:233], v[190:193], v[80:83]
	v_mfma_f32_16x16x32_bf16 v[68:71], v[222:225], v[214:217], v[68:71]
	v_mfma_f32_16x16x32_bf16 v[64:67], v[230:233], v[214:217], v[64:67]
	v_mfma_f32_16x16x32_bf16 v[116:119], v[226:229], v[174:177], v[116:119]
	v_mfma_f32_16x16x32_bf16 v[112:115], v[234:237], v[174:177], v[112:115]
	v_mfma_f32_16x16x32_bf16 v[100:103], v[226:229], v[186:189], v[100:103]
	v_mfma_f32_16x16x32_bf16 v[96:99], v[234:237], v[186:189], v[96:99]
	v_mfma_f32_16x16x32_bf16 v[84:87], v[226:229], v[194:197], v[84:87]
	v_mfma_f32_16x16x32_bf16 v[80:83], v[234:237], v[194:197], v[80:83]
	v_mfma_f32_16x16x32_bf16 v[68:71], v[226:229], v[218:221], v[68:71]
	v_mfma_f32_16x16x32_bf16 v[64:67], v[234:237], v[218:221], v[64:67]
	s_barrier
	s_mov_b32 m0, s47
	v_lshl_add_u64 v[158:159], v[240:241], 0, s[2:3]
	ds_read_b128 v[154:157], v181 offset:49152
	ds_read_b128 v[174:177], v181 offset:50176
	ds_read_b128 v[182:185], v181 offset:51200
	ds_read_b128 v[186:189], v181 offset:52224
	ds_read_b128 v[190:193], v181 offset:53248
	ds_read_b128 v[194:197], v181 offset:54272
	ds_read_b128 v[214:217], v181 offset:55296
	ds_read_b128 v[218:221], v181 offset:56320
	global_load_lds_dwordx4 v[158:159], off
	v_lshl_add_u64 v[158:159], v[242:243], 0, s[2:3]
	s_mov_b32 m0, s48
	s_nop 0
	global_load_lds_dwordx4 v[158:159], off
	s_barrier
; DEV bf16x8 pack8(f32x4 a, f32x4 b) { u32x4 w; w.x = cvt_pk_bf16(a[0], a[1]); w.y = cvt_pk_bf16(a[2], a[3]); w.z = cvt_pk_bf16(b[0], b[1]); w.w = cvt_pk_bf16(b[2], b[3]); return __builtin_bit_cast(bf16x8, w); }
; #define PG8_WAIT_V(n) asm volatile("s_waitcnt vmcnt(" #n ")" ::: "memory")
; #define PG8_WAIT_L(n) asm volatile("s_waitcnt lgkmcnt(" #n ")" ::: "memory")
; #define PG8_BAR __builtin_amdgcn_s_barrier()
; template <class Epi>
; DEV void gemm_phase(LAS unsigned char* lds, const Gemm g, const StaticOrder& S, const Epi& E) {
;     ...
;             PG8_BAR; PG8_WAIT_L(0); PG8_MMA(1, 0, At, B0); PG8_BAR; PG8_SCHED;
;             PG8_STAGE(PG8_SB(1, 1), b3 + hstep, voffB);
;             PG8_WAIT_V(6); PG8_BAR; PG8_MMA(1, 1, At, B1); PG8_BAR;
;         }
;     DEV void operator()(AccRef acc, const pg8::Unit& u, int wr, int wc, int fr, int fq) const {
;         const int row0 = u.pm * 256 + wr * 64 + fr, col0 = u.pn * 256 + wc * 32 + 8 * fq;
; #pragma unroll
;         for (int am = 0; am < 4; ++am) { const int ai = am >> 1, m0 = (am & 1) * 2;
;             f32x4 bv[4][2][2];
; #pragma unroll
;             for (int m = m0; m < m0 + 2; ++m)
; #pragma unroll
;                 for (int bj = 0; bj < 2; ++bj)
; #pragma unroll
;                     for (int n = 0; n < 2; ++n) bv[m][bj][n] = *(const f32x4*)(base + (size_t)(row0 + ai * 128 + m * 16) * 2048 + col0 + bj * 128 + n * 4);
; #pragma unroll
;             for (int m = m0; m < m0 + 2; ++m) { const size_t off = (size_t)(row0 + ai * 128 + m * 16) * 2048 + col0; float sq = 0.f;
; #pragma unroll
;                 for (int bj = 0; bj < 2; ++bj) { const f32x4 o0 = bv[m][bj][0] + scale * acc[ai][bj][m][0], o1 = bv[m][bj][1] + scale * acc[ai][bj][m][1];
;                     *(f32x4*)(out + off + bj * 128) = o0; *(f32x4*)(out + off + bj * 128 + 4) = o1;
;                     if (xb) { *(u32x4*)(xb + off + bj * 128) = __builtin_bit_cast(u32x4, pack8(o0, o1));
;                         sq += (o0[0] * o0[0] + o0[1] * o0[1] + o0[2] * o0[2] + o0[3] * o0[3]) + (o1[0] * o1[0] + o1[1] * o1[1] + o1[2] * o1[2] + o1[3] * o1[3]); } }
;                 if (ssout) { sq += __shfl_xor(sq, 16); sq += __shfl_xor(sq, 32);
;                     if (fq == 0) { if (red) red[(ai * 128 + wr * 64 + m * 16 + fr) * 4 + wc] = sq; else atomicAdd(ssout + (size_t)(row0 + ai * 128 + m * 16) * 8 + u.pn, sq); } } }
	s_waitcnt lgkmcnt(0)
	v_mfma_f32_16x16x32_bf16 v[60:63], v[128:131], v[154:157], v[60:63]
	v_mfma_f32_16x16x32_bf16 v[56:59], v[136:139], v[154:157], v[56:59]
	v_mfma_f32_16x16x32_bf16 v[44:47], v[128:131], v[182:185], v[44:47]
	v_mfma_f32_16x16x32_bf16 v[40:43], v[136:139], v[182:185], v[40:43]
	v_mfma_f32_16x16x32_bf16 v[28:31], v[128:131], v[190:193], v[28:31]
	v_mfma_f32_16x16x32_bf16 v[24:27], v[136:139], v[190:193], v[24:27]
	v_mfma_f32_16x16x32_bf16 v[12:15], v[128:131], v[214:217], v[12:15]
	v_mfma_f32_16x16x32_bf16 v[8:11], v[136:139], v[214:217], v[8:11]
	v_mfma_f32_16x16x32_bf16 v[60:63], v[132:135], v[174:177], v[60:63]
	v_mfma_f32_16x16x32_bf16 v[56:59], v[140:143], v[174:177], v[56:59]
	v_mfma_f32_16x16x32_bf16 v[44:47], v[132:135], v[186:189], v[44:47]
	v_mfma_f32_16x16x32_bf16 v[40:43], v[140:143], v[186:189], v[40:43]
	v_mfma_f32_16x16x32_bf16 v[28:31], v[132:135], v[194:197], v[28:31]
	v_mfma_f32_16x16x32_bf16 v[24:27], v[140:143], v[194:197], v[24:27]
	v_mfma_f32_16x16x32_bf16 v[12:15], v[132:135], v[218:221], v[12:15]
	v_mfma_f32_16x16x32_bf16 v[8:11], v[140:143], v[218:221], v[8:11]
	s_barrier
	s_add_u32 s34, s34, 0x20080
	s_addc_u32 s35, s35, 0
	s_add_i32 s36, s36, s42
	s_mov_b32 m0, s36
	s_nop 0
	global_load_lds_dwordx4 v160, s[34:35]
	s_add_i32 m0, s36, 0x2000
	s_nop 0
	global_load_lds_dwordx4 v148, s[34:35]
	s_waitcnt vmcnt(6)
	s_barrier
	v_mfma_f32_16x16x32_bf16 v[52:55], v[222:225], v[154:157], v[52:55]
	v_mfma_f32_16x16x32_bf16 v[48:51], v[230:233], v[154:157], v[48:51]
	v_mfma_f32_16x16x32_bf16 v[36:39], v[222:225], v[182:185], v[36:39]
	v_mfma_f32_16x16x32_bf16 v[32:35], v[230:233], v[182:185], v[32:35]
	v_mfma_f32_16x16x32_bf16 v[20:23], v[222:225], v[190:193], v[20:23]
	v_mfma_f32_16x16x32_bf16 v[16:19], v[230:233], v[190:193], v[16:19]
	v_mfma_f32_16x16x32_bf16 v[4:7], v[222:225], v[214:217], v[4:7]
	v_mfma_f32_16x16x32_bf16 v[0:3], v[230:233], v[214:217], v[0:3]
	v_mfma_f32_16x16x32_bf16 v[52:55], v[226:229], v[174:177], v[52:55]
	v_mfma_f32_16x16x32_bf16 v[48:51], v[234:237], v[174:177], v[48:51]
	v_mfma_f32_16x16x32_bf16 v[36:39], v[226:229], v[186:189], v[36:39]
	v_mfma_f32_16x16x32_bf16 v[32:35], v[234:237], v[186:189], v[32:35]
	v_mfma_f32_16x16x32_bf16 v[20:23], v[226:229], v[194:197], v[20:23]
	v_mfma_f32_16x16x32_bf16 v[16:19], v[234:237], v[194:197], v[16:19]
	v_mfma_f32_16x16x32_bf16 v[4:7], v[226:229], v[218:221], v[4:7]
	v_mfma_f32_16x16x32_bf16 v[0:3], v[234:237], v[218:221], v[0:3]
	s_add_i32 s54, s54, 2
	s_add_u32 s30, s30, 0x100
	s_addc_u32 s31, s31, 0
	s_add_u32 s52, s52, 0x100
	s_addc_u32 s53, s53, 0
	s_cmp_gt_u32 s54, 5
	s_barrier
	s_cbranch_scc0 .LBB0_260
	v_lshl_add_u32 v156, s28, 8, v167
	v_lshl_or_b32 v154, s18, 8, v179
	v_readlane_b32 s28, v254, 16
	v_ashrrev_i32_e32 v155, 31, v154
	v_readlane_b32 s29, v254, 17
	v_ashrrev_i32_e32 v157, 31, v156
	v_lshlrev_b64 v[128:129], 13, v[156:157]
	v_lshl_add_u64 v[158:159], v[154:155], 2, s[28:29]
	v_lshl_add_u64 v[214:215], v[158:159], 0, v[128:129]
	global_load_dwordx4 v[182:185], v[214:215], off offset:16
	global_load_dwordx4 v[186:189], v[214:215], off
	global_load_dwordx4 v[190:193], v[214:215], off offset:528
	global_load_dwordx4 v[194:197], v[214:215], off offset:512
	v_or_b32_e32 v174, 16, v156
	v_ashrrev_i32_e32 v175, 31, v174
	v_lshlrev_b64 v[128:129], 13, v[174:175]
	v_lshl_add_u64 v[176:177], v[158:159], 0, v[128:129]
	global_load_dwordx4 v[136:139], v[176:177], off offset:16
	global_load_dwordx4 v[140:143], v[176:177], off
	global_load_dwordx4 v[128:131], v[176:177], off offset:528
	global_load_dwordx4 v[132:135], v[176:177], off offset:512
	v_lshlrev_b64 v[216:217], 11, v[156:157]
	v_readlane_b32 s28, v250, 9
	v_lshl_add_u64 v[216:217], v[216:217], 0, v[154:155]
	v_readlane_b32 s29, v250, 10
	v_cmp_lt_i32_e32 vcc, v208, v206
	s_ashr_i32 s19, s18, 31
	s_waitcnt vmcnt(0)
	v_pk_add_f32 v[120:121], v[120:121], v[182:183]
	v_pk_add_f32 v[126:127], v[126:127], v[188:189]
	v_pk_add_f32 v[124:125], v[124:125], v[186:187]
	v_pk_add_f32 v[122:123], v[122:123], v[184:185]
	global_store_dwordx4 v[214:215], v[124:127], off
	global_store_dwordx4 v[214:215], v[120:123], off offset:16
	v_cvt_pk_bf16_f32 v184, v120, v121
	v_cvt_pk_bf16_f32 v182, v124, v125
	v_mul_f32_e32 v121, v121, v121
	v_cvt_pk_bf16_f32 v183, v126, v127
	v_cvt_pk_bf16_f32 v185, v122, v123
	v_lshl_add_u64 v[186:187], v[216:217], 1, s[28:29]
	v_fmac_f32_e32 v121, v120, v120
	v_pk_add_f32 v[118:119], v[118:119], v[196:197]
	v_pk_add_f32 v[116:117], v[116:117], v[194:195]
	v_pk_add_f32 v[112:113], v[112:113], v[190:191]
	global_store_dwordx4 v[186:187], v[182:185], off
	v_mul_f32_e32 v125, v125, v125
	v_fmac_f32_e32 v121, v122, v122
	v_pk_add_f32 v[114:115], v[114:115], v[192:193]
	global_store_dwordx4 v[214:215], v[116:119], off offset:512
	global_store_dwordx4 v[214:215], v[112:115], off offset:528
	v_cvt_pk_bf16_f32 v120, v116, v117
	v_cvt_pk_bf16_f32 v122, v112, v113
	v_mul_f32_e32 v117, v117, v117
	v_mul_f32_e32 v113, v113, v113
	v_fmac_f32_e32 v125, v124, v124
	v_fmac_f32_e32 v117, v116, v116
	v_fmac_f32_e32 v113, v112, v112
	v_fmac_f32_e32 v125, v126, v126
	v_fmac_f32_e32 v117, v118, v118
	v_fmac_f32_e32 v113, v114, v114
	v_fmac_f32_e32 v125, v127, v127
	v_fmac_f32_e32 v121, v123, v123
	v_fmac_f32_e32 v117, v119, v119
	v_fmac_f32_e32 v113, v115, v115
	v_add_f32_e32 v124, v125, v121
	v_add_f32_e32 v112, v117, v113
	v_cndmask_b32_e32 v113, v204, v208, vcc
	v_cvt_pk_bf16_f32 v121, v118, v119
	v_add_f32_e32 v112, v124, v112
	v_lshlrev_b32_e32 v118, 2, v113
	ds_bpermute_b32 v113, v118, v112
	v_cmp_lt_i32_e32 vcc, v207, v206
	v_cvt_pk_bf16_f32 v123, v114, v115
	global_store_dwordx4 v[186:187], v[120:123], off offset:256
	s_waitcnt lgkmcnt(0)
	v_add_f32_e32 v112, v112, v113
	v_cndmask_b32_e32 v113, v204, v207, vcc
	v_lshlrev_b32_e32 v119, 2, v113
	ds_bpermute_b32 v113, v119, v112
	s_and_saveexec_b64 s[28:29], s[6:7]
	s_cbranch_execz .LBB0_266
	s_waitcnt lgkmcnt(0)
	v_add_f32_e32 v112, v112, v113
	s_mov_b64 s[30:31], -1
	s_and_b64 vcc, exec, s[16:17]
	s_cbranch_vccz .LBB0_264
	v_lshlrev_b64 v[114:115], 5, v[156:157]
	v_lshl_add_u64 v[114:115], s[12:13], 0, v[114:115]
	v_lshl_add_u64 v[114:115], s[18:19], 2, v[114:115]
	global_atomic_add_f32 v[114:115], v112, off
	s_mov_b64 s[30:31], 0

; #define PG8_STAGE(bufoff, gbase, voff) do { _Pragma("unroll") for (int _i = 0; _i < 2; ++_i) \
;         __builtin_amdgcn_global_load_lds((const unsigned*)((const char*)(gbase) + (voff)[_i]), (LAS unsigned*)(lds + (bufoff) + ldsw + _i * 8192), 16, 0, 0); } while (0)
; #define PG8_LDA(dst, b, h) do { _Pragma("unroll") for (int m = 0; m < 4; ++m) _Pragma("unroll") for (int k = 0; k < 2; ++k) dst[m][k] = *(const LAS bf16x8*)(lds + PG8_SA(b, h) + aoff + m * 2048 + k * 1024); } while (0)
; #define PG8_LDB(dst, b, h) do { _Pragma("unroll") for (int n = 0; n < 2; ++n) _Pragma("unroll") for (int k = 0; k < 2; ++k) dst[n][k] = *(const LAS bf16x8*)(lds + PG8_SB(b, h) + boff + n * 2048 + k * 1024); } while (0)
; #define PG8_MMA(ai, bj, At, Bt) do { __builtin_amdgcn_s_setprio(1); _Pragma("unroll") for (int m = 0; m < 4; ++m) _Pragma("unroll") for (int n = 0; n < 2; ++n) _Pragma("unroll") for (int k = 0; k < 2; ++k) \
;         acc[ai][bj][m][n] = __builtin_amdgcn_mfma_f32_16x16x32_bf16(Bt[n][k], At[m][k], acc[ai][bj][m][n], 0, 0, 0); __builtin_amdgcn_s_setprio(0); } while (0)
; #define PG8_WAIT_V(n) asm volatile("s_waitcnt vmcnt(" #n ")" ::: "memory")
; #define PG8_WAIT_L(n) asm volatile("s_waitcnt lgkmcnt(" #n ")" ::: "memory")
; #define PG8_BAR __builtin_amdgcn_s_barrier()
; #define PG8_SCHED __builtin_amdgcn_sched_barrier(0)
; template <class Epi>
; DEV void gemm_phase(LAS unsigned char* lds, const Gemm g, const StaticOrder& S, const Epi& E) {
;     ...
;             PG8_LDB(B0, 0, 0); PG8_SCHED; PG8_LDA(At, 0, 0); PG8_STAGE(PG8_SA(1, 1), a1 + hstep, voffA);
;             PG8_WAIT_L(8); PG8_BAR; PG8_WAIT_L(0); PG8_MMA(0, 0, At, B0); PG8_BAR; PG8_SCHED;
;             PG8_LDB(B1, 0, 1); PG8_STAGE(PG8_SB(0, 0), b2, voffB);
;             PG8_BAR; PG8_WAIT_L(0); PG8_MMA(0, 1, At, B1); PG8_BAR;
;             PG8_LDA(At, 0, 1); PG8_STAGE(PG8_SA(0, 0), a2, voffA);
;             PG8_BAR; PG8_WAIT_L(0); PG8_MMA(1, 0, At, B0); PG8_BAR; PG8_SCHED;
;             PG8_STAGE(PG8_SB(0, 1), b2 + hstep, voffB);
;             PG8_WAIT_V(6); PG8_BAR; PG8_MMA(1, 1, At, B1); PG8_BAR;
.LBB0_344:
	s_add_u32 s20, s18, 0xfff80080
	s_addc_u32 s21, s19, -1
	s_add_i32 s45, 0, 0x10000
	v_add_u32_e32 v146, s45, v149
	ds_read_b128 v[128:131], v146
	ds_read_b128 v[132:135], v146 offset:1024
	ds_read_b128 v[142:145], v146 offset:2048
	ds_read_b128 v[150:153], v146 offset:3072
	s_cmp_eq_u32 s44, 28
	s_cselect_b32 s23, s1, s21
	s_cselect_b32 s22, s13, s20
	s_cselect_b32 s21, s11, s43
	s_cselect_b32 s20, s41, s42
	s_add_i32 m0, s30, 0xc000
	ds_read_b128 v[174:177], v159
	ds_read_b128 v[178:181], v159 offset:1024
	ds_read_b128 v[182:185], v159 offset:2048
	ds_read_b128 v[186:189], v159 offset:3072
	ds_read_b128 v[190:193], v159 offset:4096
	ds_read_b128 v[194:197], v159 offset:5120
	ds_read_b128 v[214:217], v159 offset:6144
	ds_read_b128 v[218:221], v159 offset:7168
	global_load_lds_dwordx4 v138, s[18:19]
	s_add_i32 m0, s30, 0xe000
	s_nop 0
	global_load_lds_dwordx4 v140, s[18:19]
	s_waitcnt lgkmcnt(8)
	s_barrier
	s_waitcnt lgkmcnt(0)
	v_mfma_f32_16x16x32_bf16 v[124:127], v[128:131], v[174:177], v[124:127]
	v_mfma_f32_16x16x32_bf16 v[120:123], v[142:145], v[174:177], v[120:123]
	v_mfma_f32_16x16x32_bf16 v[116:119], v[128:131], v[182:185], v[116:119]
	v_mfma_f32_16x16x32_bf16 v[108:111], v[142:145], v[182:185], v[108:111]
	v_mfma_f32_16x16x32_bf16 v[100:103], v[128:131], v[190:193], v[100:103]
	v_mfma_f32_16x16x32_bf16 v[92:95], v[142:145], v[190:193], v[92:95]
	v_mfma_f32_16x16x32_bf16 v[84:87], v[128:131], v[214:217], v[84:87]
	v_mfma_f32_16x16x32_bf16 v[76:79], v[142:145], v[214:217], v[76:79]
	v_mfma_f32_16x16x32_bf16 v[124:127], v[132:135], v[178:181], v[124:127]
	v_mfma_f32_16x16x32_bf16 v[120:123], v[150:153], v[178:181], v[120:123]
	v_mfma_f32_16x16x32_bf16 v[116:119], v[132:135], v[186:189], v[116:119]
	v_mfma_f32_16x16x32_bf16 v[108:111], v[150:153], v[186:189], v[108:111]
	v_mfma_f32_16x16x32_bf16 v[100:103], v[132:135], v[194:197], v[100:103]
	v_mfma_f32_16x16x32_bf16 v[92:95], v[150:153], v[194:197], v[92:95]
	v_mfma_f32_16x16x32_bf16 v[84:87], v[132:135], v[218:221], v[84:87]
	v_mfma_f32_16x16x32_bf16 v[76:79], v[150:153], v[218:221], v[76:79]
	s_barrier
	s_add_i32 s48, 0, 0x14000
	s_add_i32 s45, s45, s29
	v_add_u32_e32 v146, s48, v149
	v_lshl_add_u64 v[154:155], s[20:21], 0, v[160:161]
	s_mov_b32 m0, s45
	ds_read_b128 v[222:225], v146
	ds_read_b128 v[226:229], v146 offset:1024
	ds_read_b128 v[230:233], v146 offset:2048
	ds_read_b128 v[234:237], v146 offset:3072
	global_load_lds_dwordx4 v160, s[20:21]
	v_lshl_add_u64 v[238:239], s[20:21], 0, v[136:137]
	s_add_i32 m0, s45, 0x2000
	s_nop 0
	global_load_lds_dwordx4 v136, s[20:21]
	s_barrier
	s_waitcnt lgkmcnt(0)
	v_mfma_f32_16x16x32_bf16 v[112:115], v[222:225], v[174:177], v[112:115]
	v_mfma_f32_16x16x32_bf16 v[104:107], v[230:233], v[174:177], v[104:107]
	v_mfma_f32_16x16x32_bf16 v[96:99], v[222:225], v[182:185], v[96:99]
	v_mfma_f32_16x16x32_bf16 v[88:91], v[230:233], v[182:185], v[88:91]
	v_mfma_f32_16x16x32_bf16 v[80:83], v[222:225], v[190:193], v[80:83]
	v_mfma_f32_16x16x32_bf16 v[72:75], v[230:233], v[190:193], v[72:75]
	v_mfma_f32_16x16x32_bf16 v[68:71], v[222:225], v[214:217], v[68:71]
	v_mfma_f32_16x16x32_bf16 v[64:67], v[230:233], v[214:217], v[64:67]
	v_mfma_f32_16x16x32_bf16 v[112:115], v[226:229], v[178:181], v[112:115]
	v_mfma_f32_16x16x32_bf16 v[104:107], v[234:237], v[178:181], v[104:107]
	v_mfma_f32_16x16x32_bf16 v[96:99], v[226:229], v[186:189], v[96:99]
	v_mfma_f32_16x16x32_bf16 v[88:91], v[234:237], v[186:189], v[88:91]
	v_mfma_f32_16x16x32_bf16 v[80:83], v[226:229], v[194:197], v[80:83]
	v_mfma_f32_16x16x32_bf16 v[72:75], v[234:237], v[194:197], v[72:75]
	v_mfma_f32_16x16x32_bf16 v[68:71], v[226:229], v[218:221], v[68:71]
	v_mfma_f32_16x16x32_bf16 v[64:67], v[234:237], v[218:221], v[64:67]
	s_barrier
	s_mov_b32 m0, s30
	v_lshl_add_u64 v[240:241], s[22:23], 0, v[160:161]
	ds_read_b128 v[174:177], v159 offset:16384
	ds_read_b128 v[178:181], v159 offset:17408
	ds_read_b128 v[182:185], v159 offset:18432
	ds_read_b128 v[186:189], v159 offset:19456
	ds_read_b128 v[190:193], v159 offset:20480
	ds_read_b128 v[194:197], v159 offset:21504
	ds_read_b128 v[214:217], v159 offset:22528
	ds_read_b128 v[218:221], v159 offset:23552
	global_load_lds_dwordx4 v160, s[22:23]
	v_lshl_add_u64 v[242:243], s[22:23], 0, v[136:137]
	s_mov_b32 m0, s31
	s_nop 0
	global_load_lds_dwordx4 v136, s[22:23]
	s_barrier
	s_waitcnt lgkmcnt(0)
	v_mfma_f32_16x16x32_bf16 v[60:63], v[128:131], v[174:177], v[60:63]
	v_mfma_f32_16x16x32_bf16 v[56:59], v[142:145], v[174:177], v[56:59]
	v_mfma_f32_16x16x32_bf16 v[52:55], v[128:131], v[182:185], v[52:55]
	v_mfma_f32_16x16x32_bf16 v[44:47], v[142:145], v[182:185], v[44:47]
	v_mfma_f32_16x16x32_bf16 v[36:39], v[128:131], v[190:193], v[36:39]
	v_mfma_f32_16x16x32_bf16 v[28:31], v[142:145], v[190:193], v[28:31]
	v_mfma_f32_16x16x32_bf16 v[20:23], v[128:131], v[214:217], v[20:23]
	v_mfma_f32_16x16x32_bf16 v[12:15], v[142:145], v[214:217], v[12:15]
	v_mfma_f32_16x16x32_bf16 v[60:63], v[132:135], v[178:181], v[60:63]
	v_mfma_f32_16x16x32_bf16 v[56:59], v[150:153], v[178:181], v[56:59]
	v_mfma_f32_16x16x32_bf16 v[52:55], v[132:135], v[186:189], v[52:55]
	v_mfma_f32_16x16x32_bf16 v[44:47], v[150:153], v[186:189], v[44:47]
	v_mfma_f32_16x16x32_bf16 v[36:39], v[132:135], v[194:197], v[36:39]
	v_mfma_f32_16x16x32_bf16 v[28:31], v[150:153], v[194:197], v[28:31]
	v_mfma_f32_16x16x32_bf16 v[20:23], v[132:135], v[218:221], v[20:23]
	v_mfma_f32_16x16x32_bf16 v[12:15], v[150:153], v[218:221], v[12:15]
	s_barrier
	s_add_u32 s46, s20, 0x80000
	s_addc_u32 s47, s21, 0
	s_add_i32 s45, s48, s29
	s_mov_b32 m0, s45
	s_nop 0
	global_load_lds_dwordx4 v160, s[46:47]
	s_add_i32 m0, s45, 0x2000
	s_nop 0
	global_load_lds_dwordx4 v136, s[46:47]
	s_waitcnt vmcnt(6)
	s_barrier
; #define PG8_STAGE(bufoff, gbase, voff) do { _Pragma("unroll") for (int _i = 0; _i < 2; ++_i) \
;         __builtin_amdgcn_global_load_lds((const unsigned*)((const char*)(gbase) + (voff)[_i]), (LAS unsigned*)(lds + (bufoff) + ldsw + _i * 8192), 16, 0, 0); } while (0)
; #define PG8_LDA(dst, b, h) do { _Pragma("unroll") for (int m = 0; m < 4; ++m) _Pragma("unroll") for (int k = 0; k < 2; ++k) dst[m][k] = *(const LAS bf16x8*)(lds + PG8_SA(b, h) + aoff + m * 2048 + k * 1024); } while (0)
; #define PG8_LDB(dst, b, h) do { _Pragma("unroll") for (int n = 0; n < 2; ++n) _Pragma("unroll") for (int k = 0; k < 2; ++k) dst[n][k] = *(const LAS bf16x8*)(lds + PG8_SB(b, h) + boff + n * 2048 + k * 1024); } while (0)
; #define PG8_MMA(ai, bj, At, Bt) do { __builtin_amdgcn_s_setprio(1); _Pragma("unroll") for (int m = 0; m < 4; ++m) _Pragma("unroll") for (int n = 0; n < 2; ++n) _Pragma("unroll") for (int k = 0; k < 2; ++k) \
;         acc[ai][bj][m][n] = __builtin_amdgcn_mfma_f32_16x16x32_bf16(Bt[n][k], At[m][k], acc[ai][bj][m][n], 0, 0, 0); __builtin_amdgcn_s_setprio(0); } while (0)
; #define PG8_WAIT_V(n) asm volatile("s_waitcnt vmcnt(" #n ")" ::: "memory")
; #define PG8_WAIT_L(n) asm volatile("s_waitcnt lgkmcnt(" #n ")" ::: "memory")
; #define PG8_BAR __builtin_amdgcn_s_barrier()
; #define PG8_SCHED __builtin_amdgcn_sched_barrier(0)
; template <class Epi>
; DEV void gemm_phase(LAS unsigned char* lds, const Gemm g, const StaticOrder& S, const Epi& E) {
;     ...
;             PG8_WAIT_V(6); PG8_BAR; PG8_MMA(1, 1, At, B1); PG8_BAR;
;             PG8_LDB(B0, 1, 0); PG8_SCHED; PG8_LDA(At, 1, 0); PG8_STAGE(PG8_SA(0, 1), a2 + hstep, voffA);
;             PG8_WAIT_L(8); PG8_BAR; PG8_WAIT_L(0); PG8_MMA(0, 0, At, B0); PG8_BAR; PG8_SCHED;
;             PG8_LDB(B1, 1, 1); PG8_STAGE(PG8_SB(1, 0), b3, voffB);
;             PG8_BAR; PG8_WAIT_L(0); PG8_MMA(0, 1, At, B1); PG8_BAR;
;             PG8_LDA(At, 1, 1); PG8_STAGE(PG8_SA(1, 0), a3, voffA);
	v_mfma_f32_16x16x32_bf16 v[48:51], v[222:225], v[174:177], v[48:51]
	v_mfma_f32_16x16x32_bf16 v[40:43], v[230:233], v[174:177], v[40:43]
	v_mfma_f32_16x16x32_bf16 v[32:35], v[222:225], v[182:185], v[32:35]
	v_mfma_f32_16x16x32_bf16 v[24:27], v[230:233], v[182:185], v[24:27]
	v_mfma_f32_16x16x32_bf16 v[16:19], v[222:225], v[190:193], v[16:19]
	v_mfma_f32_16x16x32_bf16 v[8:11], v[230:233], v[190:193], v[8:11]
	v_mfma_f32_16x16x32_bf16 v[4:7], v[222:225], v[214:217], v[4:7]
	v_mfma_f32_16x16x32_bf16 v[0:3], v[230:233], v[214:217], v[0:3]
	v_mfma_f32_16x16x32_bf16 v[48:51], v[226:229], v[178:181], v[48:51]
	v_mfma_f32_16x16x32_bf16 v[40:43], v[234:237], v[178:181], v[40:43]
	v_mfma_f32_16x16x32_bf16 v[32:35], v[226:229], v[186:189], v[32:35]
	v_mfma_f32_16x16x32_bf16 v[24:27], v[234:237], v[186:189], v[24:27]
	v_mfma_f32_16x16x32_bf16 v[16:19], v[226:229], v[194:197], v[16:19]
	v_mfma_f32_16x16x32_bf16 v[8:11], v[234:237], v[194:197], v[8:11]
	v_mfma_f32_16x16x32_bf16 v[4:7], v[226:229], v[218:221], v[4:7]
	v_mfma_f32_16x16x32_bf16 v[0:3], v[234:237], v[218:221], v[0:3]
	s_barrier
	s_add_i32 s45, 0, 0x18000
	v_add_u32_e32 v146, s45, v149
	ds_read_b128 v[128:131], v146
	ds_read_b128 v[132:135], v146 offset:1024
	ds_read_b128 v[142:145], v146 offset:2048
	ds_read_b128 v[150:153], v146 offset:3072
	s_add_u32 s22, s22, 0x80000
	s_addc_u32 s23, s23, 0
	s_mov_b32 m0, s34
	ds_read_b128 v[174:177], v159 offset:32768
	ds_read_b128 v[178:181], v159 offset:33792
	ds_read_b128 v[182:185], v159 offset:34816
	ds_read_b128 v[186:189], v159 offset:35840
	ds_read_b128 v[190:193], v159 offset:36864
	ds_read_b128 v[194:197], v159 offset:37888
	ds_read_b128 v[214:217], v159 offset:38912
	ds_read_b128 v[218:221], v159 offset:39936
	global_load_lds_dwordx4 v160, s[22:23]
	s_mov_b32 m0, s35
	s_nop 0
	global_load_lds_dwordx4 v136, s[22:23]
	s_waitcnt lgkmcnt(8)
	s_barrier
	s_waitcnt lgkmcnt(0)
	v_mfma_f32_16x16x32_bf16 v[124:127], v[128:131], v[174:177], v[124:127]
	v_mfma_f32_16x16x32_bf16 v[120:123], v[142:145], v[174:177], v[120:123]
	v_mfma_f32_16x16x32_bf16 v[116:119], v[128:131], v[182:185], v[116:119]
	v_mfma_f32_16x16x32_bf16 v[108:111], v[142:145], v[182:185], v[108:111]
	v_mfma_f32_16x16x32_bf16 v[100:103], v[128:131], v[190:193], v[100:103]
	v_mfma_f32_16x16x32_bf16 v[92:95], v[142:145], v[190:193], v[92:95]
	v_mfma_f32_16x16x32_bf16 v[84:87], v[128:131], v[214:217], v[84:87]
	v_mfma_f32_16x16x32_bf16 v[76:79], v[142:145], v[214:217], v[76:79]
	v_mfma_f32_16x16x32_bf16 v[124:127], v[132:135], v[178:181], v[124:127]
	v_mfma_f32_16x16x32_bf16 v[120:123], v[150:153], v[178:181], v[120:123]
	v_mfma_f32_16x16x32_bf16 v[116:119], v[132:135], v[186:189], v[116:119]
	v_mfma_f32_16x16x32_bf16 v[108:111], v[150:153], v[186:189], v[108:111]
	v_mfma_f32_16x16x32_bf16 v[100:103], v[132:135], v[194:197], v[100:103]
	v_mfma_f32_16x16x32_bf16 v[92:95], v[150:153], v[194:197], v[92:95]
	v_mfma_f32_16x16x32_bf16 v[84:87], v[132:135], v[218:221], v[84:87]
	v_mfma_f32_16x16x32_bf16 v[76:79], v[150:153], v[218:221], v[76:79]
	s_barrier
	s_add_i32 s22, 0, 0x1c000
	s_add_i32 s23, s45, s29
	v_add_u32_e32 v146, s22, v149
	v_lshl_add_u64 v[154:155], v[154:155], 0, s[2:3]
	s_mov_b32 m0, s23
	ds_read_b128 v[222:225], v146
	ds_read_b128 v[226:229], v146 offset:1024
	ds_read_b128 v[230:233], v146 offset:2048
	ds_read_b128 v[234:237], v146 offset:3072
	global_load_lds_dwordx4 v[154:155], off
	v_lshl_add_u64 v[154:155], v[238:239], 0, s[2:3]
	s_add_i32 m0, s23, 0x2000
	s_nop 0
	global_load_lds_dwordx4 v[154:155], off
	s_barrier
	s_waitcnt lgkmcnt(0)
	v_mfma_f32_16x16x32_bf16 v[112:115], v[222:225], v[174:177], v[112:115]
	v_mfma_f32_16x16x32_bf16 v[104:107], v[230:233], v[174:177], v[104:107]
	v_mfma_f32_16x16x32_bf16 v[96:99], v[222:225], v[182:185], v[96:99]
	v_mfma_f32_16x16x32_bf16 v[88:91], v[230:233], v[182:185], v[88:91]
	v_mfma_f32_16x16x32_bf16 v[80:83], v[222:225], v[190:193], v[80:83]
	v_mfma_f32_16x16x32_bf16 v[72:75], v[230:233], v[190:193], v[72:75]
	v_mfma_f32_16x16x32_bf16 v[68:71], v[222:225], v[214:217], v[68:71]
	v_mfma_f32_16x16x32_bf16 v[64:67], v[230:233], v[214:217], v[64:67]
	v_mfma_f32_16x16x32_bf16 v[112:115], v[226:229], v[178:181], v[112:115]
	v_mfma_f32_16x16x32_bf16 v[104:107], v[234:237], v[178:181], v[104:107]
	v_mfma_f32_16x16x32_bf16 v[96:99], v[226:229], v[186:189], v[96:99]
	v_mfma_f32_16x16x32_bf16 v[88:91], v[234:237], v[186:189], v[88:91]
	v_mfma_f32_16x16x32_bf16 v[80:83], v[226:229], v[194:197], v[80:83]
	v_mfma_f32_16x16x32_bf16 v[72:75], v[234:237], v[194:197], v[72:75]
	v_mfma_f32_16x16x32_bf16 v[68:71], v[226:229], v[218:221], v[68:71]
	v_mfma_f32_16x16x32_bf16 v[64:67], v[234:237], v[218:221], v[64:67]
	s_barrier
	s_mov_b32 m0, s37
	v_lshl_add_u64 v[154:155], v[240:241], 0, s[2:3]
	ds_read_b128 v[174:177], v159 offset:49152
	ds_read_b128 v[178:181], v159 offset:50176
	ds_read_b128 v[182:185], v159 offset:51200
	ds_read_b128 v[186:189], v159 offset:52224
	ds_read_b128 v[190:193], v159 offset:53248
	ds_read_b128 v[194:197], v159 offset:54272
	ds_read_b128 v[214:217], v159 offset:55296
	ds_read_b128 v[218:221], v159 offset:56320
	global_load_lds_dwordx4 v[154:155], off
	v_lshl_add_u64 v[154:155], v[242:243], 0, s[2:3]
	s_mov_b32 m0, s38
	s_nop 0
	global_load_lds_dwordx4 v[154:155], off
	s_barrier
; #define PG8_STAGE(bufoff, gbase, voff) do { _Pragma("unroll") for (int _i = 0; _i < 2; ++_i) \
;         __builtin_amdgcn_global_load_lds((const unsigned*)((const char*)(gbase) + (voff)[_i]), (LAS unsigned*)(lds + (bufoff) + ldsw + _i * 8192), 16, 0, 0); } while (0)
; #define PG8_MMA(ai, bj, At, Bt) do { __builtin_amdgcn_s_setprio(1); _Pragma("unroll") for (int m = 0; m < 4; ++m) _Pragma("unroll") for (int n = 0; n < 2; ++n) _Pragma("unroll") for (int k = 0; k < 2; ++k) \
;         acc[ai][bj][m][n] = __builtin_amdgcn_mfma_f32_16x16x32_bf16(Bt[n][k], At[m][k], acc[ai][bj][m][n], 0, 0, 0); __builtin_amdgcn_s_setprio(0); } while (0)
; #define PG8_WAIT_V(n) asm volatile("s_waitcnt vmcnt(" #n ")" ::: "memory")
; #define PG8_WAIT_L(n) asm volatile("s_waitcnt lgkmcnt(" #n ")" ::: "memory")
; #define PG8_BAR __builtin_amdgcn_s_barrier()
; #define PG8_SCHED __builtin_amdgcn_sched_barrier(0)
; template <class Epi>
; DEV void gemm_phase(LAS unsigned char* lds, const Gemm g, const StaticOrder& S, const Epi& E) {
;     ...
;             PG8_BAR; PG8_WAIT_L(0); PG8_MMA(1, 0, At, B0); PG8_BAR; PG8_SCHED;
;             PG8_STAGE(PG8_SB(1, 1), b3 + hstep, voffB);
;             PG8_WAIT_V(6); PG8_BAR; PG8_MMA(1, 1, At, B1); PG8_BAR;
;         }
; template <int ACT, bool PERM>
; DEV void store_bf16_tile(AccRef acc, u16* O, int ld, int row0, int col0, const float* ss) {
;     float rsv[2][4];
; #pragma unroll
;     for (int ai = 0; ai < 2; ++ai)
; #pragma unroll
;         for (int m = 0; m < 4; ++m) rsv[ai][m] = ss ? rowscale(ss, row0 + ai * 128 + m * 16) : 1.0f;
; #pragma unroll
;     for (int ai = 0; ai < 2; ++ai)
; #pragma unroll
;         for (int m = 0; m < 4; ++m) { u16* rowp = O + (size_t)(row0 + ai * 128 + m * 16) * ld + col0; const float rs = rsv[ai][m];
	s_waitcnt lgkmcnt(0)
	v_mfma_f32_16x16x32_bf16 v[60:63], v[128:131], v[174:177], v[60:63]
	v_mfma_f32_16x16x32_bf16 v[56:59], v[142:145], v[174:177], v[56:59]
	v_mfma_f32_16x16x32_bf16 v[52:55], v[128:131], v[182:185], v[52:55]
	v_mfma_f32_16x16x32_bf16 v[44:47], v[142:145], v[182:185], v[44:47]
	v_mfma_f32_16x16x32_bf16 v[36:39], v[128:131], v[190:193], v[36:39]
	v_mfma_f32_16x16x32_bf16 v[28:31], v[142:145], v[190:193], v[28:31]
	v_mfma_f32_16x16x32_bf16 v[20:23], v[128:131], v[214:217], v[20:23]
	v_mfma_f32_16x16x32_bf16 v[12:15], v[142:145], v[214:217], v[12:15]
	v_mfma_f32_16x16x32_bf16 v[60:63], v[132:135], v[178:181], v[60:63]
	v_mfma_f32_16x16x32_bf16 v[56:59], v[150:153], v[178:181], v[56:59]
	v_mfma_f32_16x16x32_bf16 v[52:55], v[132:135], v[186:189], v[52:55]
	v_mfma_f32_16x16x32_bf16 v[44:47], v[150:153], v[186:189], v[44:47]
	v_mfma_f32_16x16x32_bf16 v[36:39], v[132:135], v[194:197], v[36:39]
	v_mfma_f32_16x16x32_bf16 v[28:31], v[150:153], v[194:197], v[28:31]
	v_mfma_f32_16x16x32_bf16 v[20:23], v[132:135], v[218:221], v[20:23]
	v_mfma_f32_16x16x32_bf16 v[12:15], v[150:153], v[218:221], v[12:15]
	s_barrier
	s_add_u32 s20, s20, 0x80080
	s_addc_u32 s21, s21, 0
	s_add_i32 s22, s22, s29
	s_mov_b32 m0, s22
	s_nop 0
	global_load_lds_dwordx4 v160, s[20:21]
	s_add_i32 m0, s22, 0x2000
	s_nop 0
	global_load_lds_dwordx4 v136, s[20:21]
	s_waitcnt vmcnt(6)
	s_barrier
	v_mfma_f32_16x16x32_bf16 v[48:51], v[222:225], v[174:177], v[48:51]
	v_mfma_f32_16x16x32_bf16 v[40:43], v[230:233], v[174:177], v[40:43]
	v_mfma_f32_16x16x32_bf16 v[32:35], v[222:225], v[182:185], v[32:35]
	v_mfma_f32_16x16x32_bf16 v[24:27], v[230:233], v[182:185], v[24:27]
	v_mfma_f32_16x16x32_bf16 v[16:19], v[222:225], v[190:193], v[16:19]
	v_mfma_f32_16x16x32_bf16 v[8:11], v[230:233], v[190:193], v[8:11]
	v_mfma_f32_16x16x32_bf16 v[4:7], v[222:225], v[214:217], v[4:7]
	v_mfma_f32_16x16x32_bf16 v[0:3], v[230:233], v[214:217], v[0:3]
	v_mfma_f32_16x16x32_bf16 v[48:51], v[226:229], v[178:181], v[48:51]
	v_mfma_f32_16x16x32_bf16 v[40:43], v[234:237], v[178:181], v[40:43]
	v_mfma_f32_16x16x32_bf16 v[32:35], v[226:229], v[186:189], v[32:35]
	v_mfma_f32_16x16x32_bf16 v[24:27], v[234:237], v[186:189], v[24:27]
	v_mfma_f32_16x16x32_bf16 v[16:19], v[226:229], v[194:197], v[16:19]
	v_mfma_f32_16x16x32_bf16 v[8:11], v[234:237], v[194:197], v[8:11]
	v_mfma_f32_16x16x32_bf16 v[4:7], v[226:229], v[218:221], v[4:7]
	v_mfma_f32_16x16x32_bf16 v[0:3], v[234:237], v[218:221], v[0:3]
	s_add_i32 s44, s44, 2
	s_add_u32 s18, s18, 0x100
	s_addc_u32 s19, s19, 0
	s_add_u32 s42, s42, 0x100
	s_addc_u32 s43, s43, 0
	s_cmp_gt_u32 s44, 29
	s_barrier
	s_cbranch_scc0 .LBB0_344
	v_lshl_add_u32 v142, s0, 8, v147
	v_ashrrev_i32_e32 v143, 31, v142
	v_lshlrev_b64 v[128:129], 5, v[142:143]
	v_lshl_add_u64 v[132:133], s[4:5], 0, v[128:129]
	global_load_dwordx4 v[128:131], v[132:133], off offset:16
	s_nop 0
	global_load_dwordx4 v[132:135], v[132:133], off
	s_mov_b32 s0, 0x3727c5ac
	s_mov_b32 s18, 0x3a000000
	s_mov_b32 s11, 0x800000
	s_mov_b64 s[20:21], s[16:17]
	s_waitcnt vmcnt(0)
	v_mov_b32_e32 v144, v133
	v_mov_b32_e32 v145, v134
	v_mov_b32_e32 v133, v135
	v_pk_add_f32 v[150:151], v[144:145], v[132:133]
	v_or_b32_e32 v144, 16, v142
	v_mov_b32_e32 v132, v130
	v_mov_b32_e32 v133, v128
	v_mov_b32_e32 v128, v131
	v_ashrrev_i32_e32 v145, 31, v144
	v_pk_add_f32 v[152:153], v[132:133], v[128:129]
	v_lshlrev_b64 v[128:129], 5, v[144:145]
	v_lshl_add_u64 v[132:133], s[4:5], 0, v[128:129]
	global_load_dwordx4 v[128:131], v[132:133], off offset:16
	s_nop 0
	global_load_dwordx4 v[132:135], v[132:133], off
	s_waitcnt vmcnt(0)
	v_mov_b32_e32 v154, v133
	v_mov_b32_e32 v155, v134
	v_mov_b32_e32 v133, v135
	v_pk_add_f32 v[132:133], v[154:155], v[132:133]
	v_mov_b32_e32 v134, v130
	v_mov_b32_e32 v135, v128
	v_mov_b32_e32 v128, v131
	v_pk_add_f32 v[128:129], v[134:135], v[128:129]
	v_mov_b32_e32 v130, v132
	v_mov_b32_e32 v131, v150
	v_mov_b32_e32 v150, v133
	v_pk_add_f32 v[130:131], v[130:131], v[150:151]
	v_mov_b32_e32 v132, v129
	v_mov_b32_e32 v133, v153
	v_pk_add_f32 v[130:131], v[130:131], v[132:133]
	v_mov_b32_e32 v129, v152
	v_pk_add_f32 v[128:129], v[128:129], v[130:131]
	v_mov_b64_e32 v[150:151], s[0:1]
	v_pk_fma_f32 v[128:129], v[128:129], s[18:19], v[150:151] op_sel_hi:[1,0,0]
	v_or_b32_e32 v152, 32, v142
	v_mul_f32_e32 v130, 0x4b800000, v129
	v_cmp_gt_f32_e64 s[0:1], s11, v129
	v_cmp_gt_f32_e32 vcc, s11, v128
	v_ashrrev_i32_e32 v153, 31, v152
	v_cndmask_b32_e64 v129, v129, v130, s[0:1]
	v_rsq_f32_e32 v129, v129
	s_nop 0
	v_mul_f32_e32 v130, 0x45800000, v129
	v_cndmask_b32_e64 v148, v129, v130, s[0:1]
	v_mul_f32_e32 v129, 0x4b800000, v128
	v_cndmask_b32_e32 v128, v128, v129, vcc
	v_rsq_f32_e32 v128, v128
	v_pk_mul_f32 v[106:107], v[106:107], v[148:149] op_sel_hi:[1,0]
	v_pk_mul_f32 v[104:105], v[104:105], v[148:149] op_sel_hi:[1,0]
	v_pk_mul_f32 v[114:115], v[114:115], v[148:149] op_sel_hi:[1,0]
	v_mul_f32_e32 v129, 0x45800000, v128
	v_cndmask_b32_e32 v146, v128, v129, vcc
	v_lshlrev_b64 v[128:129], 5, v[152:153]
	v_lshl_add_u64 v[132:133], s[4:5], 0, v[128:129]
	global_load_dwordx4 v[128:131], v[132:133], off offset:16
	s_nop 0
	global_load_dwordx4 v[132:135], v[132:133], off
	v_cvt_pk_bf16_f32 v104, v104, v105
	v_cvt_pk_bf16_f32 v105, v106, v107
	v_pk_mul_f32 v[90:91], v[90:91], v[146:147] op_sel_hi:[1,0]
	v_pk_mul_f32 v[88:89], v[88:89], v[146:147] op_sel_hi:[1,0]
	v_pk_mul_f32 v[112:113], v[112:113], v[148:149] op_sel_hi:[1,0]
	v_cvt_pk_bf16_f32 v88, v88, v89
	v_cvt_pk_bf16_f32 v89, v90, v91
	v_pk_mul_f32 v[98:99], v[98:99], v[146:147] op_sel_hi:[1,0]
	v_pk_mul_f32 v[96:97], v[96:97], v[146:147] op_sel_hi:[1,0]
	v_cvt_pk_bf16_f32 v112, v112, v113
	v_cvt_pk_bf16_f32 v113, v114, v115
	v_cvt_pk_bf16_f32 v96, v96, v97
	v_cvt_pk_bf16_f32 v97, v98, v99
	v_pk_mul_f32 v[126:127], v[126:127], v[148:149] op_sel_hi:[1,0]
	v_pk_mul_f32 v[124:125], v[124:125], v[148:149] op_sel_hi:[1,0]
	v_pk_mul_f32 v[122:123], v[122:123], v[148:149] op_sel_hi:[1,0]
	v_pk_mul_f32 v[120:121], v[120:121], v[148:149] op_sel_hi:[1,0]
	v_pk_mul_f32 v[106:107], v[118:119], v[146:147] op_sel_hi:[1,0]
	v_pk_mul_f32 v[110:111], v[110:111], v[146:147] op_sel_hi:[1,0]
	v_pk_mul_f32 v[108:109], v[108:109], v[146:147] op_sel_hi:[1,0]
	v_cvt_pk_bf16_f32 v124, v124, v125
	v_cvt_pk_bf16_f32 v125, v126, v127
	v_cvt_pk_bf16_f32 v120, v120, v121
	v_cvt_pk_bf16_f32 v121, v122, v123
	s_waitcnt vmcnt(0)
; DEV f32x4 gelu4(f32x4 v) { f32x2 a = gelu_pk((f32x2){v[0], v[1]}), b = gelu_pk((f32x2){v[2], v[3]}); return (f32x4){a.x, a.y, b.x, b.y}; }
; DEV float rowscale(const float* ss, int row) { const f32x4 a = *(const f32x4*)(ss + (size_t)row * 8), b = *(const f32x4*)(ss + (size_t)row * 8 + 4);
;     return rsqrtf(((a[0] + a[1]) + (a[2] + a[3]) + (b[0] + b[1]) + (b[2] + b[3])) * (1.0f / 2048.0f) + EPS); }
; template <int ACT, bool PERM>
; DEV void store_bf16_tile(AccRef acc, u16* O, int ld, int row0, int col0, const float* ss) {
;     float rsv[2][4];
; #pragma unroll
;     for (int ai = 0; ai < 2; ++ai)
; #pragma unroll
;         for (int m = 0; m < 4; ++m) rsv[ai][m] = ss ? rowscale(ss, row0 + ai * 128 + m * 16) : 1.0f;
; #pragma unroll
;     for (int ai = 0; ai < 2; ++ai)
; #pragma unroll
;         for (int m = 0; m < 4; ++m) { u16* rowp = O + (size_t)(row0 + ai * 128 + m * 16) * ld + col0; const float rs = rsv[ai][m];
; #pragma unroll
;             for (int bj = 0; bj < 2; ++bj) { f32x4 v0 = acc[ai][bj][m][0] * rs, v1 = acc[ai][bj][m][1] * rs; if (ACT == 1) { v0 = gelu4(v0); v1 = gelu4(v1); }
	v_mov_b32_e32 v154, v133
	v_mov_b32_e32 v155, v134
	v_mov_b32_e32 v133, v135
	v_pk_add_f32 v[174:175], v[154:155], v[132:133]
	v_or_b32_e32 v154, 48, v142
	v_mov_b32_e32 v132, v130
	v_mov_b32_e32 v133, v128
	v_mov_b32_e32 v128, v131
	v_ashrrev_i32_e32 v155, 31, v154
	v_pk_add_f32 v[176:177], v[132:133], v[128:129]
	v_lshlrev_b64 v[128:129], 5, v[154:155]
	v_lshl_add_u64 v[132:133], s[4:5], 0, v[128:129]
	global_load_dwordx4 v[128:131], v[132:133], off offset:16
	s_nop 0
	global_load_dwordx4 v[132:135], v[132:133], off
	s_waitcnt vmcnt(0)
	v_mov_b32_e32 v178, v133
	v_mov_b32_e32 v179, v134
	v_mov_b32_e32 v133, v135
	v_pk_add_f32 v[132:133], v[178:179], v[132:133]
	v_mov_b32_e32 v134, v130
	v_mov_b32_e32 v135, v128
	v_mov_b32_e32 v128, v131
	v_pk_add_f32 v[128:129], v[134:135], v[128:129]
	v_mov_b32_e32 v130, v132
	v_mov_b32_e32 v131, v174
	v_mov_b32_e32 v174, v133
	v_pk_add_f32 v[130:131], v[130:131], v[174:175]
	v_mov_b32_e32 v132, v129
	v_mov_b32_e32 v133, v177
	v_pk_add_f32 v[130:131], v[130:131], v[132:133]
	v_mov_b32_e32 v129, v176
	v_pk_add_f32 v[128:129], v[128:129], v[130:131]
	v_add_u32_e32 v174, 0x80, v142
	v_pk_fma_f32 v[128:129], v[128:129], s[18:19], v[150:151] op_sel_hi:[1,0,0]
	v_ashrrev_i32_e32 v175, 31, v174
	v_mul_f32_e32 v130, 0x4b800000, v129
	v_cmp_gt_f32_e64 s[0:1], s11, v129
	v_cmp_gt_f32_e32 vcc, s11, v128
	s_nop 0
	v_cndmask_b32_e64 v129, v129, v130, s[0:1]
	v_rsq_f32_e32 v129, v129
	s_nop 0
	v_mul_f32_e32 v130, 0x45800000, v129
	v_cndmask_b32_e64 v158, v129, v130, s[0:1]
	v_mul_f32_e32 v129, 0x4b800000, v128
	v_cndmask_b32_e32 v128, v128, v129, vcc
	v_rsq_f32_e32 v128, v128
	v_pk_mul_f32 v[74:75], v[74:75], v[158:159] op_sel_hi:[1,0]
	v_pk_mul_f32 v[72:73], v[72:73], v[158:159] op_sel_hi:[1,0]
	v_pk_mul_f32 v[82:83], v[82:83], v[158:159] op_sel_hi:[1,0]
	v_mul_f32_e32 v129, 0x45800000, v128
	v_cndmask_b32_e32 v156, v128, v129, vcc
	v_lshlrev_b64 v[128:129], 5, v[174:175]
	v_lshl_add_u64 v[132:133], s[4:5], 0, v[128:129]
	global_load_dwordx4 v[128:131], v[132:133], off offset:16
	s_nop 0
	global_load_dwordx4 v[132:135], v[132:133], off
	v_cvt_pk_bf16_f32 v72, v72, v73
	v_cvt_pk_bf16_f32 v73, v74, v75
	v_pk_mul_f32 v[66:67], v[66:67], v[156:157] op_sel_hi:[1,0]
	v_pk_mul_f32 v[64:65], v[64:65], v[156:157] op_sel_hi:[1,0]
	v_pk_mul_f32 v[80:81], v[80:81], v[158:159] op_sel_hi:[1,0]
	v_cvt_pk_bf16_f32 v64, v64, v65
	v_cvt_pk_bf16_f32 v65, v66, v67
	v_cvt_pk_bf16_f32 v80, v80, v81
	v_cvt_pk_bf16_f32 v81, v82, v83
	v_pk_mul_f32 v[90:91], v[102:103], v[158:159] op_sel_hi:[1,0]
	v_pk_mul_f32 v[94:95], v[94:95], v[158:159] op_sel_hi:[1,0]
	v_pk_mul_f32 v[92:93], v[92:93], v[158:159] op_sel_hi:[1,0]
	v_pk_mul_f32 v[74:75], v[86:87], v[156:157] op_sel_hi:[1,0]
	v_pk_mul_f32 v[78:79], v[78:79], v[156:157] op_sel_hi:[1,0]
	v_pk_mul_f32 v[76:77], v[76:77], v[156:157] op_sel_hi:[1,0]
	v_pk_mul_f32 v[70:71], v[70:71], v[156:157] op_sel_hi:[1,0]
	v_pk_mul_f32 v[68:69], v[68:69], v[156:157] op_sel_hi:[1,0]
	s_waitcnt vmcnt(0)
	v_mov_b32_e32 v176, v133
	v_mov_b32_e32 v177, v134
	v_mov_b32_e32 v133, v135
	v_pk_add_f32 v[178:179], v[176:177], v[132:133]
	v_add_u32_e32 v176, 0x90, v142
	v_mov_b32_e32 v132, v130
	v_mov_b32_e32 v133, v128
	v_mov_b32_e32 v128, v131
	v_ashrrev_i32_e32 v177, 31, v176
	v_pk_add_f32 v[180:181], v[132:133], v[128:129]
	v_lshlrev_b64 v[128:129], 5, v[176:177]
	v_lshl_add_u64 v[132:133], s[4:5], 0, v[128:129]
	global_load_dwordx4 v[128:131], v[132:133], off offset:16
	s_nop 0
	global_load_dwordx4 v[132:135], v[132:133], off
	v_cvt_pk_bf16_f32 v68, v68, v69
	v_cvt_pk_bf16_f32 v69, v70, v71
	s_waitcnt vmcnt(0)
	v_mov_b32_e32 v182, v133
	v_mov_b32_e32 v183, v134
	v_mov_b32_e32 v133, v135
	v_pk_add_f32 v[132:133], v[182:183], v[132:133]
	v_mov_b32_e32 v134, v130
	v_mov_b32_e32 v135, v128
	v_mov_b32_e32 v128, v131
	v_pk_add_f32 v[128:129], v[134:135], v[128:129]
	v_mov_b32_e32 v130, v132
	v_mov_b32_e32 v131, v178
	v_mov_b32_e32 v178, v133
	v_pk_add_f32 v[130:131], v[130:131], v[178:179]
	v_mov_b32_e32 v132, v129
	v_mov_b32_e32 v133, v181
	v_pk_add_f32 v[130:131], v[130:131], v[132:133]
	v_mov_b32_e32 v129, v180
	v_pk_add_f32 v[128:129], v[128:129], v[130:131]
	v_add_u32_e32 v182, 0xa0, v142
	v_pk_fma_f32 v[128:129], v[128:129], s[18:19], v[150:151] op_sel_hi:[1,0,0]
	v_ashrrev_i32_e32 v183, 31, v182
	v_mul_f32_e32 v130, 0x4b800000, v129
	v_cmp_gt_f32_e64 s[0:1], s11, v129
	v_cmp_gt_f32_e32 vcc, s11, v128
	s_nop 0
	v_cndmask_b32_e64 v129, v129, v130, s[0:1]
	v_rsq_f32_e32 v129, v129
	s_nop 0
	v_mul_f32_e32 v130, 0x45800000, v129
	v_cndmask_b32_e64 v180, v129, v130, s[0:1]
	v_mul_f32_e32 v129, 0x4b800000, v128
	v_cndmask_b32_e32 v128, v128, v129, vcc
	v_rsq_f32_e32 v128, v128
	v_pk_mul_f32 v[42:43], v[42:43], v[180:181] op_sel_hi:[1,0]
	v_pk_mul_f32 v[40:41], v[40:41], v[180:181] op_sel_hi:[1,0]
	v_pk_mul_f32 v[50:51], v[50:51], v[180:181] op_sel_hi:[1,0]
	v_mul_f32_e32 v129, 0x45800000, v128
	v_cndmask_b32_e32 v178, v128, v129, vcc
	v_lshlrev_b64 v[128:129], 5, v[182:183]
	v_lshl_add_u64 v[132:133], s[4:5], 0, v[128:129]
	global_load_dwordx4 v[128:131], v[132:133], off offset:16
	s_nop 0
	global_load_dwordx4 v[132:135], v[132:133], off
	v_cvt_pk_bf16_f32 v40, v40, v41
	v_cvt_pk_bf16_f32 v41, v42, v43
	v_pk_mul_f32 v[26:27], v[26:27], v[178:179] op_sel_hi:[1,0]
	v_pk_mul_f32 v[24:25], v[24:25], v[178:179] op_sel_hi:[1,0]
	v_pk_mul_f32 v[48:49], v[48:49], v[180:181] op_sel_hi:[1,0]
	v_cvt_pk_bf16_f32 v24, v24, v25
	v_cvt_pk_bf16_f32 v25, v26, v27
	v_pk_mul_f32 v[34:35], v[34:35], v[178:179] op_sel_hi:[1,0]
	v_pk_mul_f32 v[32:33], v[32:33], v[178:179] op_sel_hi:[1,0]
	v_cvt_pk_bf16_f32 v48, v48, v49
	v_cvt_pk_bf16_f32 v49, v50, v51
	v_cvt_pk_bf16_f32 v32, v32, v33
	v_cvt_pk_bf16_f32 v33, v34, v35
	v_pk_mul_f32 v[62:63], v[62:63], v[180:181] op_sel_hi:[1,0]
	v_pk_mul_f32 v[60:61], v[60:61], v[180:181] op_sel_hi:[1,0]
	v_pk_mul_f32 v[58:59], v[58:59], v[180:181] op_sel_hi:[1,0]
	v_pk_mul_f32 v[56:57], v[56:57], v[180:181] op_sel_hi:[1,0]
	v_pk_mul_f32 v[42:43], v[54:55], v[178:179] op_sel_hi:[1,0]
	v_pk_mul_f32 v[46:47], v[46:47], v[178:179] op_sel_hi:[1,0]
	v_pk_mul_f32 v[44:45], v[44:45], v[178:179] op_sel_hi:[1,0]
	v_cvt_pk_bf16_f32 v60, v60, v61
	v_cvt_pk_bf16_f32 v61, v62, v63
	v_cvt_pk_bf16_f32 v56, v56, v57
	v_cvt_pk_bf16_f32 v57, v58, v59
	s_waitcnt vmcnt(0)
; DEV bf16x8 pack8(f32x4 a, f32x4 b) { u32x4 w; w.x = cvt_pk_bf16(a[0], a[1]); w.y = cvt_pk_bf16(a[2], a[3]); w.z = cvt_pk_bf16(b[0], b[1]); w.w = cvt_pk_bf16(b[2], b[3]); return __builtin_bit_cast(bf16x8, w); }
; DEV u32x2 pack4(f32x4 a) { u32x2 w; w.x = cvt_pk_bf16(a[0], a[1]); w.y = cvt_pk_bf16(a[2], a[3]); return w; }
; DEV f32x4 gelu4(f32x4 v) { f32x2 a = gelu_pk((f32x2){v[0], v[1]}), b = gelu_pk((f32x2){v[2], v[3]}); return (f32x4){a.x, a.y, b.x, b.y}; }
; template <int ACT, bool PERM>
; DEV void store_bf16_tile(AccRef acc, u16* O, int ld, int row0, int col0, const float* ss) {
;     float rsv[2][4];
; #pragma unroll
;     for (int ai = 0; ai < 2; ++ai)
; #pragma unroll
;         for (int m = 0; m < 4; ++m) rsv[ai][m] = ss ? rowscale(ss, row0 + ai * 128 + m * 16) : 1.0f;
; #pragma unroll
;     for (int ai = 0; ai < 2; ++ai)
; #pragma unroll
;         for (int m = 0; m < 4; ++m) { u16* rowp = O + (size_t)(row0 + ai * 128 + m * 16) * ld + col0; const float rs = rsv[ai][m];
; #pragma unroll
;             for (int bj = 0; bj < 2; ++bj) { f32x4 v0 = acc[ai][bj][m][0] * rs, v1 = acc[ai][bj][m][1] * rs; if (ACT == 1) { v0 = gelu4(v0); v1 = gelu4(v1); }
;                 if (PERM) *(u32x4*)(rowp + bj * 128) = __builtin_bit_cast(u32x4, pack8(v0, v1));
;                 else { *(u32x2*)(rowp + bj * 128) = pack4(v0); *(u32x2*)(rowp + bj * 128 + 16) = pack4(v1); } } }
	v_mov_b32_e32 v184, v133
	v_mov_b32_e32 v185, v134
	v_mov_b32_e32 v133, v135
	v_pk_add_f32 v[188:189], v[184:185], v[132:133]
	v_add_u32_e32 v184, 0xb0, v142
	v_mov_b32_e32 v132, v130
	v_mov_b32_e32 v133, v128
	v_mov_b32_e32 v128, v131
	v_ashrrev_i32_e32 v185, 31, v184
	v_pk_add_f32 v[186:187], v[132:133], v[128:129]
	v_lshlrev_b64 v[128:129], 5, v[184:185]
	v_lshl_add_u64 v[132:133], s[4:5], 0, v[128:129]
	global_load_dwordx4 v[128:131], v[132:133], off offset:16
	s_nop 0
	global_load_dwordx4 v[132:135], v[132:133], off
	s_waitcnt vmcnt(0)
	v_mov_b32_e32 v190, v133
	v_mov_b32_e32 v191, v134
	v_mov_b32_e32 v133, v135
	v_pk_add_f32 v[132:133], v[190:191], v[132:133]
	v_mov_b32_e32 v134, v130
	v_mov_b32_e32 v135, v128
	v_mov_b32_e32 v128, v131
	v_pk_add_f32 v[128:129], v[134:135], v[128:129]
	v_mov_b32_e32 v130, v132
	v_mov_b32_e32 v131, v188
	v_mov_b32_e32 v188, v133
	v_pk_add_f32 v[130:131], v[130:131], v[188:189]
	v_mov_b32_e32 v132, v129
	v_mov_b32_e32 v133, v187
	v_pk_add_f32 v[130:131], v[130:131], v[132:133]
	v_mov_b32_e32 v129, v186
	v_pk_add_f32 v[128:129], v[128:129], v[130:131]
	v_lshl_or_b32 v132, s40, 8, v157
	v_pk_fma_f32 v[128:129], v[128:129], s[18:19], v[150:151] op_sel_hi:[1,0,0]
	v_ashrrev_i32_e32 v133, 31, v132
	v_mul_f32_e32 v130, 0x4b800000, v129
	v_cmp_gt_f32_e64 s[0:1], s11, v129
	v_lshlrev_b64 v[134:135], 10, v[142:143]
	v_cmp_gt_f32_e32 vcc, s11, v128
	v_cndmask_b32_e64 v129, v129, v130, s[0:1]
	v_rsq_f32_e32 v129, v129
	s_mov_b32 s40, s10
	s_mov_b64 s[18:19], s[14:15]
	v_mul_f32_e32 v130, 0x45800000, v129
	v_cndmask_b32_e64 v130, v129, v130, s[0:1]
	v_readlane_b32 s0, v250, 11
	v_readlane_b32 s1, v250, 12
	v_mul_f32_e32 v129, 0x4b800000, v128
	v_cndmask_b32_e32 v128, v128, v129, vcc
	v_lshl_add_u64 v[132:133], v[132:133], 1, s[0:1]
	v_lshl_add_u64 v[134:135], v[132:133], 0, v[134:135]
	global_store_dwordx2 v[134:135], v[104:105], off offset:288
	v_lshlrev_b64 v[104:105], 10, v[144:145]
	v_lshl_add_u64 v[104:105], v[132:133], 0, v[104:105]
	global_store_dwordx2 v[104:105], v[88:89], off offset:288
	v_lshlrev_b64 v[88:89], 10, v[152:153]
	v_lshl_add_u64 v[88:89], v[132:133], 0, v[88:89]
	global_store_dwordx2 v[88:89], v[72:73], off offset:288
	v_lshlrev_b64 v[72:73], 10, v[154:155]
	v_lshl_add_u64 v[72:73], v[132:133], 0, v[72:73]
	v_rsq_f32_e32 v128, v128
	global_store_dwordx2 v[72:73], v[64:65], off offset:288
	v_lshlrev_b64 v[64:65], 10, v[174:175]
	v_lshl_add_u64 v[64:65], v[132:133], 0, v[64:65]
	global_store_dwordx2 v[64:65], v[40:41], off offset:288
	v_lshlrev_b64 v[40:41], 10, v[176:177]
	v_lshl_add_u64 v[40:41], v[132:133], 0, v[40:41]
	v_mul_f32_e32 v129, 0x45800000, v128
	global_store_dwordx2 v[40:41], v[24:25], off offset:288
	v_lshlrev_b64 v[24:25], 10, v[182:183]
	v_pk_mul_f32 v[18:19], v[18:19], v[130:131] op_sel_hi:[1,0]
	v_pk_mul_f32 v[16:17], v[16:17], v[130:131] op_sel_hi:[1,0]
	v_pk_mul_f32 v[10:11], v[10:11], v[130:131] op_sel_hi:[1,0]
	v_pk_mul_f32 v[8:9], v[8:9], v[130:131] op_sel_hi:[1,0]
	v_cndmask_b32_e32 v128, v128, v129, vcc
	v_lshl_add_u64 v[24:25], v[132:133], 0, v[24:25]
	v_cvt_pk_bf16_f32 v16, v16, v17
	v_cvt_pk_bf16_f32 v17, v18, v19
	v_cvt_pk_bf16_f32 v8, v8, v9
	v_cvt_pk_bf16_f32 v9, v10, v11
	global_store_dwordx2 v[134:135], v[112:113], off offset:256
	v_pk_mul_f32 v[112:113], v[116:117], v[146:147] op_sel_hi:[1,0]
	global_store_dwordx2 v[104:105], v[96:97], off offset:256
	v_pk_mul_f32 v[96:97], v[100:101], v[158:159] op_sel_hi:[1,0]
	global_store_dwordx2 v[88:89], v[80:81], off offset:256
	v_pk_mul_f32 v[80:81], v[84:85], v[156:157] op_sel_hi:[1,0]
	global_store_dwordx2 v[64:65], v[48:49], off offset:256
	v_pk_mul_f32 v[48:49], v[52:53], v[178:179] op_sel_hi:[1,0]
	global_store_dwordx2 v[40:41], v[32:33], off offset:256
	v_pk_mul_f32 v[26:27], v[38:39], v[130:131] op_sel_hi:[1,0]
	v_pk_mul_f32 v[32:33], v[36:37], v[130:131] op_sel_hi:[1,0]
	v_pk_mul_f32 v[30:31], v[30:31], v[130:131] op_sel_hi:[1,0]
	v_pk_mul_f32 v[28:29], v[28:29], v[130:131] op_sel_hi:[1,0]
	global_store_dwordx2 v[24:25], v[16:17], off offset:256
	global_store_dwordx2 v[24:25], v[8:9], off offset:288
	v_lshlrev_b64 v[8:9], 10, v[184:185]
	v_pk_mul_f32 v[10:11], v[22:23], v[128:129] op_sel_hi:[1,0]
	v_pk_mul_f32 v[16:17], v[20:21], v[128:129] op_sel_hi:[1,0]
	v_pk_mul_f32 v[14:15], v[14:15], v[128:129] op_sel_hi:[1,0]
	v_pk_mul_f32 v[12:13], v[12:13], v[128:129] op_sel_hi:[1,0]
	v_pk_mul_f32 v[6:7], v[6:7], v[128:129] op_sel_hi:[1,0]
	v_pk_mul_f32 v[4:5], v[4:5], v[128:129] op_sel_hi:[1,0]
	v_pk_mul_f32 v[2:3], v[2:3], v[128:129] op_sel_hi:[1,0]
	v_pk_mul_f32 v[0:1], v[0:1], v[128:129] op_sel_hi:[1,0]
	v_cvt_pk_bf16_f32 v112, v112, v113
	v_cvt_pk_bf16_f32 v113, v106, v107
	v_cvt_pk_bf16_f32 v106, v108, v109
	v_cvt_pk_bf16_f32 v107, v110, v111
	v_cvt_pk_bf16_f32 v96, v96, v97
	v_cvt_pk_bf16_f32 v97, v90, v91
	v_cvt_pk_bf16_f32 v90, v92, v93
	v_cvt_pk_bf16_f32 v91, v94, v95
	v_cvt_pk_bf16_f32 v80, v80, v81
	v_cvt_pk_bf16_f32 v81, v74, v75
	v_cvt_pk_bf16_f32 v74, v76, v77
	v_cvt_pk_bf16_f32 v75, v78, v79
	v_cvt_pk_bf16_f32 v48, v48, v49
	v_cvt_pk_bf16_f32 v49, v42, v43
	v_cvt_pk_bf16_f32 v42, v44, v45
	v_cvt_pk_bf16_f32 v43, v46, v47
	v_cvt_pk_bf16_f32 v32, v32, v33
	v_cvt_pk_bf16_f32 v33, v26, v27
	v_cvt_pk_bf16_f32 v26, v28, v29
	v_cvt_pk_bf16_f32 v27, v30, v31
	v_lshl_add_u64 v[8:9], v[132:133], 0, v[8:9]
	v_cvt_pk_bf16_f32 v16, v16, v17
	v_cvt_pk_bf16_f32 v17, v10, v11
	v_cvt_pk_bf16_f32 v10, v12, v13
	v_cvt_pk_bf16_f32 v11, v14, v15
	v_cvt_pk_bf16_f32 v4, v4, v5
	v_cvt_pk_bf16_f32 v5, v6, v7
	v_cvt_pk_bf16_f32 v0, v0, v1
	v_cvt_pk_bf16_f32 v1, v2, v3
	s_and_b64 vcc, exec, s[6:7]
	s_mov_b32 s0, s12
	global_store_dwordx2 v[134:135], v[124:125], off
	global_store_dwordx2 v[134:135], v[120:121], off offset:32
	global_store_dwordx2 v[104:105], v[112:113], off
	global_store_dwordx2 v[104:105], v[106:107], off offset:32
	global_store_dwordx2 v[88:89], v[96:97], off
	global_store_dwordx2 v[88:89], v[90:91], off offset:32
	global_store_dwordx2 v[72:73], v[80:81], off
	global_store_dwordx2 v[72:73], v[74:75], off offset:32
	global_store_dwordx2 v[72:73], v[68:69], off offset:256
	global_store_dwordx2 v[64:65], v[60:61], off
	global_store_dwordx2 v[64:65], v[56:57], off offset:32
	global_store_dwordx2 v[40:41], v[48:49], off
	global_store_dwordx2 v[40:41], v[42:43], off offset:32
	global_store_dwordx2 v[24:25], v[32:33], off
	global_store_dwordx2 v[24:25], v[26:27], off offset:32
	global_store_dwordx2 v[8:9], v[16:17], off
	global_store_dwordx2 v[8:9], v[10:11], off offset:32
	global_store_dwordx2 v[8:9], v[4:5], off offset:256
	global_store_dwordx2 v[8:9], v[0:1], off offset:288
	s_cbranch_vccz .LBB0_337
	s_waitcnt vmcnt(0)
	s_cmpk_gt_u32 s25, 0xff
	s_cbranch_scc1 .LBB0_348
	s_barrier

; #define PG8_STAGE(bufoff, gbase, voff) do { _Pragma("unroll") for (int _i = 0; _i < 2; ++_i) \
;         __builtin_amdgcn_global_load_lds((const unsigned*)((const char*)(gbase) + (voff)[_i]), (LAS unsigned*)(lds + (bufoff) + ldsw + _i * 8192), 16, 0, 0); } while (0)
; #define PG8_LDA(dst, b, h) do { _Pragma("unroll") for (int m = 0; m < 4; ++m) _Pragma("unroll") for (int k = 0; k < 2; ++k) dst[m][k] = *(const LAS bf16x8*)(lds + PG8_SA(b, h) + aoff + m * 2048 + k * 1024); } while (0)
; #define PG8_LDB(dst, b, h) do { _Pragma("unroll") for (int n = 0; n < 2; ++n) _Pragma("unroll") for (int k = 0; k < 2; ++k) dst[n][k] = *(const LAS bf16x8*)(lds + PG8_SB(b, h) + boff + n * 2048 + k * 1024); } while (0)
; #define PG8_MMA(ai, bj, At, Bt) do { __builtin_amdgcn_s_setprio(1); _Pragma("unroll") for (int m = 0; m < 4; ++m) _Pragma("unroll") for (int n = 0; n < 2; ++n) _Pragma("unroll") for (int k = 0; k < 2; ++k) \
;         acc[ai][bj][m][n] = __builtin_amdgcn_mfma_f32_16x16x32_bf16(Bt[n][k], At[m][k], acc[ai][bj][m][n], 0, 0, 0); __builtin_amdgcn_s_setprio(0); } while (0)
; #define PG8_WAIT_V(n) asm volatile("s_waitcnt vmcnt(" #n ")" ::: "memory")
; #define PG8_WAIT_L(n) asm volatile("s_waitcnt lgkmcnt(" #n ")" ::: "memory")
; #define PG8_BAR __builtin_amdgcn_s_barrier()
; #define PG8_SCHED __builtin_amdgcn_sched_barrier(0)
; template <class Epi>
; DEV void gemm_phase(LAS unsigned char* lds, const Gemm g, const StaticOrder& S, const Epi& E) {
;     ...
;             PG8_LDB(B0, 0, 0); PG8_SCHED; PG8_LDA(At, 0, 0); PG8_STAGE(PG8_SA(1, 1), a1 + hstep, voffA);
;             PG8_WAIT_L(8); PG8_BAR; PG8_WAIT_L(0); PG8_MMA(0, 0, At, B0); PG8_BAR; PG8_SCHED;
;             PG8_LDB(B1, 0, 1); PG8_STAGE(PG8_SB(0, 0), b2, voffB);
;             PG8_BAR; PG8_WAIT_L(0); PG8_MMA(0, 1, At, B1); PG8_BAR;
;             PG8_LDA(At, 0, 1); PG8_STAGE(PG8_SA(0, 0), a2, voffA);
;             PG8_BAR; PG8_WAIT_L(0); PG8_MMA(1, 0, At, B0); PG8_BAR; PG8_SCHED;
;             PG8_STAGE(PG8_SB(0, 1), b2 + hstep, voffB);
;             PG8_WAIT_V(6); PG8_BAR; PG8_MMA(1, 1, At, B1); PG8_BAR;
.LBB0_362:
	s_add_u32 s26, s24, 0xfff80080
	s_addc_u32 s27, s25, -1
	s_add_i32 s56, 0, 0x10000
	v_add_u32_e32 v150, s56, v135
	ds_read_b128 v[138:141], v150
	ds_read_b128 v[142:145], v150 offset:1024
	ds_read_b128 v[146:149], v150 offset:2048
	ds_read_b128 v[150:153], v150 offset:3072
	s_cmp_eq_u32 s55, 28
	s_cselect_b32 s29, s19, s27
	s_cselect_b32 s28, s51, s26
	s_cselect_b32 s27, s17, s54
	s_cselect_b32 s26, s52, s53
	s_add_i32 m0, s13, 0xc000
	ds_read_b128 v[154:157], v137
	ds_read_b128 v[174:177], v137 offset:1024
	ds_read_b128 v[178:181], v137 offset:2048
	ds_read_b128 v[182:185], v137 offset:3072
	ds_read_b128 v[186:189], v137 offset:4096
	ds_read_b128 v[190:193], v137 offset:5120
	ds_read_b128 v[194:197], v137 offset:6144
	ds_read_b128 v[214:217], v137 offset:7168
	global_load_lds_dwordx4 v130, s[24:25]
	s_add_i32 m0, s13, 0xe000
	s_nop 0
	global_load_lds_dwordx4 v132, s[24:25]
	s_waitcnt lgkmcnt(8)
	s_barrier
	s_waitcnt lgkmcnt(0)
	v_mfma_f32_16x16x32_bf16 v[124:127], v[138:141], v[154:157], v[124:127]
	v_mfma_f32_16x16x32_bf16 v[120:123], v[146:149], v[154:157], v[120:123]
	v_mfma_f32_16x16x32_bf16 v[116:119], v[138:141], v[178:181], v[116:119]
	v_mfma_f32_16x16x32_bf16 v[108:111], v[146:149], v[178:181], v[108:111]
	v_mfma_f32_16x16x32_bf16 v[100:103], v[138:141], v[186:189], v[100:103]
	v_mfma_f32_16x16x32_bf16 v[92:95], v[146:149], v[186:189], v[92:95]
	v_mfma_f32_16x16x32_bf16 v[84:87], v[138:141], v[194:197], v[84:87]
	v_mfma_f32_16x16x32_bf16 v[76:79], v[146:149], v[194:197], v[76:79]
	v_mfma_f32_16x16x32_bf16 v[124:127], v[142:145], v[174:177], v[124:127]
	v_mfma_f32_16x16x32_bf16 v[120:123], v[150:153], v[174:177], v[120:123]
	v_mfma_f32_16x16x32_bf16 v[116:119], v[142:145], v[182:185], v[116:119]
	v_mfma_f32_16x16x32_bf16 v[108:111], v[150:153], v[182:185], v[108:111]
	v_mfma_f32_16x16x32_bf16 v[100:103], v[142:145], v[190:193], v[100:103]
	v_mfma_f32_16x16x32_bf16 v[92:95], v[150:153], v[190:193], v[92:95]
	v_mfma_f32_16x16x32_bf16 v[84:87], v[142:145], v[214:217], v[84:87]
	v_mfma_f32_16x16x32_bf16 v[76:79], v[150:153], v[214:217], v[76:79]
	s_barrier
	s_add_i32 s58, 0, 0x14000
	v_add_u32_e32 v158, s58, v135
	s_add_i32 s56, s56, s41
	ds_read_b128 v[218:221], v158
	ds_read_b128 v[222:225], v158 offset:1024
	ds_read_b128 v[226:229], v158 offset:2048
	ds_read_b128 v[230:233], v158 offset:3072
	v_lshl_add_u64 v[158:159], s[26:27], 0, v[160:161]
	s_mov_b32 m0, s56
	v_lshl_add_u64 v[234:235], s[26:27], 0, v[128:129]
	global_load_lds_dwordx4 v160, s[26:27]
	s_add_i32 m0, s56, 0x2000
	s_nop 0
	global_load_lds_dwordx4 v128, s[26:27]
	s_barrier
	s_waitcnt lgkmcnt(0)
	v_mfma_f32_16x16x32_bf16 v[112:115], v[218:221], v[154:157], v[112:115]
	v_mfma_f32_16x16x32_bf16 v[104:107], v[226:229], v[154:157], v[104:107]
	v_mfma_f32_16x16x32_bf16 v[96:99], v[218:221], v[178:181], v[96:99]
	v_mfma_f32_16x16x32_bf16 v[88:91], v[226:229], v[178:181], v[88:91]
	v_mfma_f32_16x16x32_bf16 v[80:83], v[218:221], v[186:189], v[80:83]
	v_mfma_f32_16x16x32_bf16 v[72:75], v[226:229], v[186:189], v[72:75]
	v_mfma_f32_16x16x32_bf16 v[68:71], v[218:221], v[194:197], v[68:71]
	v_mfma_f32_16x16x32_bf16 v[64:67], v[226:229], v[194:197], v[64:67]
	v_mfma_f32_16x16x32_bf16 v[112:115], v[222:225], v[174:177], v[112:115]
	v_mfma_f32_16x16x32_bf16 v[104:107], v[230:233], v[174:177], v[104:107]
	v_mfma_f32_16x16x32_bf16 v[96:99], v[222:225], v[182:185], v[96:99]
	v_mfma_f32_16x16x32_bf16 v[88:91], v[230:233], v[182:185], v[88:91]
	v_mfma_f32_16x16x32_bf16 v[80:83], v[222:225], v[190:193], v[80:83]
	v_mfma_f32_16x16x32_bf16 v[72:75], v[230:233], v[190:193], v[72:75]
	v_mfma_f32_16x16x32_bf16 v[68:71], v[222:225], v[214:217], v[68:71]
	v_mfma_f32_16x16x32_bf16 v[64:67], v[230:233], v[214:217], v[64:67]
	s_barrier
	s_mov_b32 m0, s13
	v_lshl_add_u64 v[236:237], s[28:29], 0, v[160:161]
	ds_read_b128 v[154:157], v137 offset:16384
	ds_read_b128 v[174:177], v137 offset:17408
	ds_read_b128 v[178:181], v137 offset:18432
	ds_read_b128 v[182:185], v137 offset:19456
	ds_read_b128 v[186:189], v137 offset:20480
	ds_read_b128 v[190:193], v137 offset:21504
	ds_read_b128 v[194:197], v137 offset:22528
	ds_read_b128 v[214:217], v137 offset:23552
	global_load_lds_dwordx4 v160, s[28:29]
	v_lshl_add_u64 v[238:239], s[28:29], 0, v[128:129]
	s_mov_b32 m0, s43
	s_nop 0
	global_load_lds_dwordx4 v128, s[28:29]
	s_barrier
	s_waitcnt lgkmcnt(0)
	v_mfma_f32_16x16x32_bf16 v[60:63], v[138:141], v[154:157], v[60:63]
	v_mfma_f32_16x16x32_bf16 v[56:59], v[146:149], v[154:157], v[56:59]
	v_mfma_f32_16x16x32_bf16 v[52:55], v[138:141], v[178:181], v[52:55]
	v_mfma_f32_16x16x32_bf16 v[44:47], v[146:149], v[178:181], v[44:47]
	v_mfma_f32_16x16x32_bf16 v[36:39], v[138:141], v[186:189], v[36:39]
	v_mfma_f32_16x16x32_bf16 v[28:31], v[146:149], v[186:189], v[28:31]
	v_mfma_f32_16x16x32_bf16 v[20:23], v[138:141], v[194:197], v[20:23]
	v_mfma_f32_16x16x32_bf16 v[12:15], v[146:149], v[194:197], v[12:15]
	v_mfma_f32_16x16x32_bf16 v[60:63], v[142:145], v[174:177], v[60:63]
	v_mfma_f32_16x16x32_bf16 v[56:59], v[150:153], v[174:177], v[56:59]
	v_mfma_f32_16x16x32_bf16 v[52:55], v[142:145], v[182:185], v[52:55]
	v_mfma_f32_16x16x32_bf16 v[44:47], v[150:153], v[182:185], v[44:47]
	v_mfma_f32_16x16x32_bf16 v[36:39], v[142:145], v[190:193], v[36:39]
	v_mfma_f32_16x16x32_bf16 v[28:31], v[150:153], v[190:193], v[28:31]
	v_mfma_f32_16x16x32_bf16 v[20:23], v[142:145], v[214:217], v[20:23]
	v_mfma_f32_16x16x32_bf16 v[12:15], v[150:153], v[214:217], v[12:15]
	s_barrier
	s_add_u32 s56, s26, 0x80000
	s_addc_u32 s57, s27, 0
	s_add_i32 s58, s58, s41
	s_mov_b32 m0, s58
	s_nop 0
	global_load_lds_dwordx4 v160, s[56:57]
	s_add_i32 m0, s58, 0x2000
	s_nop 0
	global_load_lds_dwordx4 v128, s[56:57]
	s_waitcnt vmcnt(6)
	s_barrier
; #define PG8_STAGE(bufoff, gbase, voff) do { _Pragma("unroll") for (int _i = 0; _i < 2; ++_i) \
;         __builtin_amdgcn_global_load_lds((const unsigned*)((const char*)(gbase) + (voff)[_i]), (LAS unsigned*)(lds + (bufoff) + ldsw + _i * 8192), 16, 0, 0); } while (0)
; #define PG8_LDA(dst, b, h) do { _Pragma("unroll") for (int m = 0; m < 4; ++m) _Pragma("unroll") for (int k = 0; k < 2; ++k) dst[m][k] = *(const LAS bf16x8*)(lds + PG8_SA(b, h) + aoff + m * 2048 + k * 1024); } while (0)
; #define PG8_LDB(dst, b, h) do { _Pragma("unroll") for (int n = 0; n < 2; ++n) _Pragma("unroll") for (int k = 0; k < 2; ++k) dst[n][k] = *(const LAS bf16x8*)(lds + PG8_SB(b, h) + boff + n * 2048 + k * 1024); } while (0)
; #define PG8_MMA(ai, bj, At, Bt) do { __builtin_amdgcn_s_setprio(1); _Pragma("unroll") for (int m = 0; m < 4; ++m) _Pragma("unroll") for (int n = 0; n < 2; ++n) _Pragma("unroll") for (int k = 0; k < 2; ++k) \
;         acc[ai][bj][m][n] = __builtin_amdgcn_mfma_f32_16x16x32_bf16(Bt[n][k], At[m][k], acc[ai][bj][m][n], 0, 0, 0); __builtin_amdgcn_s_setprio(0); } while (0)
; #define PG8_WAIT_V(n) asm volatile("s_waitcnt vmcnt(" #n ")" ::: "memory")
; #define PG8_WAIT_L(n) asm volatile("s_waitcnt lgkmcnt(" #n ")" ::: "memory")
; #define PG8_BAR __builtin_amdgcn_s_barrier()
; #define PG8_SCHED __builtin_amdgcn_sched_barrier(0)
; template <class Epi>
; DEV void gemm_phase(LAS unsigned char* lds, const Gemm g, const StaticOrder& S, const Epi& E) {
;     ...
;             PG8_WAIT_V(6); PG8_BAR; PG8_MMA(1, 1, At, B1); PG8_BAR;
;             PG8_LDB(B0, 1, 0); PG8_SCHED; PG8_LDA(At, 1, 0); PG8_STAGE(PG8_SA(0, 1), a2 + hstep, voffA);
;             PG8_WAIT_L(8); PG8_BAR; PG8_WAIT_L(0); PG8_MMA(0, 0, At, B0); PG8_BAR; PG8_SCHED;
;             PG8_LDB(B1, 1, 1); PG8_STAGE(PG8_SB(1, 0), b3, voffB);
;             PG8_BAR; PG8_WAIT_L(0); PG8_MMA(0, 1, At, B1); PG8_BAR;
;             PG8_LDA(At, 1, 1); PG8_STAGE(PG8_SA(1, 0), a3, voffA);
	v_mfma_f32_16x16x32_bf16 v[48:51], v[218:221], v[154:157], v[48:51]
	v_mfma_f32_16x16x32_bf16 v[40:43], v[226:229], v[154:157], v[40:43]
	v_mfma_f32_16x16x32_bf16 v[32:35], v[218:221], v[178:181], v[32:35]
	v_mfma_f32_16x16x32_bf16 v[24:27], v[226:229], v[178:181], v[24:27]
	v_mfma_f32_16x16x32_bf16 v[16:19], v[218:221], v[186:189], v[16:19]
	v_mfma_f32_16x16x32_bf16 v[8:11], v[226:229], v[186:189], v[8:11]
	v_mfma_f32_16x16x32_bf16 v[4:7], v[218:221], v[194:197], v[4:7]
	v_mfma_f32_16x16x32_bf16 v[0:3], v[226:229], v[194:197], v[0:3]
	v_mfma_f32_16x16x32_bf16 v[48:51], v[222:225], v[174:177], v[48:51]
	v_mfma_f32_16x16x32_bf16 v[40:43], v[230:233], v[174:177], v[40:43]
	v_mfma_f32_16x16x32_bf16 v[32:35], v[222:225], v[182:185], v[32:35]
	v_mfma_f32_16x16x32_bf16 v[24:27], v[230:233], v[182:185], v[24:27]
	v_mfma_f32_16x16x32_bf16 v[16:19], v[222:225], v[190:193], v[16:19]
	v_mfma_f32_16x16x32_bf16 v[8:11], v[230:233], v[190:193], v[8:11]
	v_mfma_f32_16x16x32_bf16 v[4:7], v[222:225], v[214:217], v[4:7]
	v_mfma_f32_16x16x32_bf16 v[0:3], v[230:233], v[214:217], v[0:3]
	s_barrier
	s_add_i32 s56, 0, 0x18000
	v_add_u32_e32 v150, s56, v135
	ds_read_b128 v[138:141], v150
	ds_read_b128 v[142:145], v150 offset:1024
	ds_read_b128 v[146:149], v150 offset:2048
	ds_read_b128 v[150:153], v150 offset:3072
	s_add_u32 s28, s28, 0x80000
	s_addc_u32 s29, s29, 0
	s_mov_b32 m0, s44
	ds_read_b128 v[154:157], v137 offset:32768
	ds_read_b128 v[174:177], v137 offset:33792
	ds_read_b128 v[178:181], v137 offset:34816
	ds_read_b128 v[182:185], v137 offset:35840
	ds_read_b128 v[186:189], v137 offset:36864
	ds_read_b128 v[190:193], v137 offset:37888
	ds_read_b128 v[194:197], v137 offset:38912
	ds_read_b128 v[214:217], v137 offset:39936
	global_load_lds_dwordx4 v160, s[28:29]
	s_mov_b32 m0, s45
	s_nop 0
	global_load_lds_dwordx4 v128, s[28:29]
	s_waitcnt lgkmcnt(8)
	s_barrier
	s_waitcnt lgkmcnt(0)
	v_mfma_f32_16x16x32_bf16 v[124:127], v[138:141], v[154:157], v[124:127]
	v_mfma_f32_16x16x32_bf16 v[120:123], v[146:149], v[154:157], v[120:123]
	v_mfma_f32_16x16x32_bf16 v[116:119], v[138:141], v[178:181], v[116:119]
	v_mfma_f32_16x16x32_bf16 v[108:111], v[146:149], v[178:181], v[108:111]
	v_mfma_f32_16x16x32_bf16 v[100:103], v[138:141], v[186:189], v[100:103]
	v_mfma_f32_16x16x32_bf16 v[92:95], v[146:149], v[186:189], v[92:95]
	v_mfma_f32_16x16x32_bf16 v[84:87], v[138:141], v[194:197], v[84:87]
	v_mfma_f32_16x16x32_bf16 v[76:79], v[146:149], v[194:197], v[76:79]
	v_mfma_f32_16x16x32_bf16 v[124:127], v[142:145], v[174:177], v[124:127]
	v_mfma_f32_16x16x32_bf16 v[120:123], v[150:153], v[174:177], v[120:123]
	v_mfma_f32_16x16x32_bf16 v[116:119], v[142:145], v[182:185], v[116:119]
	v_mfma_f32_16x16x32_bf16 v[108:111], v[150:153], v[182:185], v[108:111]
	v_mfma_f32_16x16x32_bf16 v[100:103], v[142:145], v[190:193], v[100:103]
	v_mfma_f32_16x16x32_bf16 v[92:95], v[150:153], v[190:193], v[92:95]
	v_mfma_f32_16x16x32_bf16 v[84:87], v[142:145], v[214:217], v[84:87]
	v_mfma_f32_16x16x32_bf16 v[76:79], v[150:153], v[214:217], v[76:79]
	s_barrier
	s_add_i32 s28, 0, 0x1c000
	s_add_i32 s29, s56, s41
	v_add_u32_e32 v167, s28, v135
	v_lshl_add_u64 v[158:159], v[158:159], 0, s[2:3]
	s_mov_b32 m0, s29
	ds_read_b128 v[218:221], v167
	ds_read_b128 v[222:225], v167 offset:1024
	ds_read_b128 v[226:229], v167 offset:2048
	ds_read_b128 v[230:233], v167 offset:3072
	global_load_lds_dwordx4 v[158:159], off
	v_lshl_add_u64 v[158:159], v[234:235], 0, s[2:3]
	s_add_i32 m0, s29, 0x2000
	s_nop 0
	global_load_lds_dwordx4 v[158:159], off
	s_barrier
	s_waitcnt lgkmcnt(0)
	v_mfma_f32_16x16x32_bf16 v[112:115], v[218:221], v[154:157], v[112:115]
	v_mfma_f32_16x16x32_bf16 v[104:107], v[226:229], v[154:157], v[104:107]
	v_mfma_f32_16x16x32_bf16 v[96:99], v[218:221], v[178:181], v[96:99]
	v_mfma_f32_16x16x32_bf16 v[88:91], v[226:229], v[178:181], v[88:91]
	v_mfma_f32_16x16x32_bf16 v[80:83], v[218:221], v[186:189], v[80:83]
	v_mfma_f32_16x16x32_bf16 v[72:75], v[226:229], v[186:189], v[72:75]
	v_mfma_f32_16x16x32_bf16 v[68:71], v[218:221], v[194:197], v[68:71]
	v_mfma_f32_16x16x32_bf16 v[64:67], v[226:229], v[194:197], v[64:67]
	v_mfma_f32_16x16x32_bf16 v[112:115], v[222:225], v[174:177], v[112:115]
	v_mfma_f32_16x16x32_bf16 v[104:107], v[230:233], v[174:177], v[104:107]
	v_mfma_f32_16x16x32_bf16 v[96:99], v[222:225], v[182:185], v[96:99]
	v_mfma_f32_16x16x32_bf16 v[88:91], v[230:233], v[182:185], v[88:91]
	v_mfma_f32_16x16x32_bf16 v[80:83], v[222:225], v[190:193], v[80:83]
	v_mfma_f32_16x16x32_bf16 v[72:75], v[230:233], v[190:193], v[72:75]
	v_mfma_f32_16x16x32_bf16 v[68:71], v[222:225], v[214:217], v[68:71]
	v_mfma_f32_16x16x32_bf16 v[64:67], v[230:233], v[214:217], v[64:67]
	s_barrier
	s_mov_b32 m0, s46
	v_lshl_add_u64 v[158:159], v[236:237], 0, s[2:3]
	ds_read_b128 v[154:157], v137 offset:49152
	ds_read_b128 v[174:177], v137 offset:50176
	ds_read_b128 v[178:181], v137 offset:51200
	ds_read_b128 v[182:185], v137 offset:52224
	ds_read_b128 v[186:189], v137 offset:53248
	ds_read_b128 v[190:193], v137 offset:54272
	ds_read_b128 v[194:197], v137 offset:55296
	ds_read_b128 v[214:217], v137 offset:56320
	global_load_lds_dwordx4 v[158:159], off
	v_lshl_add_u64 v[158:159], v[238:239], 0, s[2:3]
	s_mov_b32 m0, s47
	s_nop 0
	global_load_lds_dwordx4 v[158:159], off
	s_barrier
; #define PG8_STAGE(bufoff, gbase, voff) do { _Pragma("unroll") for (int _i = 0; _i < 2; ++_i) \
;         __builtin_amdgcn_global_load_lds((const unsigned*)((const char*)(gbase) + (voff)[_i]), (LAS unsigned*)(lds + (bufoff) + ldsw + _i * 8192), 16, 0, 0); } while (0)
; #define PG8_MMA(ai, bj, At, Bt) do { __builtin_amdgcn_s_setprio(1); _Pragma("unroll") for (int m = 0; m < 4; ++m) _Pragma("unroll") for (int n = 0; n < 2; ++n) _Pragma("unroll") for (int k = 0; k < 2; ++k) \
;         acc[ai][bj][m][n] = __builtin_amdgcn_mfma_f32_16x16x32_bf16(Bt[n][k], At[m][k], acc[ai][bj][m][n], 0, 0, 0); __builtin_amdgcn_s_setprio(0); } while (0)
; #define PG8_WAIT_V(n) asm volatile("s_waitcnt vmcnt(" #n ")" ::: "memory")
; #define PG8_WAIT_L(n) asm volatile("s_waitcnt lgkmcnt(" #n ")" ::: "memory")
; #define PG8_BAR __builtin_amdgcn_s_barrier()
; #define PG8_SCHED __builtin_amdgcn_sched_barrier(0)
; template <class Epi>
; DEV void gemm_phase(LAS unsigned char* lds, const Gemm g, const StaticOrder& S, const Epi& E) {
;     ...
;             PG8_BAR; PG8_WAIT_L(0); PG8_MMA(1, 0, At, B0); PG8_BAR; PG8_SCHED;
;             PG8_STAGE(PG8_SB(1, 1), b3 + hstep, voffB);
;             PG8_WAIT_V(6); PG8_BAR; PG8_MMA(1, 1, At, B1); PG8_BAR;
;         }
	s_waitcnt lgkmcnt(0)
	v_mfma_f32_16x16x32_bf16 v[60:63], v[138:141], v[154:157], v[60:63]
	v_mfma_f32_16x16x32_bf16 v[56:59], v[146:149], v[154:157], v[56:59]
	v_mfma_f32_16x16x32_bf16 v[52:55], v[138:141], v[178:181], v[52:55]
	v_mfma_f32_16x16x32_bf16 v[44:47], v[146:149], v[178:181], v[44:47]
	v_mfma_f32_16x16x32_bf16 v[36:39], v[138:141], v[186:189], v[36:39]
	v_mfma_f32_16x16x32_bf16 v[28:31], v[146:149], v[186:189], v[28:31]
	v_mfma_f32_16x16x32_bf16 v[20:23], v[138:141], v[194:197], v[20:23]
	v_mfma_f32_16x16x32_bf16 v[12:15], v[146:149], v[194:197], v[12:15]
	v_mfma_f32_16x16x32_bf16 v[60:63], v[142:145], v[174:177], v[60:63]
	v_mfma_f32_16x16x32_bf16 v[56:59], v[150:153], v[174:177], v[56:59]
	v_mfma_f32_16x16x32_bf16 v[52:55], v[142:145], v[182:185], v[52:55]
	v_mfma_f32_16x16x32_bf16 v[44:47], v[150:153], v[182:185], v[44:47]
	v_mfma_f32_16x16x32_bf16 v[36:39], v[142:145], v[190:193], v[36:39]
	v_mfma_f32_16x16x32_bf16 v[28:31], v[150:153], v[190:193], v[28:31]
	v_mfma_f32_16x16x32_bf16 v[20:23], v[142:145], v[214:217], v[20:23]
	v_mfma_f32_16x16x32_bf16 v[12:15], v[150:153], v[214:217], v[12:15]
	s_barrier
	s_add_u32 s26, s26, 0x80080
	s_addc_u32 s27, s27, 0
	s_add_i32 s28, s28, s41
	s_mov_b32 m0, s28
	s_nop 0
	global_load_lds_dwordx4 v160, s[26:27]
	s_add_i32 m0, s28, 0x2000
	s_nop 0
	global_load_lds_dwordx4 v128, s[26:27]
	s_waitcnt vmcnt(6)
	s_barrier
	v_mfma_f32_16x16x32_bf16 v[48:51], v[218:221], v[154:157], v[48:51]
	v_mfma_f32_16x16x32_bf16 v[40:43], v[226:229], v[154:157], v[40:43]
	v_mfma_f32_16x16x32_bf16 v[32:35], v[218:221], v[178:181], v[32:35]
	v_mfma_f32_16x16x32_bf16 v[24:27], v[226:229], v[178:181], v[24:27]
	v_mfma_f32_16x16x32_bf16 v[16:19], v[218:221], v[186:189], v[16:19]
	v_mfma_f32_16x16x32_bf16 v[8:11], v[226:229], v[186:189], v[8:11]
	v_mfma_f32_16x16x32_bf16 v[4:7], v[218:221], v[194:197], v[4:7]
	v_mfma_f32_16x16x32_bf16 v[0:3], v[226:229], v[194:197], v[0:3]
	v_mfma_f32_16x16x32_bf16 v[48:51], v[222:225], v[174:177], v[48:51]
	v_mfma_f32_16x16x32_bf16 v[40:43], v[230:233], v[174:177], v[40:43]
	v_mfma_f32_16x16x32_bf16 v[32:35], v[222:225], v[182:185], v[32:35]
	v_mfma_f32_16x16x32_bf16 v[24:27], v[230:233], v[182:185], v[24:27]
	v_mfma_f32_16x16x32_bf16 v[16:19], v[222:225], v[190:193], v[16:19]
	v_mfma_f32_16x16x32_bf16 v[8:11], v[230:233], v[190:193], v[8:11]
	v_mfma_f32_16x16x32_bf16 v[4:7], v[222:225], v[214:217], v[4:7]
	v_mfma_f32_16x16x32_bf16 v[0:3], v[230:233], v[214:217], v[0:3]
	s_add_i32 s55, s55, 2
	s_add_u32 s24, s24, 0x100
	s_addc_u32 s25, s25, 0
	s_add_u32 s53, s53, 0x100
	s_addc_u32 s54, s54, 0
	s_cmp_gt_u32 s55, 29
	s_barrier
	s_cbranch_scc0 .LBB0_362
; DEV bf16x8 pack8(f32x4 a, f32x4 b) { u32x4 w; w.x = cvt_pk_bf16(a[0], a[1]); w.y = cvt_pk_bf16(a[2], a[3]); w.z = cvt_pk_bf16(b[0], b[1]); w.w = cvt_pk_bf16(b[2], b[3]); return __builtin_bit_cast(bf16x8, w); }
; DEV u32x2 pack4(f32x4 a) { u32x2 w; w.x = cvt_pk_bf16(a[0], a[1]); w.y = cvt_pk_bf16(a[2], a[3]); return w; }
; DEV f32x4 gelu4(f32x4 v) { f32x2 a = gelu_pk((f32x2){v[0], v[1]}), b = gelu_pk((f32x2){v[2], v[3]}); return (f32x4){a.x, a.y, b.x, b.y}; }
; template <int ACT, bool PERM>
; DEV void store_bf16_tile(AccRef acc, u16* O, int ld, int row0, int col0, const float* ss) {
;     ...
; #pragma unroll
;     for (int ai = 0; ai < 2; ++ai)
; #pragma unroll
;         for (int m = 0; m < 4; ++m) { u16* rowp = O + (size_t)(row0 + ai * 128 + m * 16) * ld + col0; const float rs = rsv[ai][m];
; #pragma unroll
;             for (int bj = 0; bj < 2; ++bj) { f32x4 v0 = acc[ai][bj][m][0] * rs, v1 = acc[ai][bj][m][1] * rs; if (ACT == 1) { v0 = gelu4(v0); v1 = gelu4(v1); }
;                 if (PERM) *(u32x4*)(rowp + bj * 128) = __builtin_bit_cast(u32x4, pack8(v0, v1));
;                 else { *(u32x2*)(rowp + bj * 128) = pack4(v0); *(u32x2*)(rowp + bj * 128 + 16) = pack4(v1); } } }
	v_lshl_add_u32 v138, s12, 8, v134
	v_lshl_or_b32 v140, s50, 8, v136
	v_ashrrev_i32_e32 v141, 31, v140
	v_ashrrev_i32_e32 v139, 31, v138
	v_lshl_add_u64 v[140:141], v[140:141], 1, s[10:11]
	v_lshlrev_b64 v[142:143], 11, v[138:139]
	v_lshl_add_u64 v[142:143], v[140:141], 0, v[142:143]
	v_cvt_pk_bf16_f32 v104, v104, v105
	v_cvt_pk_bf16_f32 v105, v106, v107
	global_store_dwordx2 v[142:143], v[104:105], off offset:288
	v_or_b32_e32 v104, 16, v138
	v_ashrrev_i32_e32 v105, 31, v104
	v_lshlrev_b64 v[104:105], 11, v[104:105]
	v_lshl_add_u64 v[104:105], v[140:141], 0, v[104:105]
	v_cvt_pk_bf16_f32 v88, v88, v89
	v_cvt_pk_bf16_f32 v89, v90, v91
	global_store_dwordx2 v[104:105], v[88:89], off offset:288
	v_or_b32_e32 v88, 32, v138
	v_ashrrev_i32_e32 v89, 31, v88
	v_lshlrev_b64 v[88:89], 11, v[88:89]
	v_lshl_add_u64 v[88:89], v[140:141], 0, v[88:89]
	v_cvt_pk_bf16_f32 v72, v72, v73
	v_cvt_pk_bf16_f32 v73, v74, v75
	global_store_dwordx2 v[88:89], v[72:73], off offset:288
	v_or_b32_e32 v72, 48, v138
	v_ashrrev_i32_e32 v73, 31, v72
	v_lshlrev_b64 v[72:73], 11, v[72:73]
	s_mov_b32 s12, 0x40000
	v_lshl_add_u64 v[72:73], v[140:141], 0, v[72:73]
	v_cvt_pk_bf16_f32 v64, v64, v65
	v_cvt_pk_bf16_f32 v65, v66, v67
	s_mov_b64 s[24:25], 0x40000
	v_cvt_pk_bf16_f32 v60, v60, v61
	v_cvt_pk_bf16_f32 v61, v62, v63
	v_add_co_u32_e32 v62, vcc, s12, v142
	global_store_dwordx2 v[72:73], v[64:65], off offset:288
	v_lshl_add_u64 v[64:65], v[142:143], 0, s[24:25]
	v_addc_co_u32_e32 v63, vcc, 0, v143, vcc
	v_cvt_pk_bf16_f32 v48, v48, v49
	v_cvt_pk_bf16_f32 v49, v50, v51
	s_mov_b32 s12, 0x48000
	global_store_dwordx2 v[64:65], v[48:49], off offset:256
	v_cvt_pk_bf16_f32 v40, v40, v41
	v_cvt_pk_bf16_f32 v41, v42, v43
	s_mov_b64 s[24:25], 0x48000
	v_add_co_u32_e32 v48, vcc, s12, v142
	global_store_dwordx2 v[64:65], v[40:41], off offset:288
	v_lshl_add_u64 v[40:41], v[142:143], 0, s[24:25]
	v_addc_co_u32_e32 v49, vcc, 0, v143, vcc
	v_cvt_pk_bf16_f32 v32, v32, v33
	v_cvt_pk_bf16_f32 v33, v34, v35
	s_mov_b32 s12, 0x50000
	global_store_dwordx2 v[40:41], v[32:33], off offset:256
	v_cvt_pk_bf16_f32 v24, v24, v25
	v_cvt_pk_bf16_f32 v25, v26, v27
	s_mov_b64 s[24:25], 0x50000
	v_add_co_u32_e32 v32, vcc, s12, v142
	global_store_dwordx2 v[40:41], v[24:25], off offset:288
	v_lshl_add_u64 v[24:25], v[142:143], 0, s[24:25]
	v_addc_co_u32_e32 v33, vcc, 0, v143, vcc
	v_cvt_pk_bf16_f32 v16, v16, v17
	v_cvt_pk_bf16_f32 v17, v18, v19
	global_store_dwordx2 v[24:25], v[16:17], off offset:256
	v_add_co_u32_e32 v16, vcc, s59, v142
	v_cvt_pk_bf16_f32 v106, v116, v117
	v_cvt_pk_bf16_f32 v107, v118, v119
	v_cvt_pk_bf16_f32 v90, v100, v101
	v_cvt_pk_bf16_f32 v91, v102, v103
	v_cvt_pk_bf16_f32 v74, v84, v85
	v_cvt_pk_bf16_f32 v75, v86, v87
	v_cvt_pk_bf16_f32 v42, v52, v53
	v_cvt_pk_bf16_f32 v43, v54, v55
	v_cvt_pk_bf16_f32 v26, v36, v37
	v_cvt_pk_bf16_f32 v27, v38, v39
	v_cvt_pk_bf16_f32 v8, v8, v9
	v_cvt_pk_bf16_f32 v9, v10, v11
	s_mov_b64 s[24:25], 0x58000
	v_cvt_pk_bf16_f32 v10, v20, v21
	v_cvt_pk_bf16_f32 v11, v22, v23
	v_addc_co_u32_e32 v17, vcc, 0, v143, vcc
	v_cvt_pk_bf16_f32 v124, v124, v125
	v_cvt_pk_bf16_f32 v125, v126, v127
	v_cvt_pk_bf16_f32 v120, v120, v121
	v_cvt_pk_bf16_f32 v121, v122, v123
	v_cvt_pk_bf16_f32 v112, v112, v113
	v_cvt_pk_bf16_f32 v113, v114, v115
	global_store_dwordx2 v[104:105], v[106:107], off
	v_cvt_pk_bf16_f32 v106, v108, v109
	v_cvt_pk_bf16_f32 v107, v110, v111
	v_cvt_pk_bf16_f32 v96, v96, v97
	v_cvt_pk_bf16_f32 v97, v98, v99
	global_store_dwordx2 v[88:89], v[90:91], off
	v_cvt_pk_bf16_f32 v90, v92, v93
	v_cvt_pk_bf16_f32 v91, v94, v95
	v_cvt_pk_bf16_f32 v80, v80, v81
	v_cvt_pk_bf16_f32 v81, v82, v83
	global_store_dwordx2 v[72:73], v[74:75], off
	v_cvt_pk_bf16_f32 v74, v76, v77
	v_cvt_pk_bf16_f32 v75, v78, v79
	v_cvt_pk_bf16_f32 v68, v68, v69
	v_cvt_pk_bf16_f32 v69, v70, v71
	v_cvt_pk_bf16_f32 v56, v56, v57
	v_cvt_pk_bf16_f32 v57, v58, v59
	global_store_dwordx2 v[48:49], v[42:43], off
	v_cvt_pk_bf16_f32 v42, v44, v45
	v_cvt_pk_bf16_f32 v43, v46, v47
	global_store_dwordx2 v[32:33], v[26:27], off
	v_cvt_pk_bf16_f32 v26, v28, v29
	v_cvt_pk_bf16_f32 v27, v30, v31
	global_store_dwordx2 v[24:25], v[8:9], off offset:288
	v_lshl_add_u64 v[8:9], v[142:143], 0, s[24:25]
	global_store_dwordx2 v[16:17], v[10:11], off
	v_cvt_pk_bf16_f32 v10, v12, v13
	v_cvt_pk_bf16_f32 v11, v14, v15
	v_cvt_pk_bf16_f32 v4, v4, v5
	v_cvt_pk_bf16_f32 v5, v6, v7
	v_cvt_pk_bf16_f32 v0, v0, v1
	v_cvt_pk_bf16_f32 v1, v2, v3
	s_and_b64 vcc, exec, s[14:15]
	s_mov_b32 s50, s16
	s_mov_b32 s12, s18
	s_mov_b64 s[26:27], s[22:23]
	s_mov_b64 s[24:25], s[20:21]
	global_store_dwordx2 v[142:143], v[124:125], off
	global_store_dwordx2 v[142:143], v[120:121], off offset:32
	global_store_dwordx2 v[142:143], v[112:113], off offset:256
	global_store_dwordx2 v[104:105], v[106:107], off offset:32
	global_store_dwordx2 v[104:105], v[96:97], off offset:256
	global_store_dwordx2 v[88:89], v[90:91], off offset:32
	global_store_dwordx2 v[88:89], v[80:81], off offset:256
	global_store_dwordx2 v[72:73], v[74:75], off offset:32
	global_store_dwordx2 v[72:73], v[68:69], off offset:256
	global_store_dwordx2 v[62:63], v[60:61], off
	global_store_dwordx2 v[64:65], v[56:57], off offset:32
	global_store_dwordx2 v[40:41], v[42:43], off offset:32
	global_store_dwordx2 v[24:25], v[26:27], off offset:32
	global_store_dwordx2 v[8:9], v[10:11], off offset:32
	global_store_dwordx2 v[8:9], v[4:5], off offset:256
	global_store_dwordx2 v[8:9], v[0:1], off offset:288
	s_cbranch_vccz .LBB0_359
	s_waitcnt vmcnt(0)
	s_cmpk_gt_u32 s36, 0xff
	s_cbranch_scc1 .LBB0_353
	s_barrier
	s_branch .LBB0_353

; #define PG8_STAGE(bufoff, gbase, voff) do { _Pragma("unroll") for (int _i = 0; _i < 2; ++_i) \
;         __builtin_amdgcn_global_load_lds((const unsigned*)((const char*)(gbase) + (voff)[_i]), (LAS unsigned*)(lds + (bufoff) + ldsw + _i * 8192), 16, 0, 0); } while (0)
; #define PG8_LDA(dst, b, h) do { _Pragma("unroll") for (int m = 0; m < 4; ++m) _Pragma("unroll") for (int k = 0; k < 2; ++k) dst[m][k] = *(const LAS bf16x8*)(lds + PG8_SA(b, h) + aoff + m * 2048 + k * 1024); } while (0)
; #define PG8_LDB(dst, b, h) do { _Pragma("unroll") for (int n = 0; n < 2; ++n) _Pragma("unroll") for (int k = 0; k < 2; ++k) dst[n][k] = *(const LAS bf16x8*)(lds + PG8_SB(b, h) + boff + n * 2048 + k * 1024); } while (0)
; #define PG8_MMA(ai, bj, At, Bt) do { __builtin_amdgcn_s_setprio(1); _Pragma("unroll") for (int m = 0; m < 4; ++m) _Pragma("unroll") for (int n = 0; n < 2; ++n) _Pragma("unroll") for (int k = 0; k < 2; ++k) \
;         acc[ai][bj][m][n] = __builtin_amdgcn_mfma_f32_16x16x32_bf16(Bt[n][k], At[m][k], acc[ai][bj][m][n], 0, 0, 0); __builtin_amdgcn_s_setprio(0); } while (0)
; #define PG8_WAIT_V(n) asm volatile("s_waitcnt vmcnt(" #n ")" ::: "memory")
; #define PG8_WAIT_L(n) asm volatile("s_waitcnt lgkmcnt(" #n ")" ::: "memory")
; #define PG8_BAR __builtin_amdgcn_s_barrier()
; #define PG8_SCHED __builtin_amdgcn_sched_barrier(0)
; template <class Epi>
; DEV void gemm_phase(LAS unsigned char* lds, const Gemm g, const StaticOrder& S, const Epi& E) {
;     ...
;             PG8_LDB(B0, 0, 0); PG8_SCHED; PG8_LDA(At, 0, 0); PG8_STAGE(PG8_SA(1, 1), a1 + hstep, voffA);
;             PG8_WAIT_L(8); PG8_BAR; PG8_WAIT_L(0); PG8_MMA(0, 0, At, B0); PG8_BAR; PG8_SCHED;
;             PG8_LDB(B1, 0, 1); PG8_STAGE(PG8_SB(0, 0), b2, voffB);
;             PG8_BAR; PG8_WAIT_L(0); PG8_MMA(0, 1, At, B1); PG8_BAR;
;             PG8_LDA(At, 0, 1); PG8_STAGE(PG8_SA(0, 0), a2, voffA);
;             PG8_BAR; PG8_WAIT_L(0); PG8_MMA(1, 0, At, B0); PG8_BAR; PG8_SCHED;
;             PG8_STAGE(PG8_SB(0, 1), b2 + hstep, voffB);
;             PG8_WAIT_V(6); PG8_BAR; PG8_MMA(1, 1, At, B1); PG8_BAR;
.LBB0_404:
	s_add_u32 s28, s26, 0xfff00080
	s_addc_u32 s29, s27, -1
	s_add_i32 s49, 0, 0x10000
	v_add_u32_e32 v140, s49, v178
	ds_read_b128 v[128:131], v140
	ds_read_b128 v[132:135], v140 offset:1024
	ds_read_b128 v[136:139], v140 offset:2048
	ds_read_b128 v[140:143], v140 offset:3072
	s_cmp_eq_u32 s48, 60
	s_cselect_b32 s31, s15, s29
	s_cselect_b32 s30, s19, s28
	s_cselect_b32 s29, s17, s47
	s_cselect_b32 s28, s25, s46
	s_add_i32 m0, s37, 0xc000
	ds_read_b128 v[154:157], v181
	ds_read_b128 v[174:177], v181 offset:1024
	ds_read_b128 v[182:185], v181 offset:2048
	ds_read_b128 v[186:189], v181 offset:3072
	ds_read_b128 v[190:193], v181 offset:4096
	ds_read_b128 v[194:197], v181 offset:5120
	ds_read_b128 v[214:217], v181 offset:6144
	ds_read_b128 v[218:221], v181 offset:7168
	global_load_lds_dwordx4 v150, s[26:27]
	s_add_i32 m0, s37, 0xe000
	s_nop 0
	global_load_lds_dwordx4 v152, s[26:27]
	s_waitcnt lgkmcnt(8)
	s_barrier
	s_waitcnt lgkmcnt(0)
	v_mfma_f32_16x16x32_bf16 v[124:127], v[128:131], v[154:157], v[124:127]
	v_mfma_f32_16x16x32_bf16 v[120:123], v[136:139], v[154:157], v[120:123]
	v_mfma_f32_16x16x32_bf16 v[108:111], v[128:131], v[182:185], v[108:111]
	v_mfma_f32_16x16x32_bf16 v[104:107], v[136:139], v[182:185], v[104:107]
	v_mfma_f32_16x16x32_bf16 v[92:95], v[128:131], v[190:193], v[92:95]
	v_mfma_f32_16x16x32_bf16 v[88:91], v[136:139], v[190:193], v[88:91]
	v_mfma_f32_16x16x32_bf16 v[76:79], v[128:131], v[214:217], v[76:79]
	v_mfma_f32_16x16x32_bf16 v[72:75], v[136:139], v[214:217], v[72:75]
	v_mfma_f32_16x16x32_bf16 v[124:127], v[132:135], v[174:177], v[124:127]
	v_mfma_f32_16x16x32_bf16 v[120:123], v[140:143], v[174:177], v[120:123]
	v_mfma_f32_16x16x32_bf16 v[108:111], v[132:135], v[186:189], v[108:111]
	v_mfma_f32_16x16x32_bf16 v[104:107], v[140:143], v[186:189], v[104:107]
	v_mfma_f32_16x16x32_bf16 v[92:95], v[132:135], v[194:197], v[92:95]
	v_mfma_f32_16x16x32_bf16 v[88:91], v[140:143], v[194:197], v[88:91]
	v_mfma_f32_16x16x32_bf16 v[76:79], v[132:135], v[218:221], v[76:79]
	v_mfma_f32_16x16x32_bf16 v[72:75], v[140:143], v[218:221], v[72:75]
	s_barrier
	s_add_i32 s52, 0, 0x14000
	v_add_u32_e32 v158, s52, v178
	s_add_i32 s49, s49, s36
	ds_read_b128 v[222:225], v158
	ds_read_b128 v[226:229], v158 offset:1024
	ds_read_b128 v[230:233], v158 offset:2048
	ds_read_b128 v[234:237], v158 offset:3072
	v_lshl_add_u64 v[158:159], s[28:29], 0, v[160:161]
	s_mov_b32 m0, s49
	v_lshl_add_u64 v[238:239], s[28:29], 0, v[148:149]
	global_load_lds_dwordx4 v160, s[28:29]
	s_add_i32 m0, s49, 0x2000
	s_nop 0
	global_load_lds_dwordx4 v148, s[28:29]
	s_barrier
	s_waitcnt lgkmcnt(0)
	v_mfma_f32_16x16x32_bf16 v[116:119], v[222:225], v[154:157], v[116:119]
	v_mfma_f32_16x16x32_bf16 v[112:115], v[230:233], v[154:157], v[112:115]
	v_mfma_f32_16x16x32_bf16 v[100:103], v[222:225], v[182:185], v[100:103]
	v_mfma_f32_16x16x32_bf16 v[96:99], v[230:233], v[182:185], v[96:99]
	v_mfma_f32_16x16x32_bf16 v[84:87], v[222:225], v[190:193], v[84:87]
	v_mfma_f32_16x16x32_bf16 v[80:83], v[230:233], v[190:193], v[80:83]
	v_mfma_f32_16x16x32_bf16 v[68:71], v[222:225], v[214:217], v[68:71]
	v_mfma_f32_16x16x32_bf16 v[64:67], v[230:233], v[214:217], v[64:67]
	v_mfma_f32_16x16x32_bf16 v[116:119], v[226:229], v[174:177], v[116:119]
	v_mfma_f32_16x16x32_bf16 v[112:115], v[234:237], v[174:177], v[112:115]
	v_mfma_f32_16x16x32_bf16 v[100:103], v[226:229], v[186:189], v[100:103]
	v_mfma_f32_16x16x32_bf16 v[96:99], v[234:237], v[186:189], v[96:99]
	v_mfma_f32_16x16x32_bf16 v[84:87], v[226:229], v[194:197], v[84:87]
	v_mfma_f32_16x16x32_bf16 v[80:83], v[234:237], v[194:197], v[80:83]
	v_mfma_f32_16x16x32_bf16 v[68:71], v[226:229], v[218:221], v[68:71]
	v_mfma_f32_16x16x32_bf16 v[64:67], v[234:237], v[218:221], v[64:67]
	s_barrier
	s_mov_b32 m0, s37
	v_lshl_add_u64 v[240:241], s[30:31], 0, v[144:145]
	ds_read_b128 v[154:157], v181 offset:16384
	ds_read_b128 v[174:177], v181 offset:17408
	ds_read_b128 v[182:185], v181 offset:18432
	ds_read_b128 v[186:189], v181 offset:19456
	ds_read_b128 v[190:193], v181 offset:20480
	ds_read_b128 v[194:197], v181 offset:21504
	ds_read_b128 v[214:217], v181 offset:22528
	ds_read_b128 v[218:221], v181 offset:23552
	global_load_lds_dwordx4 v144, s[30:31]
	v_lshl_add_u64 v[242:243], s[30:31], 0, v[146:147]
	s_mov_b32 m0, s38
	s_nop 0
	global_load_lds_dwordx4 v146, s[30:31]
	s_barrier
	s_waitcnt lgkmcnt(0)
	v_mfma_f32_16x16x32_bf16 v[60:63], v[128:131], v[154:157], v[60:63]
	v_mfma_f32_16x16x32_bf16 v[56:59], v[136:139], v[154:157], v[56:59]
	v_mfma_f32_16x16x32_bf16 v[44:47], v[128:131], v[182:185], v[44:47]
	v_mfma_f32_16x16x32_bf16 v[40:43], v[136:139], v[182:185], v[40:43]
	v_mfma_f32_16x16x32_bf16 v[28:31], v[128:131], v[190:193], v[28:31]
	v_mfma_f32_16x16x32_bf16 v[24:27], v[136:139], v[190:193], v[24:27]
	v_mfma_f32_16x16x32_bf16 v[12:15], v[128:131], v[214:217], v[12:15]
	v_mfma_f32_16x16x32_bf16 v[8:11], v[136:139], v[214:217], v[8:11]
	v_mfma_f32_16x16x32_bf16 v[60:63], v[132:135], v[174:177], v[60:63]
	v_mfma_f32_16x16x32_bf16 v[56:59], v[140:143], v[174:177], v[56:59]
	v_mfma_f32_16x16x32_bf16 v[44:47], v[132:135], v[186:189], v[44:47]
	v_mfma_f32_16x16x32_bf16 v[40:43], v[140:143], v[186:189], v[40:43]
	v_mfma_f32_16x16x32_bf16 v[28:31], v[132:135], v[194:197], v[28:31]
	v_mfma_f32_16x16x32_bf16 v[24:27], v[140:143], v[194:197], v[24:27]
	v_mfma_f32_16x16x32_bf16 v[12:15], v[132:135], v[218:221], v[12:15]
	v_mfma_f32_16x16x32_bf16 v[8:11], v[140:143], v[218:221], v[8:11]
	s_barrier
	s_add_u32 s50, s28, 0x100000
	s_addc_u32 s51, s29, 0
	s_add_i32 s49, s52, s36
	s_mov_b32 m0, s49
	s_nop 0
	global_load_lds_dwordx4 v160, s[50:51]
	s_add_i32 m0, s49, 0x2000
	s_nop 0
	global_load_lds_dwordx4 v148, s[50:51]
	s_waitcnt vmcnt(6)
	s_barrier
; #define PG8_STAGE(bufoff, gbase, voff) do { _Pragma("unroll") for (int _i = 0; _i < 2; ++_i) \
;         __builtin_amdgcn_global_load_lds((const unsigned*)((const char*)(gbase) + (voff)[_i]), (LAS unsigned*)(lds + (bufoff) + ldsw + _i * 8192), 16, 0, 0); } while (0)
; #define PG8_LDA(dst, b, h) do { _Pragma("unroll") for (int m = 0; m < 4; ++m) _Pragma("unroll") for (int k = 0; k < 2; ++k) dst[m][k] = *(const LAS bf16x8*)(lds + PG8_SA(b, h) + aoff + m * 2048 + k * 1024); } while (0)
; #define PG8_LDB(dst, b, h) do { _Pragma("unroll") for (int n = 0; n < 2; ++n) _Pragma("unroll") for (int k = 0; k < 2; ++k) dst[n][k] = *(const LAS bf16x8*)(lds + PG8_SB(b, h) + boff + n * 2048 + k * 1024); } while (0)
; #define PG8_MMA(ai, bj, At, Bt) do { __builtin_amdgcn_s_setprio(1); _Pragma("unroll") for (int m = 0; m < 4; ++m) _Pragma("unroll") for (int n = 0; n < 2; ++n) _Pragma("unroll") for (int k = 0; k < 2; ++k) \
;         acc[ai][bj][m][n] = __builtin_amdgcn_mfma_f32_16x16x32_bf16(Bt[n][k], At[m][k], acc[ai][bj][m][n], 0, 0, 0); __builtin_amdgcn_s_setprio(0); } while (0)
; #define PG8_WAIT_V(n) asm volatile("s_waitcnt vmcnt(" #n ")" ::: "memory")
; #define PG8_WAIT_L(n) asm volatile("s_waitcnt lgkmcnt(" #n ")" ::: "memory")
; #define PG8_BAR __builtin_amdgcn_s_barrier()
; #define PG8_SCHED __builtin_amdgcn_sched_barrier(0)
; template <class Epi>
; DEV void gemm_phase(LAS unsigned char* lds, const Gemm g, const StaticOrder& S, const Epi& E) {
;     ...
;             PG8_WAIT_V(6); PG8_BAR; PG8_MMA(1, 1, At, B1); PG8_BAR;
;             PG8_LDB(B0, 1, 0); PG8_SCHED; PG8_LDA(At, 1, 0); PG8_STAGE(PG8_SA(0, 1), a2 + hstep, voffA);
;             PG8_WAIT_L(8); PG8_BAR; PG8_WAIT_L(0); PG8_MMA(0, 0, At, B0); PG8_BAR; PG8_SCHED;
;             PG8_LDB(B1, 1, 1); PG8_STAGE(PG8_SB(1, 0), b3, voffB);
;             PG8_BAR; PG8_WAIT_L(0); PG8_MMA(0, 1, At, B1); PG8_BAR;
;             PG8_LDA(At, 1, 1); PG8_STAGE(PG8_SA(1, 0), a3, voffA);
	v_mfma_f32_16x16x32_bf16 v[52:55], v[222:225], v[154:157], v[52:55]
	v_mfma_f32_16x16x32_bf16 v[48:51], v[230:233], v[154:157], v[48:51]
	v_mfma_f32_16x16x32_bf16 v[36:39], v[222:225], v[182:185], v[36:39]
	v_mfma_f32_16x16x32_bf16 v[32:35], v[230:233], v[182:185], v[32:35]
	v_mfma_f32_16x16x32_bf16 v[20:23], v[222:225], v[190:193], v[20:23]
	v_mfma_f32_16x16x32_bf16 v[16:19], v[230:233], v[190:193], v[16:19]
	v_mfma_f32_16x16x32_bf16 v[4:7], v[222:225], v[214:217], v[4:7]
	v_mfma_f32_16x16x32_bf16 v[0:3], v[230:233], v[214:217], v[0:3]
	v_mfma_f32_16x16x32_bf16 v[52:55], v[226:229], v[174:177], v[52:55]
	v_mfma_f32_16x16x32_bf16 v[48:51], v[234:237], v[174:177], v[48:51]
	v_mfma_f32_16x16x32_bf16 v[36:39], v[226:229], v[186:189], v[36:39]
	v_mfma_f32_16x16x32_bf16 v[32:35], v[234:237], v[186:189], v[32:35]
	v_mfma_f32_16x16x32_bf16 v[20:23], v[226:229], v[194:197], v[20:23]
	v_mfma_f32_16x16x32_bf16 v[16:19], v[234:237], v[194:197], v[16:19]
	v_mfma_f32_16x16x32_bf16 v[4:7], v[226:229], v[218:221], v[4:7]
	v_mfma_f32_16x16x32_bf16 v[0:3], v[234:237], v[218:221], v[0:3]
	s_barrier
	s_add_i32 s49, 0, 0x18000
	v_add_u32_e32 v140, s49, v178
	ds_read_b128 v[128:131], v140
	ds_read_b128 v[132:135], v140 offset:1024
	ds_read_b128 v[136:139], v140 offset:2048
	ds_read_b128 v[140:143], v140 offset:3072
	s_add_u32 s30, s30, 0x100000
	s_addc_u32 s31, s31, 0
	s_mov_b32 m0, s39
	ds_read_b128 v[154:157], v181 offset:32768
	ds_read_b128 v[174:177], v181 offset:33792
	ds_read_b128 v[182:185], v181 offset:34816
	ds_read_b128 v[186:189], v181 offset:35840
	ds_read_b128 v[190:193], v181 offset:36864
	ds_read_b128 v[194:197], v181 offset:37888
	ds_read_b128 v[214:217], v181 offset:38912
	ds_read_b128 v[218:221], v181 offset:39936
	global_load_lds_dwordx4 v144, s[30:31]
	s_mov_b32 m0, s40
	s_nop 0
	global_load_lds_dwordx4 v146, s[30:31]
	s_waitcnt lgkmcnt(8)
	s_barrier
	s_waitcnt lgkmcnt(0)
	v_mfma_f32_16x16x32_bf16 v[124:127], v[128:131], v[154:157], v[124:127]
	v_mfma_f32_16x16x32_bf16 v[120:123], v[136:139], v[154:157], v[120:123]
	v_mfma_f32_16x16x32_bf16 v[108:111], v[128:131], v[182:185], v[108:111]
	v_mfma_f32_16x16x32_bf16 v[104:107], v[136:139], v[182:185], v[104:107]
	v_mfma_f32_16x16x32_bf16 v[92:95], v[128:131], v[190:193], v[92:95]
	v_mfma_f32_16x16x32_bf16 v[88:91], v[136:139], v[190:193], v[88:91]
	v_mfma_f32_16x16x32_bf16 v[76:79], v[128:131], v[214:217], v[76:79]
	v_mfma_f32_16x16x32_bf16 v[72:75], v[136:139], v[214:217], v[72:75]
	v_mfma_f32_16x16x32_bf16 v[124:127], v[132:135], v[174:177], v[124:127]
	v_mfma_f32_16x16x32_bf16 v[120:123], v[140:143], v[174:177], v[120:123]
	v_mfma_f32_16x16x32_bf16 v[108:111], v[132:135], v[186:189], v[108:111]
	v_mfma_f32_16x16x32_bf16 v[104:107], v[140:143], v[186:189], v[104:107]
	v_mfma_f32_16x16x32_bf16 v[92:95], v[132:135], v[194:197], v[92:95]
	v_mfma_f32_16x16x32_bf16 v[88:91], v[140:143], v[194:197], v[88:91]
	v_mfma_f32_16x16x32_bf16 v[76:79], v[132:135], v[218:221], v[76:79]
	v_mfma_f32_16x16x32_bf16 v[72:75], v[140:143], v[218:221], v[72:75]
	s_barrier
	s_add_i32 s30, 0, 0x1c000
	s_add_i32 s31, s49, s36
	v_add_u32_e32 v234, s30, v178
	v_lshl_add_u64 v[158:159], v[158:159], 0, s[2:3]
	s_mov_b32 m0, s31
	ds_read_b128 v[222:225], v234
	ds_read_b128 v[226:229], v234 offset:1024
	ds_read_b128 v[230:233], v234 offset:2048
	ds_read_b128 v[234:237], v234 offset:3072
	global_load_lds_dwordx4 v[158:159], off
	v_lshl_add_u64 v[158:159], v[238:239], 0, s[2:3]
	s_add_i32 m0, s31, 0x2000
	s_nop 0
	global_load_lds_dwordx4 v[158:159], off
	s_barrier
	s_waitcnt lgkmcnt(0)
	v_mfma_f32_16x16x32_bf16 v[116:119], v[222:225], v[154:157], v[116:119]
	v_mfma_f32_16x16x32_bf16 v[112:115], v[230:233], v[154:157], v[112:115]
	v_mfma_f32_16x16x32_bf16 v[100:103], v[222:225], v[182:185], v[100:103]
	v_mfma_f32_16x16x32_bf16 v[96:99], v[230:233], v[182:185], v[96:99]
	v_mfma_f32_16x16x32_bf16 v[84:87], v[222:225], v[190:193], v[84:87]
	v_mfma_f32_16x16x32_bf16 v[80:83], v[230:233], v[190:193], v[80:83]
	v_mfma_f32_16x16x32_bf16 v[68:71], v[222:225], v[214:217], v[68:71]
	v_mfma_f32_16x16x32_bf16 v[64:67], v[230:233], v[214:217], v[64:67]
	v_mfma_f32_16x16x32_bf16 v[116:119], v[226:229], v[174:177], v[116:119]
	v_mfma_f32_16x16x32_bf16 v[112:115], v[234:237], v[174:177], v[112:115]
	v_mfma_f32_16x16x32_bf16 v[100:103], v[226:229], v[186:189], v[100:103]
	v_mfma_f32_16x16x32_bf16 v[96:99], v[234:237], v[186:189], v[96:99]
	v_mfma_f32_16x16x32_bf16 v[84:87], v[226:229], v[194:197], v[84:87]
	v_mfma_f32_16x16x32_bf16 v[80:83], v[234:237], v[194:197], v[80:83]
	v_mfma_f32_16x16x32_bf16 v[68:71], v[226:229], v[218:221], v[68:71]
	v_mfma_f32_16x16x32_bf16 v[64:67], v[234:237], v[218:221], v[64:67]
	s_barrier
	s_mov_b32 m0, s41
	v_lshl_add_u64 v[158:159], v[240:241], 0, s[2:3]
	ds_read_b128 v[154:157], v181 offset:49152
	ds_read_b128 v[174:177], v181 offset:50176
	ds_read_b128 v[182:185], v181 offset:51200
	ds_read_b128 v[186:189], v181 offset:52224
	ds_read_b128 v[190:193], v181 offset:53248
	ds_read_b128 v[194:197], v181 offset:54272
	ds_read_b128 v[214:217], v181 offset:55296
	ds_read_b128 v[218:221], v181 offset:56320
	global_load_lds_dwordx4 v[158:159], off
	v_lshl_add_u64 v[158:159], v[242:243], 0, s[2:3]
	s_mov_b32 m0, s42
	s_nop 0
	global_load_lds_dwordx4 v[158:159], off
	s_barrier
; DEV bf16x8 pack8(f32x4 a, f32x4 b) { u32x4 w; w.x = cvt_pk_bf16(a[0], a[1]); w.y = cvt_pk_bf16(a[2], a[3]); w.z = cvt_pk_bf16(b[0], b[1]); w.w = cvt_pk_bf16(b[2], b[3]); return __builtin_bit_cast(bf16x8, w); }
; #define PG8_WAIT_V(n) asm volatile("s_waitcnt vmcnt(" #n ")" ::: "memory")
; #define PG8_WAIT_L(n) asm volatile("s_waitcnt lgkmcnt(" #n ")" ::: "memory")
; #define PG8_BAR __builtin_amdgcn_s_barrier()
; template <class Epi>
; DEV void gemm_phase(LAS unsigned char* lds, const Gemm g, const StaticOrder& S, const Epi& E) {
;     ...
;             PG8_BAR; PG8_WAIT_L(0); PG8_MMA(1, 0, At, B0); PG8_BAR; PG8_SCHED;
;             PG8_STAGE(PG8_SB(1, 1), b3 + hstep, voffB);
;             PG8_WAIT_V(6); PG8_BAR; PG8_MMA(1, 1, At, B1); PG8_BAR;
;         }
;     DEV void operator()(AccRef acc, const pg8::Unit& u, int wr, int wc, int fr, int fq) const {
;         const int row0 = u.pm * 256 + wr * 64 + fr, col0 = u.pn * 256 + wc * 32 + 8 * fq;
; #pragma unroll
;         for (int am = 0; am < 4; ++am) { const int ai = am >> 1, m0 = (am & 1) * 2;
;             f32x4 bv[4][2][2];
; #pragma unroll
;             for (int m = m0; m < m0 + 2; ++m)
; #pragma unroll
;                 for (int bj = 0; bj < 2; ++bj)
; #pragma unroll
;                     for (int n = 0; n < 2; ++n) bv[m][bj][n] = *(const f32x4*)(base + (size_t)(row0 + ai * 128 + m * 16) * 2048 + col0 + bj * 128 + n * 4);
; #pragma unroll
;             for (int m = m0; m < m0 + 2; ++m) { const size_t off = (size_t)(row0 + ai * 128 + m * 16) * 2048 + col0; float sq = 0.f;
; #pragma unroll
;                 for (int bj = 0; bj < 2; ++bj) { const f32x4 o0 = bv[m][bj][0] + scale * acc[ai][bj][m][0], o1 = bv[m][bj][1] + scale * acc[ai][bj][m][1];
;                     *(f32x4*)(out + off + bj * 128) = o0; *(f32x4*)(out + off + bj * 128 + 4) = o1;
;                     if (xb) { *(u32x4*)(xb + off + bj * 128) = __builtin_bit_cast(u32x4, pack8(o0, o1));
;                         sq += (o0[0] * o0[0] + o0[1] * o0[1] + o0[2] * o0[2] + o0[3] * o0[3]) + (o1[0] * o1[0] + o1[1] * o1[1] + o1[2] * o1[2] + o1[3] * o1[3]); } }
;                 if (ssout) { sq += __shfl_xor(sq, 16); sq += __shfl_xor(sq, 32);
;                     if (fq == 0) { if (red) red[(ai * 128 + wr * 64 + m * 16 + fr) * 4 + wc] = sq; else atomicAdd(ssout + (size_t)(row0 + ai * 128 + m * 16) * 8 + u.pn, sq); } } }
	s_waitcnt lgkmcnt(0)
	v_mfma_f32_16x16x32_bf16 v[60:63], v[128:131], v[154:157], v[60:63]
	v_mfma_f32_16x16x32_bf16 v[56:59], v[136:139], v[154:157], v[56:59]
	v_mfma_f32_16x16x32_bf16 v[44:47], v[128:131], v[182:185], v[44:47]
	v_mfma_f32_16x16x32_bf16 v[40:43], v[136:139], v[182:185], v[40:43]
	v_mfma_f32_16x16x32_bf16 v[28:31], v[128:131], v[190:193], v[28:31]
	v_mfma_f32_16x16x32_bf16 v[24:27], v[136:139], v[190:193], v[24:27]
	v_mfma_f32_16x16x32_bf16 v[12:15], v[128:131], v[214:217], v[12:15]
	v_mfma_f32_16x16x32_bf16 v[8:11], v[136:139], v[214:217], v[8:11]
	v_mfma_f32_16x16x32_bf16 v[60:63], v[132:135], v[174:177], v[60:63]
	v_mfma_f32_16x16x32_bf16 v[56:59], v[140:143], v[174:177], v[56:59]
	v_mfma_f32_16x16x32_bf16 v[44:47], v[132:135], v[186:189], v[44:47]
	v_mfma_f32_16x16x32_bf16 v[40:43], v[140:143], v[186:189], v[40:43]
	v_mfma_f32_16x16x32_bf16 v[28:31], v[132:135], v[194:197], v[28:31]
	v_mfma_f32_16x16x32_bf16 v[24:27], v[140:143], v[194:197], v[24:27]
	v_mfma_f32_16x16x32_bf16 v[12:15], v[132:135], v[218:221], v[12:15]
	v_mfma_f32_16x16x32_bf16 v[8:11], v[140:143], v[218:221], v[8:11]
	s_barrier
	s_add_u32 s28, s28, 0x100080
	s_addc_u32 s29, s29, 0
	s_add_i32 s30, s30, s36
	s_mov_b32 m0, s30
	s_nop 0
	global_load_lds_dwordx4 v160, s[28:29]
	s_add_i32 m0, s30, 0x2000
	s_nop 0
	global_load_lds_dwordx4 v148, s[28:29]
	s_waitcnt vmcnt(6)
	s_barrier
	v_mfma_f32_16x16x32_bf16 v[52:55], v[222:225], v[154:157], v[52:55]
	v_mfma_f32_16x16x32_bf16 v[48:51], v[230:233], v[154:157], v[48:51]
	v_mfma_f32_16x16x32_bf16 v[36:39], v[222:225], v[182:185], v[36:39]
	v_mfma_f32_16x16x32_bf16 v[32:35], v[230:233], v[182:185], v[32:35]
	v_mfma_f32_16x16x32_bf16 v[20:23], v[222:225], v[190:193], v[20:23]
	v_mfma_f32_16x16x32_bf16 v[16:19], v[230:233], v[190:193], v[16:19]
	v_mfma_f32_16x16x32_bf16 v[4:7], v[222:225], v[214:217], v[4:7]
	v_mfma_f32_16x16x32_bf16 v[0:3], v[230:233], v[214:217], v[0:3]
	v_mfma_f32_16x16x32_bf16 v[52:55], v[226:229], v[174:177], v[52:55]
	v_mfma_f32_16x16x32_bf16 v[48:51], v[234:237], v[174:177], v[48:51]
	v_mfma_f32_16x16x32_bf16 v[36:39], v[226:229], v[186:189], v[36:39]
	v_mfma_f32_16x16x32_bf16 v[32:35], v[234:237], v[186:189], v[32:35]
	v_mfma_f32_16x16x32_bf16 v[20:23], v[226:229], v[194:197], v[20:23]
	v_mfma_f32_16x16x32_bf16 v[16:19], v[234:237], v[194:197], v[16:19]
	v_mfma_f32_16x16x32_bf16 v[4:7], v[226:229], v[218:221], v[4:7]
	v_mfma_f32_16x16x32_bf16 v[0:3], v[234:237], v[218:221], v[0:3]
	s_add_i32 s48, s48, 2
	s_add_u32 s26, s26, 0x100
	s_addc_u32 s27, s27, 0
	s_add_u32 s46, s46, 0x100
	s_addc_u32 s47, s47, 0
	s_cmp_gt_u32 s48, 61
	s_barrier
	s_cbranch_scc0 .LBB0_404
	v_lshl_add_u32 v156, s24, 8, v167
	v_lshl_or_b32 v154, s14, 8, v179
	v_readlane_b32 s24, v254, 16
	v_ashrrev_i32_e32 v155, 31, v154
	v_readlane_b32 s25, v254, 17
	v_ashrrev_i32_e32 v157, 31, v156
	v_lshlrev_b64 v[128:129], 13, v[156:157]
	v_lshl_add_u64 v[158:159], v[154:155], 2, s[24:25]
	v_lshl_add_u64 v[214:215], v[158:159], 0, v[128:129]
	global_load_dwordx4 v[182:185], v[214:215], off offset:16
	global_load_dwordx4 v[186:189], v[214:215], off
	global_load_dwordx4 v[190:193], v[214:215], off offset:528
	global_load_dwordx4 v[194:197], v[214:215], off offset:512
	v_or_b32_e32 v174, 16, v156
	v_ashrrev_i32_e32 v175, 31, v174
	v_lshlrev_b64 v[128:129], 13, v[174:175]
	v_lshl_add_u64 v[176:177], v[158:159], 0, v[128:129]
	global_load_dwordx4 v[136:139], v[176:177], off offset:16
	global_load_dwordx4 v[140:143], v[176:177], off
	global_load_dwordx4 v[128:131], v[176:177], off offset:528
	global_load_dwordx4 v[132:135], v[176:177], off offset:512
	v_lshlrev_b64 v[216:217], 11, v[156:157]
	v_readlane_b32 s24, v250, 9
	v_lshl_add_u64 v[216:217], v[216:217], 0, v[154:155]
	v_readlane_b32 s25, v250, 10
	v_cmp_lt_i32_e32 vcc, v208, v206
	s_ashr_i32 s15, s14, 31
	s_waitcnt vmcnt(0)
	v_pk_add_f32 v[120:121], v[120:121], v[182:183]
	v_pk_add_f32 v[126:127], v[126:127], v[188:189]
	v_pk_add_f32 v[124:125], v[124:125], v[186:187]
	v_pk_add_f32 v[122:123], v[122:123], v[184:185]
	global_store_dwordx4 v[214:215], v[124:127], off
	global_store_dwordx4 v[214:215], v[120:123], off offset:16
	v_cvt_pk_bf16_f32 v184, v120, v121
	v_cvt_pk_bf16_f32 v182, v124, v125
	v_mul_f32_e32 v121, v121, v121
	v_cvt_pk_bf16_f32 v183, v126, v127
	v_cvt_pk_bf16_f32 v185, v122, v123
	v_lshl_add_u64 v[186:187], v[216:217], 1, s[24:25]
	v_fmac_f32_e32 v121, v120, v120
	v_pk_add_f32 v[118:119], v[118:119], v[196:197]
	v_pk_add_f32 v[116:117], v[116:117], v[194:195]
	v_pk_add_f32 v[112:113], v[112:113], v[190:191]
	global_store_dwordx4 v[186:187], v[182:185], off
	v_mul_f32_e32 v125, v125, v125
	v_fmac_f32_e32 v121, v122, v122
	v_pk_add_f32 v[114:115], v[114:115], v[192:193]
	global_store_dwordx4 v[214:215], v[116:119], off offset:512
	global_store_dwordx4 v[214:215], v[112:115], off offset:528
	v_cvt_pk_bf16_f32 v120, v116, v117
	v_cvt_pk_bf16_f32 v122, v112, v113
	v_mul_f32_e32 v117, v117, v117
	v_mul_f32_e32 v113, v113, v113
	v_fmac_f32_e32 v125, v124, v124
	v_fmac_f32_e32 v117, v116, v116
	v_fmac_f32_e32 v113, v112, v112
	v_fmac_f32_e32 v125, v126, v126
	v_fmac_f32_e32 v117, v118, v118
	v_fmac_f32_e32 v113, v114, v114
	v_fmac_f32_e32 v125, v127, v127
	v_fmac_f32_e32 v121, v123, v123
	v_fmac_f32_e32 v117, v119, v119
	v_fmac_f32_e32 v113, v115, v115
	v_add_f32_e32 v124, v125, v121
	v_add_f32_e32 v112, v117, v113
	v_cndmask_b32_e32 v113, v204, v208, vcc
	v_cvt_pk_bf16_f32 v121, v118, v119
	v_add_f32_e32 v112, v124, v112
	v_lshlrev_b32_e32 v118, 2, v113
	ds_bpermute_b32 v113, v118, v112
	v_cmp_lt_i32_e32 vcc, v207, v206
	v_cvt_pk_bf16_f32 v123, v114, v115
	global_store_dwordx4 v[186:187], v[120:123], off offset:256
	s_waitcnt lgkmcnt(0)
	v_add_f32_e32 v112, v112, v113
	v_cndmask_b32_e32 v113, v204, v207, vcc
	v_lshlrev_b32_e32 v119, 2, v113
	ds_bpermute_b32 v113, v119, v112
	s_and_saveexec_b64 s[24:25], s[6:7]
	s_cbranch_execz .LBB0_410
	s_waitcnt lgkmcnt(0)
	v_add_f32_e32 v112, v112, v113
	s_mov_b64 s[26:27], -1
	s_and_b64 vcc, exec, s[12:13]
	s_cbranch_vccz .LBB0_408
	v_readlane_b32 s26, v250, 59
	v_lshlrev_b64 v[114:115], 5, v[156:157]
	v_readlane_b32 s27, v250, 60
	s_nop 1
	v_lshl_add_u64 v[114:115], s[26:27], 0, v[114:115]
	v_lshl_add_u64 v[114:115], s[14:15], 2, v[114:115]
	global_atomic_add_f32 v[114:115], v112, off
	s_mov_b64 s[26:27], 0

; #define PG8_STAGE(bufoff, gbase, voff) do { _Pragma("unroll") for (int _i = 0; _i < 2; ++_i) \
;         __builtin_amdgcn_global_load_lds((const unsigned*)((const char*)(gbase) + (voff)[_i]), (LAS unsigned*)(lds + (bufoff) + ldsw + _i * 8192), 16, 0, 0); } while (0)
; #define PG8_LDA(dst, b, h) do { _Pragma("unroll") for (int m = 0; m < 4; ++m) _Pragma("unroll") for (int k = 0; k < 2; ++k) dst[m][k] = *(const LAS bf16x8*)(lds + PG8_SA(b, h) + aoff + m * 2048 + k * 1024); } while (0)
; #define PG8_LDB(dst, b, h) do { _Pragma("unroll") for (int n = 0; n < 2; ++n) _Pragma("unroll") for (int k = 0; k < 2; ++k) dst[n][k] = *(const LAS bf16x8*)(lds + PG8_SB(b, h) + boff + n * 2048 + k * 1024); } while (0)
; #define PG8_MMA(ai, bj, At, Bt) do { __builtin_amdgcn_s_setprio(1); _Pragma("unroll") for (int m = 0; m < 4; ++m) _Pragma("unroll") for (int n = 0; n < 2; ++n) _Pragma("unroll") for (int k = 0; k < 2; ++k) \
;         acc[ai][bj][m][n] = __builtin_amdgcn_mfma_f32_16x16x32_bf16(Bt[n][k], At[m][k], acc[ai][bj][m][n], 0, 0, 0); __builtin_amdgcn_s_setprio(0); } while (0)
; #define PG8_WAIT_V(n) asm volatile("s_waitcnt vmcnt(" #n ")" ::: "memory")
; #define PG8_WAIT_L(n) asm volatile("s_waitcnt lgkmcnt(" #n ")" ::: "memory")
; #define PG8_BAR __builtin_amdgcn_s_barrier()
; #define PG8_SCHED __builtin_amdgcn_sched_barrier(0)
; template <class Epi>
; DEV void gemm_phase(LAS unsigned char* lds, const Gemm g, const StaticOrder& S, const Epi& E) {
;     ...
;             PG8_LDB(B0, 0, 0); PG8_SCHED; PG8_LDA(At, 0, 0); PG8_STAGE(PG8_SA(1, 1), a1 + hstep, voffA);
;             PG8_WAIT_L(8); PG8_BAR; PG8_WAIT_L(0); PG8_MMA(0, 0, At, B0); PG8_BAR; PG8_SCHED;
;             PG8_LDB(B1, 0, 1); PG8_STAGE(PG8_SB(0, 0), b2, voffB);
;             PG8_BAR; PG8_WAIT_L(0); PG8_MMA(0, 1, At, B1); PG8_BAR;
;             PG8_LDA(At, 0, 1); PG8_STAGE(PG8_SA(0, 0), a2, voffA);
;             PG8_BAR; PG8_WAIT_L(0); PG8_MMA(1, 0, At, B0); PG8_BAR; PG8_SCHED;
;             PG8_STAGE(PG8_SB(0, 1), b2 + hstep, voffB);
;             PG8_WAIT_V(6); PG8_BAR; PG8_MMA(1, 1, At, B1); PG8_BAR;
.LBB0_588:
	s_add_u32 s16, s14, 0xfff80080
	s_addc_u32 s17, s15, -1
	s_add_i32 s41, 0, 0x10000
	v_add_u32_e32 v154, s41, v167
	ds_read_b128 v[128:131], v154
	ds_read_b128 v[132:135], v154 offset:1024
	ds_read_b128 v[150:153], v154 offset:2048
	ds_read_b128 v[174:177], v154 offset:3072
	s_cmp_eq_u32 s40, 28
	s_cselect_b32 s19, s1, s17
	s_cselect_b32 s18, s9, s16
	s_cselect_b32 s17, s7, s37
	s_cselect_b32 s16, s35, s36
	s_add_i32 m0, s24, 0xc000
	ds_read_b128 v[182:185], v219
	ds_read_b128 v[190:193], v219 offset:1024
	ds_read_b128 v[194:197], v219 offset:2048
	ds_read_b128 v[220:223], v219 offset:3072
	ds_read_b128 v[224:227], v219 offset:4096
	ds_read_b128 v[228:231], v219 offset:5120
	ds_read_b128 v[232:235], v219 offset:6144
	ds_read_b128 v[236:239], v219 offset:7168
	global_load_lds_dwordx4 v146, s[14:15]
	s_add_i32 m0, s24, 0xe000
	s_nop 0
	global_load_lds_dwordx4 v148, s[14:15]
	s_waitcnt lgkmcnt(8)
	s_barrier
	s_waitcnt lgkmcnt(0)
	v_mfma_f32_16x16x32_bf16 v[124:127], v[128:131], v[182:185], v[124:127]
	v_mfma_f32_16x16x32_bf16 v[120:123], v[150:153], v[182:185], v[120:123]
	v_mfma_f32_16x16x32_bf16 v[108:111], v[128:131], v[194:197], v[108:111]
	v_mfma_f32_16x16x32_bf16 v[104:107], v[150:153], v[194:197], v[104:107]
	v_mfma_f32_16x16x32_bf16 v[92:95], v[128:131], v[224:227], v[92:95]
	v_mfma_f32_16x16x32_bf16 v[88:91], v[150:153], v[224:227], v[88:91]
	v_mfma_f32_16x16x32_bf16 v[76:79], v[128:131], v[232:235], v[76:79]
	v_mfma_f32_16x16x32_bf16 v[72:75], v[150:153], v[232:235], v[72:75]
	v_mfma_f32_16x16x32_bf16 v[124:127], v[132:135], v[190:193], v[124:127]
	v_mfma_f32_16x16x32_bf16 v[120:123], v[174:177], v[190:193], v[120:123]
	v_mfma_f32_16x16x32_bf16 v[108:111], v[132:135], v[220:223], v[108:111]
	v_mfma_f32_16x16x32_bf16 v[104:107], v[174:177], v[220:223], v[104:107]
	v_mfma_f32_16x16x32_bf16 v[92:95], v[132:135], v[228:231], v[92:95]
	v_mfma_f32_16x16x32_bf16 v[88:91], v[174:177], v[228:231], v[88:91]
	v_mfma_f32_16x16x32_bf16 v[76:79], v[132:135], v[236:239], v[76:79]
	v_mfma_f32_16x16x32_bf16 v[72:75], v[174:177], v[236:239], v[72:75]
	s_barrier
	s_add_i32 s44, 0, 0x14000
	v_add_u32_e32 v154, s44, v167
	s_add_i32 s41, s41, s22
	ds_read_b128 v[240:243], v154
	ds_read_b128 v[244:247], v154 offset:1024
	ds_read_b128 v[186:189], v154 offset:2048
	ds_read_b128 v[214:217], v154 offset:3072
	v_lshl_add_u64 v[154:155], s[16:17], 0, v[140:141]
	s_mov_b32 m0, s41
	v_lshl_add_u64 v[158:159], s[16:17], 0, v[136:137]
	global_load_lds_dwordx4 v140, s[16:17]
	s_add_i32 m0, s41, 0x2000
	s_nop 0
	global_load_lds_dwordx4 v136, s[16:17]
	s_barrier
	s_waitcnt lgkmcnt(0)
	v_mfma_f32_16x16x32_bf16 v[116:119], v[240:243], v[182:185], v[116:119]
	v_mfma_f32_16x16x32_bf16 v[112:115], v[186:189], v[182:185], v[112:115]
	v_mfma_f32_16x16x32_bf16 v[100:103], v[240:243], v[194:197], v[100:103]
	v_mfma_f32_16x16x32_bf16 v[96:99], v[186:189], v[194:197], v[96:99]
	v_mfma_f32_16x16x32_bf16 v[84:87], v[240:243], v[224:227], v[84:87]
	v_mfma_f32_16x16x32_bf16 v[80:83], v[186:189], v[224:227], v[80:83]
	v_mfma_f32_16x16x32_bf16 v[68:71], v[240:243], v[232:235], v[68:71]
	v_mfma_f32_16x16x32_bf16 v[64:67], v[186:189], v[232:235], v[64:67]
	v_mfma_f32_16x16x32_bf16 v[116:119], v[244:247], v[190:193], v[116:119]
	v_mfma_f32_16x16x32_bf16 v[112:115], v[214:217], v[190:193], v[112:115]
	v_mfma_f32_16x16x32_bf16 v[100:103], v[244:247], v[220:223], v[100:103]
	v_mfma_f32_16x16x32_bf16 v[96:99], v[214:217], v[220:223], v[96:99]
	v_mfma_f32_16x16x32_bf16 v[84:87], v[244:247], v[228:231], v[84:87]
	v_mfma_f32_16x16x32_bf16 v[80:83], v[214:217], v[228:231], v[80:83]
	v_mfma_f32_16x16x32_bf16 v[68:71], v[244:247], v[236:239], v[68:71]
	v_mfma_f32_16x16x32_bf16 v[64:67], v[214:217], v[236:239], v[64:67]
	s_barrier
	s_mov_b32 m0, s24
	v_lshl_add_u64 v[178:179], s[18:19], 0, v[142:143]
	ds_read_b128 v[182:185], v219 offset:16384
	ds_read_b128 v[190:193], v219 offset:17408
	ds_read_b128 v[194:197], v219 offset:18432
	ds_read_b128 v[220:223], v219 offset:19456
	ds_read_b128 v[224:227], v219 offset:20480
	ds_read_b128 v[228:231], v219 offset:21504
	ds_read_b128 v[232:235], v219 offset:22528
	ds_read_b128 v[236:239], v219 offset:23552
	global_load_lds_dwordx4 v142, s[18:19]
	v_lshl_add_u64 v[248:249], s[18:19], 0, v[138:139]
	s_mov_b32 m0, s25
	s_nop 0
	global_load_lds_dwordx4 v138, s[18:19]
	s_barrier
	s_waitcnt lgkmcnt(0)
	v_mfma_f32_16x16x32_bf16 v[60:63], v[128:131], v[182:185], v[60:63]
	v_mfma_f32_16x16x32_bf16 v[56:59], v[150:153], v[182:185], v[56:59]
	v_mfma_f32_16x16x32_bf16 v[44:47], v[128:131], v[194:197], v[44:47]
	v_mfma_f32_16x16x32_bf16 v[40:43], v[150:153], v[194:197], v[40:43]
	v_mfma_f32_16x16x32_bf16 v[28:31], v[128:131], v[224:227], v[28:31]
	v_mfma_f32_16x16x32_bf16 v[24:27], v[150:153], v[224:227], v[24:27]
	v_mfma_f32_16x16x32_bf16 v[12:15], v[128:131], v[232:235], v[12:15]
	v_mfma_f32_16x16x32_bf16 v[8:11], v[150:153], v[232:235], v[8:11]
	v_mfma_f32_16x16x32_bf16 v[60:63], v[132:135], v[190:193], v[60:63]
	v_mfma_f32_16x16x32_bf16 v[56:59], v[174:177], v[190:193], v[56:59]
	v_mfma_f32_16x16x32_bf16 v[44:47], v[132:135], v[220:223], v[44:47]
	v_mfma_f32_16x16x32_bf16 v[40:43], v[174:177], v[220:223], v[40:43]
	v_mfma_f32_16x16x32_bf16 v[28:31], v[132:135], v[228:231], v[28:31]
	v_mfma_f32_16x16x32_bf16 v[24:27], v[174:177], v[228:231], v[24:27]
	v_mfma_f32_16x16x32_bf16 v[12:15], v[132:135], v[236:239], v[12:15]
	v_mfma_f32_16x16x32_bf16 v[8:11], v[174:177], v[236:239], v[8:11]
	s_barrier
	s_add_u32 s42, s16, 0x80000
	s_addc_u32 s43, s17, 0
	s_add_i32 s41, s44, s22
	s_mov_b32 m0, s41
	s_nop 0
	global_load_lds_dwordx4 v140, s[42:43]
	s_add_i32 m0, s41, 0x2000
	s_nop 0
	global_load_lds_dwordx4 v136, s[42:43]
	s_waitcnt vmcnt(6)
	s_barrier
; #define PG8_STAGE(bufoff, gbase, voff) do { _Pragma("unroll") for (int _i = 0; _i < 2; ++_i) \
;         __builtin_amdgcn_global_load_lds((const unsigned*)((const char*)(gbase) + (voff)[_i]), (LAS unsigned*)(lds + (bufoff) + ldsw + _i * 8192), 16, 0, 0); } while (0)
; #define PG8_LDA(dst, b, h) do { _Pragma("unroll") for (int m = 0; m < 4; ++m) _Pragma("unroll") for (int k = 0; k < 2; ++k) dst[m][k] = *(const LAS bf16x8*)(lds + PG8_SA(b, h) + aoff + m * 2048 + k * 1024); } while (0)
; #define PG8_LDB(dst, b, h) do { _Pragma("unroll") for (int n = 0; n < 2; ++n) _Pragma("unroll") for (int k = 0; k < 2; ++k) dst[n][k] = *(const LAS bf16x8*)(lds + PG8_SB(b, h) + boff + n * 2048 + k * 1024); } while (0)
; #define PG8_MMA(ai, bj, At, Bt) do { __builtin_amdgcn_s_setprio(1); _Pragma("unroll") for (int m = 0; m < 4; ++m) _Pragma("unroll") for (int n = 0; n < 2; ++n) _Pragma("unroll") for (int k = 0; k < 2; ++k) \
;         acc[ai][bj][m][n] = __builtin_amdgcn_mfma_f32_16x16x32_bf16(Bt[n][k], At[m][k], acc[ai][bj][m][n], 0, 0, 0); __builtin_amdgcn_s_setprio(0); } while (0)
; #define PG8_WAIT_V(n) asm volatile("s_waitcnt vmcnt(" #n ")" ::: "memory")
; #define PG8_WAIT_L(n) asm volatile("s_waitcnt lgkmcnt(" #n ")" ::: "memory")
; #define PG8_BAR __builtin_amdgcn_s_barrier()
; #define PG8_SCHED __builtin_amdgcn_sched_barrier(0)
; template <class Epi>
; DEV void gemm_phase(LAS unsigned char* lds, const Gemm g, const StaticOrder& S, const Epi& E) {
;     ...
;             PG8_WAIT_V(6); PG8_BAR; PG8_MMA(1, 1, At, B1); PG8_BAR;
;             PG8_LDB(B0, 1, 0); PG8_SCHED; PG8_LDA(At, 1, 0); PG8_STAGE(PG8_SA(0, 1), a2 + hstep, voffA);
;             PG8_WAIT_L(8); PG8_BAR; PG8_WAIT_L(0); PG8_MMA(0, 0, At, B0); PG8_BAR; PG8_SCHED;
;             PG8_LDB(B1, 1, 1); PG8_STAGE(PG8_SB(1, 0), b3, voffB);
;             PG8_BAR; PG8_WAIT_L(0); PG8_MMA(0, 1, At, B1); PG8_BAR;
;             PG8_LDA(At, 1, 1); PG8_STAGE(PG8_SA(1, 0), a3, voffA);
	v_mfma_f32_16x16x32_bf16 v[52:55], v[240:243], v[182:185], v[52:55]
	v_mfma_f32_16x16x32_bf16 v[48:51], v[186:189], v[182:185], v[48:51]
	v_mfma_f32_16x16x32_bf16 v[36:39], v[240:243], v[194:197], v[36:39]
	v_mfma_f32_16x16x32_bf16 v[32:35], v[186:189], v[194:197], v[32:35]
	v_mfma_f32_16x16x32_bf16 v[20:23], v[240:243], v[224:227], v[20:23]
	v_mfma_f32_16x16x32_bf16 v[16:19], v[186:189], v[224:227], v[16:19]
	v_mfma_f32_16x16x32_bf16 v[4:7], v[240:243], v[232:235], v[4:7]
	v_mfma_f32_16x16x32_bf16 v[0:3], v[186:189], v[232:235], v[0:3]
	v_mfma_f32_16x16x32_bf16 v[52:55], v[244:247], v[190:193], v[52:55]
	v_mfma_f32_16x16x32_bf16 v[48:51], v[214:217], v[190:193], v[48:51]
	v_mfma_f32_16x16x32_bf16 v[36:39], v[244:247], v[220:223], v[36:39]
	v_mfma_f32_16x16x32_bf16 v[32:35], v[214:217], v[220:223], v[32:35]
	v_mfma_f32_16x16x32_bf16 v[20:23], v[244:247], v[228:231], v[20:23]
	v_mfma_f32_16x16x32_bf16 v[16:19], v[214:217], v[228:231], v[16:19]
	v_mfma_f32_16x16x32_bf16 v[4:7], v[244:247], v[236:239], v[4:7]
	v_mfma_f32_16x16x32_bf16 v[0:3], v[214:217], v[236:239], v[0:3]
	s_barrier
	s_add_i32 s41, 0, 0x18000
	v_add_u32_e32 v156, s41, v167
	ds_read_b128 v[128:131], v156
	ds_read_b128 v[132:135], v156 offset:1024
	ds_read_b128 v[150:153], v156 offset:2048
	ds_read_b128 v[174:177], v156 offset:3072
	s_add_u32 s18, s18, 0x80000
	s_addc_u32 s19, s19, 0
	s_mov_b32 m0, s26
	ds_read_b128 v[182:185], v219 offset:32768
	ds_read_b128 v[186:189], v219 offset:33792
	ds_read_b128 v[190:193], v219 offset:34816
	ds_read_b128 v[194:197], v219 offset:35840
	ds_read_b128 v[214:217], v219 offset:36864
	ds_read_b128 v[220:223], v219 offset:37888
	ds_read_b128 v[224:227], v219 offset:38912
	ds_read_b128 v[228:231], v219 offset:39936
	global_load_lds_dwordx4 v142, s[18:19]
	s_mov_b32 m0, s27
	s_nop 0
	global_load_lds_dwordx4 v138, s[18:19]
	s_waitcnt lgkmcnt(8)
	s_barrier
	s_waitcnt lgkmcnt(0)
	v_mfma_f32_16x16x32_bf16 v[124:127], v[128:131], v[182:185], v[124:127]
	v_mfma_f32_16x16x32_bf16 v[120:123], v[150:153], v[182:185], v[120:123]
	v_mfma_f32_16x16x32_bf16 v[108:111], v[128:131], v[190:193], v[108:111]
	v_mfma_f32_16x16x32_bf16 v[104:107], v[150:153], v[190:193], v[104:107]
	v_mfma_f32_16x16x32_bf16 v[92:95], v[128:131], v[214:217], v[92:95]
	v_mfma_f32_16x16x32_bf16 v[88:91], v[150:153], v[214:217], v[88:91]
	v_mfma_f32_16x16x32_bf16 v[76:79], v[128:131], v[224:227], v[76:79]
	v_mfma_f32_16x16x32_bf16 v[72:75], v[150:153], v[224:227], v[72:75]
	v_mfma_f32_16x16x32_bf16 v[124:127], v[132:135], v[186:189], v[124:127]
	v_mfma_f32_16x16x32_bf16 v[120:123], v[174:177], v[186:189], v[120:123]
	v_mfma_f32_16x16x32_bf16 v[108:111], v[132:135], v[194:197], v[108:111]
	v_mfma_f32_16x16x32_bf16 v[104:107], v[174:177], v[194:197], v[104:107]
	v_mfma_f32_16x16x32_bf16 v[92:95], v[132:135], v[220:223], v[92:95]
	v_mfma_f32_16x16x32_bf16 v[88:91], v[174:177], v[220:223], v[88:91]
	v_mfma_f32_16x16x32_bf16 v[76:79], v[132:135], v[228:231], v[76:79]
	v_mfma_f32_16x16x32_bf16 v[72:75], v[174:177], v[228:231], v[72:75]
	s_barrier
	s_add_i32 s18, 0, 0x1c000
	s_add_i32 s19, s41, s22
	v_add_u32_e32 v156, s18, v167
	v_lshl_add_u64 v[154:155], v[154:155], 0, s[2:3]
	s_mov_b32 m0, s19
	ds_read_b128 v[232:235], v156
	ds_read_b128 v[236:239], v156 offset:1024
	ds_read_b128 v[240:243], v156 offset:2048
	ds_read_b128 v[244:247], v156 offset:3072
	global_load_lds_dwordx4 v[154:155], off
	v_lshl_add_u64 v[154:155], v[158:159], 0, s[2:3]
	s_add_i32 m0, s19, 0x2000
	s_nop 0
	global_load_lds_dwordx4 v[154:155], off
	s_barrier
	s_waitcnt lgkmcnt(0)
	v_mfma_f32_16x16x32_bf16 v[116:119], v[232:235], v[182:185], v[116:119]
	v_mfma_f32_16x16x32_bf16 v[112:115], v[240:243], v[182:185], v[112:115]
	v_mfma_f32_16x16x32_bf16 v[100:103], v[232:235], v[190:193], v[100:103]
	v_mfma_f32_16x16x32_bf16 v[96:99], v[240:243], v[190:193], v[96:99]
	v_mfma_f32_16x16x32_bf16 v[84:87], v[232:235], v[214:217], v[84:87]
	v_mfma_f32_16x16x32_bf16 v[80:83], v[240:243], v[214:217], v[80:83]
	v_mfma_f32_16x16x32_bf16 v[68:71], v[232:235], v[224:227], v[68:71]
	v_mfma_f32_16x16x32_bf16 v[64:67], v[240:243], v[224:227], v[64:67]
	v_mfma_f32_16x16x32_bf16 v[116:119], v[236:239], v[186:189], v[116:119]
	v_mfma_f32_16x16x32_bf16 v[112:115], v[244:247], v[186:189], v[112:115]
	v_mfma_f32_16x16x32_bf16 v[100:103], v[236:239], v[194:197], v[100:103]
	v_mfma_f32_16x16x32_bf16 v[96:99], v[244:247], v[194:197], v[96:99]
	v_mfma_f32_16x16x32_bf16 v[84:87], v[236:239], v[220:223], v[84:87]
	v_mfma_f32_16x16x32_bf16 v[80:83], v[244:247], v[220:223], v[80:83]
	v_mfma_f32_16x16x32_bf16 v[68:71], v[236:239], v[228:231], v[68:71]
	v_mfma_f32_16x16x32_bf16 v[64:67], v[244:247], v[228:231], v[64:67]
	s_barrier
	s_mov_b32 m0, s28
	v_lshl_add_u64 v[154:155], v[178:179], 0, s[2:3]
	ds_read_b128 v[182:185], v219 offset:49152
	ds_read_b128 v[186:189], v219 offset:50176
	ds_read_b128 v[190:193], v219 offset:51200
	ds_read_b128 v[194:197], v219 offset:52224
	ds_read_b128 v[214:217], v219 offset:53248
	ds_read_b128 v[220:223], v219 offset:54272
	ds_read_b128 v[224:227], v219 offset:55296
	ds_read_b128 v[228:231], v219 offset:56320
	global_load_lds_dwordx4 v[154:155], off
	v_lshl_add_u64 v[154:155], v[248:249], 0, s[2:3]
	s_mov_b32 m0, s29
	s_nop 0
	global_load_lds_dwordx4 v[154:155], off
	s_barrier
; #define PG8_STAGE(bufoff, gbase, voff) do { _Pragma("unroll") for (int _i = 0; _i < 2; ++_i) \
;         __builtin_amdgcn_global_load_lds((const unsigned*)((const char*)(gbase) + (voff)[_i]), (LAS unsigned*)(lds + (bufoff) + ldsw + _i * 8192), 16, 0, 0); } while (0)
; #define PG8_MMA(ai, bj, At, Bt) do { __builtin_amdgcn_s_setprio(1); _Pragma("unroll") for (int m = 0; m < 4; ++m) _Pragma("unroll") for (int n = 0; n < 2; ++n) _Pragma("unroll") for (int k = 0; k < 2; ++k) \
;         acc[ai][bj][m][n] = __builtin_amdgcn_mfma_f32_16x16x32_bf16(Bt[n][k], At[m][k], acc[ai][bj][m][n], 0, 0, 0); __builtin_amdgcn_s_setprio(0); } while (0)
; #define PG8_WAIT_V(n) asm volatile("s_waitcnt vmcnt(" #n ")" ::: "memory")
; #define PG8_WAIT_L(n) asm volatile("s_waitcnt lgkmcnt(" #n ")" ::: "memory")
; #define PG8_BAR __builtin_amdgcn_s_barrier()
; #define PG8_SCHED __builtin_amdgcn_sched_barrier(0)
; template <class Epi>
; DEV void gemm_phase(LAS unsigned char* lds, const Gemm g, const StaticOrder& S, const Epi& E) {
;     ...
;             PG8_BAR; PG8_WAIT_L(0); PG8_MMA(1, 0, At, B0); PG8_BAR; PG8_SCHED;
;             PG8_STAGE(PG8_SB(1, 1), b3 + hstep, voffB);
;             PG8_WAIT_V(6); PG8_BAR; PG8_MMA(1, 1, At, B1); PG8_BAR;
;         }
;     DEV void operator()(AccRef acc, const pg8::Unit& u, int wr, int wc, int fr, int fq) const {
;         const int ct = u.pn * 256, row0 = u.pm * 256 + wr * 64 + fr, cw = wc * 32 + 8 * fq;
;         if (ct < 4096) store_bf16_tile<1, true>(acc, UV, 4096, row0, ct + cw, ss);
;         else if (ct < 6144) store_bf16_tile<0, true>(acc, Z, 2048, row0, ct - 4096 + cw, ss);
;         else if (ct < 9216) store_bf16_tile<0, true>(acc, XBC, 3072, row0, ct - 6144 + cw, ss);
;         else if (wc == 0) {
; #pragma unroll
;             for (int ai = 0; ai < 2; ++ai)
; #pragma unroll
;                 for (int m = 0; m < 4; ++m) { const float rs = rowscale(ss, row0 + ai * 128 + m * 16);
; #pragma unroll
;                     for (int n = 0; n < 2; ++n) *(f32x4*)(DTR + (size_t)(row0 + ai * 128 + m * 16) * 32 + 8 * fq + 4 * n) = acc[ai][0][m][n] * rs; }
	s_waitcnt lgkmcnt(0)
	v_mfma_f32_16x16x32_bf16 v[60:63], v[128:131], v[182:185], v[60:63]
	v_mfma_f32_16x16x32_bf16 v[56:59], v[150:153], v[182:185], v[56:59]
	v_mfma_f32_16x16x32_bf16 v[44:47], v[128:131], v[190:193], v[44:47]
	v_mfma_f32_16x16x32_bf16 v[40:43], v[150:153], v[190:193], v[40:43]
	v_mfma_f32_16x16x32_bf16 v[28:31], v[128:131], v[214:217], v[28:31]
	v_mfma_f32_16x16x32_bf16 v[24:27], v[150:153], v[214:217], v[24:27]
	v_mfma_f32_16x16x32_bf16 v[12:15], v[128:131], v[224:227], v[12:15]
	v_mfma_f32_16x16x32_bf16 v[8:11], v[150:153], v[224:227], v[8:11]
	v_mfma_f32_16x16x32_bf16 v[60:63], v[132:135], v[186:189], v[60:63]
	v_mfma_f32_16x16x32_bf16 v[56:59], v[174:177], v[186:189], v[56:59]
	v_mfma_f32_16x16x32_bf16 v[44:47], v[132:135], v[194:197], v[44:47]
	v_mfma_f32_16x16x32_bf16 v[40:43], v[174:177], v[194:197], v[40:43]
	v_mfma_f32_16x16x32_bf16 v[28:31], v[132:135], v[220:223], v[28:31]
	v_mfma_f32_16x16x32_bf16 v[24:27], v[174:177], v[220:223], v[24:27]
	v_mfma_f32_16x16x32_bf16 v[12:15], v[132:135], v[228:231], v[12:15]
	v_mfma_f32_16x16x32_bf16 v[8:11], v[174:177], v[228:231], v[8:11]
	s_barrier
	s_add_u32 s16, s16, 0x80080
	s_addc_u32 s17, s17, 0
	s_add_i32 s18, s18, s22
	s_mov_b32 m0, s18
	s_nop 0
	global_load_lds_dwordx4 v140, s[16:17]
	s_add_i32 m0, s18, 0x2000
	s_nop 0
	global_load_lds_dwordx4 v136, s[16:17]
	s_waitcnt vmcnt(6)
	s_barrier
	v_mfma_f32_16x16x32_bf16 v[52:55], v[232:235], v[182:185], v[52:55]
	v_mfma_f32_16x16x32_bf16 v[48:51], v[240:243], v[182:185], v[48:51]
	v_mfma_f32_16x16x32_bf16 v[36:39], v[232:235], v[190:193], v[36:39]
	v_mfma_f32_16x16x32_bf16 v[32:35], v[240:243], v[190:193], v[32:35]
	v_mfma_f32_16x16x32_bf16 v[20:23], v[232:235], v[214:217], v[20:23]
	v_mfma_f32_16x16x32_bf16 v[16:19], v[240:243], v[214:217], v[16:19]
	v_mfma_f32_16x16x32_bf16 v[4:7], v[232:235], v[224:227], v[4:7]
	v_mfma_f32_16x16x32_bf16 v[0:3], v[240:243], v[224:227], v[0:3]
	v_mfma_f32_16x16x32_bf16 v[52:55], v[236:239], v[186:189], v[52:55]
	v_mfma_f32_16x16x32_bf16 v[48:51], v[244:247], v[186:189], v[48:51]
	v_mfma_f32_16x16x32_bf16 v[36:39], v[236:239], v[194:197], v[36:39]
	v_mfma_f32_16x16x32_bf16 v[32:35], v[244:247], v[194:197], v[32:35]
	v_mfma_f32_16x16x32_bf16 v[20:23], v[236:239], v[220:223], v[20:23]
	v_mfma_f32_16x16x32_bf16 v[16:19], v[244:247], v[220:223], v[16:19]
	v_mfma_f32_16x16x32_bf16 v[4:7], v[236:239], v[228:231], v[4:7]
	v_mfma_f32_16x16x32_bf16 v[0:3], v[244:247], v[228:231], v[0:3]
	s_add_i32 s40, s40, 2
	s_add_u32 s14, s14, 0x100
	s_addc_u32 s15, s15, 0
	s_add_u32 s36, s36, 0x100
	s_addc_u32 s37, s37, 0
	s_cmp_gt_u32 s40, 29
	s_barrier
	s_cbranch_scc0 .LBB0_588
	s_lshl_b32 s7, s34, 8
	v_lshl_add_u32 v150, s0, 8, v157
	s_cmp_gt_i32 s34, 15
	s_mov_b64 s[0:1], -1
	s_cbranch_scc0 .LBB0_601
	s_cmp_gt_u32 s34, 23
	s_cbranch_scc0 .LBB0_598
	s_cmp_gt_u32 s34, 35
	s_cbranch_scc0 .LBB0_595
	s_andn2_b64 vcc, exec, s[4:5]
	s_cbranch_vccnz .LBB0_594
	v_ashrrev_i32_e32 v151, 31, v150
	v_readlane_b32 s0, v251, 39
	v_lshlrev_b64 v[128:129], 5, v[150:151]
	v_readlane_b32 s1, v251, 40
	s_mov_b32 s9, 0x800000
	s_nop 0
	v_lshl_add_u64 v[132:133], s[0:1], 0, v[128:129]
	global_load_dwordx4 v[128:131], v[132:133], off offset:16
	s_nop 0
	global_load_dwordx4 v[132:135], v[132:133], off
	s_waitcnt vmcnt(0)
	v_mov_b32_e32 v152, v133
	v_mov_b32_e32 v153, v134
	v_mov_b32_e32 v133, v135
	v_pk_add_f32 v[132:133], v[152:153], v[132:133]
	v_mov_b32_e32 v134, v130
	v_mov_b32_e32 v135, v128
	v_mov_b32_e32 v128, v131
	v_pk_add_f32 v[128:129], v[134:135], v[128:129]
	v_add_f32_e32 v130, v132, v133
	v_add_f32_e32 v129, v130, v129
	v_add_f32_e32 v128, v128, v129
	v_fmamk_f32 v128, v128, 0x3a000000, v199
	v_cmp_gt_f32_e32 vcc, s9, v128
	v_mul_f32_e32 v129, 0x4b800000, v128
	v_lshlrev_b64 v[134:135], 7, v[150:151]
	v_cndmask_b32_e32 v128, v128, v129, vcc
	v_rsq_f32_e32 v128, v128
	v_lshl_add_u64 v[134:135], v[144:145], 0, v[134:135]
	v_or_b32_e32 v152, 16, v150
	v_ashrrev_i32_e32 v153, 31, v152
	v_mul_f32_e32 v129, 0x45800000, v128
	v_cndmask_b32_e32 v132, v128, v129, vcc
	v_pk_mul_f32 v[130:131], v[126:127], v[132:133] op_sel_hi:[1,0]
	v_pk_mul_f32 v[128:129], v[124:125], v[132:133] op_sel_hi:[1,0]
	global_store_dwordx4 v[134:135], v[128:131], off
	s_nop 1
	v_pk_mul_f32 v[130:131], v[122:123], v[132:133] op_sel_hi:[1,0]
	v_pk_mul_f32 v[128:129], v[120:121], v[132:133] op_sel_hi:[1,0]
	global_store_dwordx4 v[134:135], v[128:131], off offset:16
	s_nop 1
	v_lshlrev_b64 v[128:129], 5, v[152:153]
	v_lshl_add_u64 v[132:133], s[0:1], 0, v[128:129]
	global_load_dwordx4 v[128:131], v[132:133], off offset:16
	s_nop 0
	global_load_dwordx4 v[132:135], v[132:133], off
	s_waitcnt vmcnt(0)
	v_mov_b32_e32 v154, v133
	v_mov_b32_e32 v155, v134
	v_mov_b32_e32 v133, v135
	v_pk_add_f32 v[132:133], v[154:155], v[132:133]
	v_mov_b32_e32 v134, v130
	v_mov_b32_e32 v135, v128
	v_mov_b32_e32 v128, v131
	v_pk_add_f32 v[128:129], v[134:135], v[128:129]
	v_add_f32_e32 v130, v132, v133
	v_add_f32_e32 v129, v130, v129
	v_add_f32_e32 v128, v128, v129
	v_fmamk_f32 v128, v128, 0x3a000000, v199
	v_cmp_gt_f32_e32 vcc, s9, v128
	v_mul_f32_e32 v129, 0x4b800000, v128
	v_lshlrev_b64 v[134:135], 7, v[152:153]
	v_cndmask_b32_e32 v128, v128, v129, vcc
	v_rsq_f32_e32 v128, v128
	v_lshl_add_u64 v[134:135], v[144:145], 0, v[134:135]
	v_or_b32_e32 v152, 32, v150
	v_ashrrev_i32_e32 v153, 31, v152
	v_mul_f32_e32 v129, 0x45800000, v128
	v_cndmask_b32_e32 v132, v128, v129, vcc
	v_pk_mul_f32 v[130:131], v[110:111], v[132:133] op_sel_hi:[1,0]
	v_pk_mul_f32 v[128:129], v[108:109], v[132:133] op_sel_hi:[1,0]
	global_store_dwordx4 v[134:135], v[128:131], off
	s_nop 1
	v_pk_mul_f32 v[130:131], v[106:107], v[132:133] op_sel_hi:[1,0]
	v_pk_mul_f32 v[128:129], v[104:105], v[132:133] op_sel_hi:[1,0]
	global_store_dwordx4 v[134:135], v[128:131], off offset:16
	s_nop 1
	v_lshlrev_b64 v[128:129], 5, v[152:153]
	v_lshl_add_u64 v[132:133], s[0:1], 0, v[128:129]
	global_load_dwordx4 v[128:131], v[132:133], off offset:16
	s_nop 0
	global_load_dwordx4 v[132:135], v[132:133], off
	s_waitcnt vmcnt(0)
;     DEV void operator()(AccRef acc, const pg8::Unit& u, int wr, int wc, int fr, int fq) const {
;     ...
;         else if (wc == 0) {
; #pragma unroll
;             for (int ai = 0; ai < 2; ++ai)
; #pragma unroll
;                 for (int m = 0; m < 4; ++m) { const float rs = rowscale(ss, row0 + ai * 128 + m * 16);
; #pragma unroll
;                     for (int n = 0; n < 2; ++n) *(f32x4*)(DTR + (size_t)(row0 + ai * 128 + m * 16) * 32 + 8 * fq + 4 * n) = acc[ai][0][m][n] * rs; }
	v_mov_b32_e32 v154, v133
	v_mov_b32_e32 v155, v134
	v_mov_b32_e32 v133, v135
	v_pk_add_f32 v[132:133], v[154:155], v[132:133]
	v_mov_b32_e32 v134, v130
	v_mov_b32_e32 v135, v128
	v_mov_b32_e32 v128, v131
	v_pk_add_f32 v[128:129], v[134:135], v[128:129]
	v_add_f32_e32 v130, v132, v133
	v_add_f32_e32 v129, v130, v129
	v_add_f32_e32 v128, v128, v129
	v_fmamk_f32 v128, v128, 0x3a000000, v199
	v_cmp_gt_f32_e32 vcc, s9, v128
	v_mul_f32_e32 v129, 0x4b800000, v128
	v_lshlrev_b64 v[134:135], 7, v[152:153]
	v_cndmask_b32_e32 v128, v128, v129, vcc
	v_rsq_f32_e32 v128, v128
	v_lshl_add_u64 v[134:135], v[144:145], 0, v[134:135]
	v_or_b32_e32 v152, 48, v150
	v_ashrrev_i32_e32 v153, 31, v152
	v_mul_f32_e32 v129, 0x45800000, v128
	v_cndmask_b32_e32 v132, v128, v129, vcc
	v_pk_mul_f32 v[130:131], v[94:95], v[132:133] op_sel_hi:[1,0]
	v_pk_mul_f32 v[128:129], v[92:93], v[132:133] op_sel_hi:[1,0]
	global_store_dwordx4 v[134:135], v[128:131], off
	s_nop 1
	v_pk_mul_f32 v[130:131], v[90:91], v[132:133] op_sel_hi:[1,0]
	v_pk_mul_f32 v[128:129], v[88:89], v[132:133] op_sel_hi:[1,0]
	global_store_dwordx4 v[134:135], v[128:131], off offset:16
	s_nop 1
	v_lshlrev_b64 v[128:129], 5, v[152:153]
	v_lshl_add_u64 v[132:133], s[0:1], 0, v[128:129]
	global_load_dwordx4 v[128:131], v[132:133], off offset:16
	s_nop 0
	global_load_dwordx4 v[132:135], v[132:133], off
	s_waitcnt vmcnt(0)
	v_mov_b32_e32 v154, v133
	v_mov_b32_e32 v155, v134
	v_mov_b32_e32 v133, v135
	v_pk_add_f32 v[132:133], v[154:155], v[132:133]
	v_mov_b32_e32 v134, v130
	v_mov_b32_e32 v135, v128
	v_mov_b32_e32 v128, v131
	v_pk_add_f32 v[128:129], v[134:135], v[128:129]
	v_add_f32_e32 v130, v132, v133
	v_add_f32_e32 v129, v130, v129
	v_add_f32_e32 v128, v128, v129
	v_fmamk_f32 v128, v128, 0x3a000000, v199
	v_cmp_gt_f32_e32 vcc, s9, v128
	v_mul_f32_e32 v129, 0x4b800000, v128
	v_lshlrev_b64 v[134:135], 7, v[152:153]
	v_cndmask_b32_e32 v128, v128, v129, vcc
	v_rsq_f32_e32 v128, v128
	v_lshl_add_u64 v[134:135], v[144:145], 0, v[134:135]
	v_add_u32_e32 v152, 0x80, v150
	v_ashrrev_i32_e32 v153, 31, v152
	v_mul_f32_e32 v129, 0x45800000, v128
	v_cndmask_b32_e32 v132, v128, v129, vcc
	v_pk_mul_f32 v[130:131], v[78:79], v[132:133] op_sel_hi:[1,0]
	v_pk_mul_f32 v[128:129], v[76:77], v[132:133] op_sel_hi:[1,0]
	global_store_dwordx4 v[134:135], v[128:131], off
	s_nop 1
	v_pk_mul_f32 v[130:131], v[74:75], v[132:133] op_sel_hi:[1,0]
	v_pk_mul_f32 v[128:129], v[72:73], v[132:133] op_sel_hi:[1,0]
	global_store_dwordx4 v[134:135], v[128:131], off offset:16
	s_nop 1
	v_lshlrev_b64 v[128:129], 5, v[152:153]
	v_lshl_add_u64 v[132:133], s[0:1], 0, v[128:129]
	global_load_dwordx4 v[128:131], v[132:133], off offset:16
	s_nop 0
	global_load_dwordx4 v[132:135], v[132:133], off
	s_waitcnt vmcnt(0)
	v_mov_b32_e32 v154, v133
	v_mov_b32_e32 v155, v134
	v_mov_b32_e32 v133, v135
	v_pk_add_f32 v[132:133], v[154:155], v[132:133]
	v_mov_b32_e32 v134, v130
	v_mov_b32_e32 v135, v128
	v_mov_b32_e32 v128, v131
	v_pk_add_f32 v[128:129], v[134:135], v[128:129]
	v_add_f32_e32 v130, v132, v133
	v_add_f32_e32 v129, v130, v129
	v_add_f32_e32 v128, v128, v129
	v_fmamk_f32 v128, v128, 0x3a000000, v199
	v_cmp_gt_f32_e32 vcc, s9, v128
	v_mul_f32_e32 v129, 0x4b800000, v128
	v_lshlrev_b64 v[134:135], 7, v[152:153]
	v_cndmask_b32_e32 v128, v128, v129, vcc
	v_rsq_f32_e32 v128, v128
	v_lshl_add_u64 v[134:135], v[144:145], 0, v[134:135]
	v_add_u32_e32 v152, 0x90, v150
	v_ashrrev_i32_e32 v153, 31, v152
	v_mul_f32_e32 v129, 0x45800000, v128
	v_cndmask_b32_e32 v132, v128, v129, vcc
	v_pk_mul_f32 v[130:131], v[62:63], v[132:133] op_sel_hi:[1,0]
	v_pk_mul_f32 v[128:129], v[60:61], v[132:133] op_sel_hi:[1,0]
	global_store_dwordx4 v[134:135], v[128:131], off
	s_nop 1
	v_pk_mul_f32 v[130:131], v[58:59], v[132:133] op_sel_hi:[1,0]
	v_pk_mul_f32 v[128:129], v[56:57], v[132:133] op_sel_hi:[1,0]
	global_store_dwordx4 v[134:135], v[128:131], off offset:16
	s_nop 1
	v_lshlrev_b64 v[128:129], 5, v[152:153]
	v_lshl_add_u64 v[132:133], s[0:1], 0, v[128:129]
	global_load_dwordx4 v[128:131], v[132:133], off offset:16
	s_nop 0
	global_load_dwordx4 v[132:135], v[132:133], off
	s_waitcnt vmcnt(0)
;     DEV void operator()(AccRef acc, const pg8::Unit& u, int wr, int wc, int fr, int fq) const {
;     ...
;         else if (wc == 0) {
; #pragma unroll
;             for (int ai = 0; ai < 2; ++ai)
; #pragma unroll
;                 for (int m = 0; m < 4; ++m) { const float rs = rowscale(ss, row0 + ai * 128 + m * 16);
; #pragma unroll
;                     for (int n = 0; n < 2; ++n) *(f32x4*)(DTR + (size_t)(row0 + ai * 128 + m * 16) * 32 + 8 * fq + 4 * n) = acc[ai][0][m][n] * rs; }
	v_mov_b32_e32 v154, v133
	v_mov_b32_e32 v155, v134
	v_mov_b32_e32 v133, v135
	v_pk_add_f32 v[132:133], v[154:155], v[132:133]
	v_mov_b32_e32 v134, v130
	v_mov_b32_e32 v135, v128
	v_mov_b32_e32 v128, v131
	v_pk_add_f32 v[128:129], v[134:135], v[128:129]
	v_add_f32_e32 v130, v132, v133
	v_add_f32_e32 v129, v130, v129
	v_add_f32_e32 v128, v128, v129
	v_fmamk_f32 v128, v128, 0x3a000000, v199
	v_cmp_gt_f32_e32 vcc, s9, v128
	v_mul_f32_e32 v129, 0x4b800000, v128
	v_lshlrev_b64 v[134:135], 7, v[152:153]
	v_cndmask_b32_e32 v128, v128, v129, vcc
	v_rsq_f32_e32 v128, v128
	v_lshl_add_u64 v[134:135], v[144:145], 0, v[134:135]
	v_add_u32_e32 v152, 0xa0, v150
	v_ashrrev_i32_e32 v153, 31, v152
	v_mul_f32_e32 v129, 0x45800000, v128
	v_cndmask_b32_e32 v132, v128, v129, vcc
	v_pk_mul_f32 v[130:131], v[46:47], v[132:133] op_sel_hi:[1,0]
	v_pk_mul_f32 v[128:129], v[44:45], v[132:133] op_sel_hi:[1,0]
	global_store_dwordx4 v[134:135], v[128:131], off
	s_nop 1
	v_pk_mul_f32 v[130:131], v[42:43], v[132:133] op_sel_hi:[1,0]
	v_pk_mul_f32 v[128:129], v[40:41], v[132:133] op_sel_hi:[1,0]
	global_store_dwordx4 v[134:135], v[128:131], off offset:16
	s_nop 1
	v_lshlrev_b64 v[128:129], 5, v[152:153]
	v_lshl_add_u64 v[132:133], s[0:1], 0, v[128:129]
	global_load_dwordx4 v[128:131], v[132:133], off offset:16
	s_nop 0
	global_load_dwordx4 v[132:135], v[132:133], off
	s_waitcnt vmcnt(0)
	v_mov_b32_e32 v154, v133
	v_mov_b32_e32 v155, v134
	v_mov_b32_e32 v133, v135
	v_pk_add_f32 v[132:133], v[154:155], v[132:133]
	v_mov_b32_e32 v134, v130
	v_mov_b32_e32 v135, v128
	v_mov_b32_e32 v128, v131
	v_pk_add_f32 v[128:129], v[134:135], v[128:129]
	v_add_f32_e32 v130, v132, v133
	v_add_f32_e32 v129, v130, v129
	v_add_f32_e32 v128, v128, v129
	v_fmamk_f32 v128, v128, 0x3a000000, v199
	v_cmp_gt_f32_e32 vcc, s9, v128
	v_mul_f32_e32 v129, 0x4b800000, v128
	v_lshlrev_b64 v[134:135], 7, v[152:153]
	v_cndmask_b32_e32 v128, v128, v129, vcc
	v_rsq_f32_e32 v128, v128
	v_lshl_add_u64 v[134:135], v[144:145], 0, v[134:135]
	v_add_u32_e32 v152, 0xb0, v150
	v_ashrrev_i32_e32 v153, 31, v152
	v_mul_f32_e32 v129, 0x45800000, v128
	v_cndmask_b32_e32 v132, v128, v129, vcc
	v_pk_mul_f32 v[130:131], v[30:31], v[132:133] op_sel_hi:[1,0]
	v_pk_mul_f32 v[128:129], v[28:29], v[132:133] op_sel_hi:[1,0]
	global_store_dwordx4 v[134:135], v[128:131], off
	s_nop 1
	v_pk_mul_f32 v[130:131], v[26:27], v[132:133] op_sel_hi:[1,0]
	v_pk_mul_f32 v[128:129], v[24:25], v[132:133] op_sel_hi:[1,0]
	global_store_dwordx4 v[134:135], v[128:131], off offset:16
	s_nop 1
	v_lshlrev_b64 v[128:129], 5, v[152:153]
	v_lshl_add_u64 v[132:133], s[0:1], 0, v[128:129]
	global_load_dwordx4 v[128:131], v[132:133], off offset:16
	s_nop 0
	global_load_dwordx4 v[132:135], v[132:133], off
	s_waitcnt vmcnt(0)
	v_mov_b32_e32 v154, v133
	v_mov_b32_e32 v155, v134
	v_mov_b32_e32 v133, v135
	v_pk_add_f32 v[132:133], v[154:155], v[132:133]
	v_mov_b32_e32 v134, v130
	v_mov_b32_e32 v135, v128
	v_mov_b32_e32 v128, v131
	v_pk_add_f32 v[128:129], v[134:135], v[128:129]
	v_add_f32_e32 v130, v132, v133
	v_add_f32_e32 v129, v130, v129
	v_add_f32_e32 v128, v128, v129
	v_fmamk_f32 v128, v128, 0x3a000000, v199
	v_cmp_gt_f32_e32 vcc, s9, v128
	v_mul_f32_e32 v129, 0x4b800000, v128
	v_lshlrev_b64 v[134:135], 7, v[152:153]
	v_cndmask_b32_e32 v128, v128, v129, vcc
	v_rsq_f32_e32 v128, v128
	v_lshl_add_u64 v[134:135], v[144:145], 0, v[134:135]
	v_mul_f32_e32 v129, 0x45800000, v128
	v_cndmask_b32_e32 v132, v128, v129, vcc
	v_pk_mul_f32 v[130:131], v[14:15], v[132:133] op_sel_hi:[1,0]
	v_pk_mul_f32 v[128:129], v[12:13], v[132:133] op_sel_hi:[1,0]
	global_store_dwordx4 v[134:135], v[128:131], off
	s_nop 1
	v_pk_mul_f32 v[130:131], v[10:11], v[132:133] op_sel_hi:[1,0]
	v_pk_mul_f32 v[128:129], v[8:9], v[132:133] op_sel_hi:[1,0]
	global_store_dwordx4 v[134:135], v[128:131], off offset:16

; #define PG8_STAGE(bufoff, gbase, voff) do { _Pragma("unroll") for (int _i = 0; _i < 2; ++_i) \
;         __builtin_amdgcn_global_load_lds((const unsigned*)((const char*)(gbase) + (voff)[_i]), (LAS unsigned*)(lds + (bufoff) + ldsw + _i * 8192), 16, 0, 0); } while (0)
; #define PG8_LDA(dst, b, h) do { _Pragma("unroll") for (int m = 0; m < 4; ++m) _Pragma("unroll") for (int k = 0; k < 2; ++k) dst[m][k] = *(const LAS bf16x8*)(lds + PG8_SA(b, h) + aoff + m * 2048 + k * 1024); } while (0)
; #define PG8_LDB(dst, b, h) do { _Pragma("unroll") for (int n = 0; n < 2; ++n) _Pragma("unroll") for (int k = 0; k < 2; ++k) dst[n][k] = *(const LAS bf16x8*)(lds + PG8_SB(b, h) + boff + n * 2048 + k * 1024); } while (0)
; #define PG8_MMA(ai, bj, At, Bt) do { __builtin_amdgcn_s_setprio(1); _Pragma("unroll") for (int m = 0; m < 4; ++m) _Pragma("unroll") for (int n = 0; n < 2; ++n) _Pragma("unroll") for (int k = 0; k < 2; ++k) \
;         acc[ai][bj][m][n] = __builtin_amdgcn_mfma_f32_16x16x32_bf16(Bt[n][k], At[m][k], acc[ai][bj][m][n], 0, 0, 0); __builtin_amdgcn_s_setprio(0); } while (0)
; #define PG8_WAIT_V(n) asm volatile("s_waitcnt vmcnt(" #n ")" ::: "memory")
; #define PG8_WAIT_L(n) asm volatile("s_waitcnt lgkmcnt(" #n ")" ::: "memory")
; #define PG8_BAR __builtin_amdgcn_s_barrier()
; #define PG8_SCHED __builtin_amdgcn_sched_barrier(0)
; template <class Epi>
; DEV void gemm_phase(LAS unsigned char* lds, const Gemm g, const StaticOrder& S, const Epi& E) {
;     ...
;             PG8_LDB(B0, 0, 0); PG8_SCHED; PG8_LDA(At, 0, 0); PG8_STAGE(PG8_SA(1, 1), a1 + hstep, voffA);
;             PG8_WAIT_L(8); PG8_BAR; PG8_WAIT_L(0); PG8_MMA(0, 0, At, B0); PG8_BAR; PG8_SCHED;
;             PG8_LDB(B1, 0, 1); PG8_STAGE(PG8_SB(0, 0), b2, voffB);
;             PG8_BAR; PG8_WAIT_L(0); PG8_MMA(0, 1, At, B1); PG8_BAR;
;             PG8_LDA(At, 0, 1); PG8_STAGE(PG8_SA(0, 0), a2, voffA);
;             PG8_BAR; PG8_WAIT_L(0); PG8_MMA(1, 0, At, B0); PG8_BAR; PG8_SCHED;
;             PG8_STAGE(PG8_SB(0, 1), b2 + hstep, voffB);
;             PG8_WAIT_V(6); PG8_BAR; PG8_MMA(1, 1, At, B1); PG8_BAR;
.LBB0_657:
	s_add_u32 s6, s28, 0x100
	s_addc_u32 s7, s29, 0
	s_add_i32 s55, 0, 0x10000
	v_add_u32_e32 v140, s55, v196
	ds_read_b128 v[128:131], v140
	ds_read_b128 v[132:135], v140 offset:1024
	ds_read_b128 v[136:139], v140 offset:2048
	ds_read_b128 v[140:143], v140 offset:3072
	s_cmpk_eq_i32 s54, 0x54
	s_cselect_b32 s35, s27, s7
	s_cselect_b32 s34, s26, s6
	s_cselect_b32 s31, s9, s53
	s_cselect_b32 s30, s8, s52
	s_add_i32 m0, s41, 0xc000
	ds_read_b128 v[144:147], v219
	ds_read_b128 v[148:151], v219 offset:1024
	ds_read_b128 v[152:155], v219 offset:2048
	ds_read_b128 v[156:159], v219 offset:3072
	ds_read_b128 v[184:187], v219 offset:4096
	ds_read_b128 v[188:191], v219 offset:5120
	ds_read_b128 v[192:195], v219 offset:6144
	ds_read_b128 v[220:223], v219 offset:7168
	global_load_lds_dwordx4 v180, s[28:29]
	s_add_i32 m0, s41, 0xe000
	s_nop 0
	global_load_lds_dwordx4 v182, s[28:29]
	s_waitcnt lgkmcnt(8)
	s_barrier
	s_waitcnt lgkmcnt(0)
	v_mfma_f32_16x16x32_bf16 v[124:127], v[128:131], v[144:147], v[124:127]
	v_mfma_f32_16x16x32_bf16 v[120:123], v[136:139], v[144:147], v[120:123]
	v_mfma_f32_16x16x32_bf16 v[112:115], v[128:131], v[152:155], v[112:115]
	v_mfma_f32_16x16x32_bf16 v[104:107], v[136:139], v[152:155], v[104:107]
	v_mfma_f32_16x16x32_bf16 v[92:95], v[128:131], v[184:187], v[92:95]
	v_mfma_f32_16x16x32_bf16 v[88:91], v[136:139], v[184:187], v[88:91]
	v_mfma_f32_16x16x32_bf16 v[80:83], v[128:131], v[192:195], v[80:83]
	v_mfma_f32_16x16x32_bf16 v[72:75], v[136:139], v[192:195], v[72:75]
	v_mfma_f32_16x16x32_bf16 v[124:127], v[132:135], v[148:151], v[124:127]
	v_mfma_f32_16x16x32_bf16 v[120:123], v[140:143], v[148:151], v[120:123]
	v_mfma_f32_16x16x32_bf16 v[112:115], v[132:135], v[156:159], v[112:115]
	v_mfma_f32_16x16x32_bf16 v[104:107], v[140:143], v[156:159], v[104:107]
	v_mfma_f32_16x16x32_bf16 v[92:95], v[132:135], v[188:191], v[92:95]
	v_mfma_f32_16x16x32_bf16 v[88:91], v[140:143], v[188:191], v[88:91]
	v_mfma_f32_16x16x32_bf16 v[80:83], v[132:135], v[220:223], v[80:83]
	v_mfma_f32_16x16x32_bf16 v[72:75], v[140:143], v[220:223], v[72:75]
	s_barrier
	s_add_i32 s56, 0, 0x14000
	v_add_u32_e32 v214, s56, v196
	s_add_i32 s28, s55, s40
	ds_read_b128 v[224:227], v214
	ds_read_b128 v[228:231], v214 offset:1024
	ds_read_b128 v[232:235], v214 offset:2048
	ds_read_b128 v[236:239], v214 offset:3072
	v_lshl_add_u64 v[214:215], s[30:31], 0, v[160:161]
	s_mov_b32 m0, s28
	v_lshl_add_u64 v[216:217], s[30:31], 0, v[178:179]
	global_load_lds_dwordx4 v160, s[30:31]
	s_add_i32 m0, s28, 0x2000
	s_nop 0
	global_load_lds_dwordx4 v178, s[30:31]
	s_barrier
	s_waitcnt lgkmcnt(0)
	v_mfma_f32_16x16x32_bf16 v[116:119], v[224:227], v[144:147], v[116:119]
	v_mfma_f32_16x16x32_bf16 v[108:111], v[232:235], v[144:147], v[108:111]
	v_mfma_f32_16x16x32_bf16 v[100:103], v[224:227], v[152:155], v[100:103]
	v_mfma_f32_16x16x32_bf16 v[96:99], v[232:235], v[152:155], v[96:99]
	v_mfma_f32_16x16x32_bf16 v[84:87], v[224:227], v[184:187], v[84:87]
	v_mfma_f32_16x16x32_bf16 v[76:79], v[232:235], v[184:187], v[76:79]
	v_mfma_f32_16x16x32_bf16 v[68:71], v[224:227], v[192:195], v[68:71]
	v_mfma_f32_16x16x32_bf16 v[64:67], v[232:235], v[192:195], v[64:67]
	v_mfma_f32_16x16x32_bf16 v[116:119], v[228:231], v[148:151], v[116:119]
	v_mfma_f32_16x16x32_bf16 v[108:111], v[236:239], v[148:151], v[108:111]
	v_mfma_f32_16x16x32_bf16 v[100:103], v[228:231], v[156:159], v[100:103]
	v_mfma_f32_16x16x32_bf16 v[96:99], v[236:239], v[156:159], v[96:99]
	v_mfma_f32_16x16x32_bf16 v[84:87], v[228:231], v[188:191], v[84:87]
	v_mfma_f32_16x16x32_bf16 v[76:79], v[236:239], v[188:191], v[76:79]
	v_mfma_f32_16x16x32_bf16 v[68:71], v[228:231], v[220:223], v[68:71]
	v_mfma_f32_16x16x32_bf16 v[64:67], v[236:239], v[220:223], v[64:67]
	s_barrier
	s_mov_b32 m0, s41
	v_lshl_add_u64 v[240:241], s[34:35], 0, v[174:175]
	ds_read_b128 v[144:147], v219 offset:16384
	ds_read_b128 v[148:151], v219 offset:17408
	ds_read_b128 v[152:155], v219 offset:18432
	ds_read_b128 v[156:159], v219 offset:19456
	ds_read_b128 v[184:187], v219 offset:20480
	ds_read_b128 v[188:191], v219 offset:21504
	ds_read_b128 v[192:195], v219 offset:22528
	ds_read_b128 v[220:223], v219 offset:23552
	global_load_lds_dwordx4 v174, s[34:35]
	v_lshl_add_u64 v[242:243], s[34:35], 0, v[176:177]
	s_mov_b32 m0, s42
	s_nop 0
	global_load_lds_dwordx4 v176, s[34:35]
	s_barrier
	s_waitcnt lgkmcnt(0)
	v_mfma_f32_16x16x32_bf16 v[60:63], v[128:131], v[144:147], v[60:63]
	v_mfma_f32_16x16x32_bf16 v[56:59], v[136:139], v[144:147], v[56:59]
	v_mfma_f32_16x16x32_bf16 v[48:51], v[128:131], v[152:155], v[48:51]
	v_mfma_f32_16x16x32_bf16 v[40:43], v[136:139], v[152:155], v[40:43]
	v_mfma_f32_16x16x32_bf16 v[28:31], v[128:131], v[184:187], v[28:31]
	v_mfma_f32_16x16x32_bf16 v[24:27], v[136:139], v[184:187], v[24:27]
	v_mfma_f32_16x16x32_bf16 v[16:19], v[128:131], v[192:195], v[16:19]
	v_mfma_f32_16x16x32_bf16 v[8:11], v[136:139], v[192:195], v[8:11]
	v_mfma_f32_16x16x32_bf16 v[60:63], v[132:135], v[148:151], v[60:63]
	v_mfma_f32_16x16x32_bf16 v[56:59], v[140:143], v[148:151], v[56:59]
	v_mfma_f32_16x16x32_bf16 v[48:51], v[132:135], v[156:159], v[48:51]
	v_mfma_f32_16x16x32_bf16 v[40:43], v[140:143], v[156:159], v[40:43]
	v_mfma_f32_16x16x32_bf16 v[28:31], v[132:135], v[188:191], v[28:31]
	v_mfma_f32_16x16x32_bf16 v[24:27], v[140:143], v[188:191], v[24:27]
	v_mfma_f32_16x16x32_bf16 v[16:19], v[132:135], v[220:223], v[16:19]
	v_mfma_f32_16x16x32_bf16 v[8:11], v[140:143], v[220:223], v[8:11]
	s_barrier
	s_add_u32 s28, s30, 0x160000
	s_addc_u32 s29, s31, 0
	s_add_i32 s55, s56, s40
	s_mov_b32 m0, s55
	s_nop 0
	global_load_lds_dwordx4 v160, s[28:29]
	s_add_i32 m0, s55, 0x2000
	s_nop 0
	global_load_lds_dwordx4 v178, s[28:29]
	s_waitcnt vmcnt(6)
	s_barrier
; #define PG8_STAGE(bufoff, gbase, voff) do { _Pragma("unroll") for (int _i = 0; _i < 2; ++_i) \
;         __builtin_amdgcn_global_load_lds((const unsigned*)((const char*)(gbase) + (voff)[_i]), (LAS unsigned*)(lds + (bufoff) + ldsw + _i * 8192), 16, 0, 0); } while (0)
; #define PG8_LDA(dst, b, h) do { _Pragma("unroll") for (int m = 0; m < 4; ++m) _Pragma("unroll") for (int k = 0; k < 2; ++k) dst[m][k] = *(const LAS bf16x8*)(lds + PG8_SA(b, h) + aoff + m * 2048 + k * 1024); } while (0)
; #define PG8_LDB(dst, b, h) do { _Pragma("unroll") for (int n = 0; n < 2; ++n) _Pragma("unroll") for (int k = 0; k < 2; ++k) dst[n][k] = *(const LAS bf16x8*)(lds + PG8_SB(b, h) + boff + n * 2048 + k * 1024); } while (0)
; #define PG8_MMA(ai, bj, At, Bt) do { __builtin_amdgcn_s_setprio(1); _Pragma("unroll") for (int m = 0; m < 4; ++m) _Pragma("unroll") for (int n = 0; n < 2; ++n) _Pragma("unroll") for (int k = 0; k < 2; ++k) \
;         acc[ai][bj][m][n] = __builtin_amdgcn_mfma_f32_16x16x32_bf16(Bt[n][k], At[m][k], acc[ai][bj][m][n], 0, 0, 0); __builtin_amdgcn_s_setprio(0); } while (0)
; #define PG8_WAIT_V(n) asm volatile("s_waitcnt vmcnt(" #n ")" ::: "memory")
; #define PG8_WAIT_L(n) asm volatile("s_waitcnt lgkmcnt(" #n ")" ::: "memory")
; #define PG8_BAR __builtin_amdgcn_s_barrier()
; #define PG8_SCHED __builtin_amdgcn_sched_barrier(0)
; template <class Epi>
; DEV void gemm_phase(LAS unsigned char* lds, const Gemm g, const StaticOrder& S, const Epi& E) {
;     ...
;             PG8_WAIT_V(6); PG8_BAR; PG8_MMA(1, 1, At, B1); PG8_BAR;
;             PG8_LDB(B0, 1, 0); PG8_SCHED; PG8_LDA(At, 1, 0); PG8_STAGE(PG8_SA(0, 1), a2 + hstep, voffA);
;             PG8_WAIT_L(8); PG8_BAR; PG8_WAIT_L(0); PG8_MMA(0, 0, At, B0); PG8_BAR; PG8_SCHED;
;             PG8_LDB(B1, 1, 1); PG8_STAGE(PG8_SB(1, 0), b3, voffB);
;             PG8_BAR; PG8_WAIT_L(0); PG8_MMA(0, 1, At, B1); PG8_BAR;
;             PG8_LDA(At, 1, 1); PG8_STAGE(PG8_SA(1, 0), a3, voffA);
	v_mfma_f32_16x16x32_bf16 v[52:55], v[224:227], v[144:147], v[52:55]
	v_mfma_f32_16x16x32_bf16 v[44:47], v[232:235], v[144:147], v[44:47]
	v_mfma_f32_16x16x32_bf16 v[36:39], v[224:227], v[152:155], v[36:39]
	v_mfma_f32_16x16x32_bf16 v[32:35], v[232:235], v[152:155], v[32:35]
	v_mfma_f32_16x16x32_bf16 v[20:23], v[224:227], v[184:187], v[20:23]
	v_mfma_f32_16x16x32_bf16 v[12:15], v[232:235], v[184:187], v[12:15]
	v_mfma_f32_16x16x32_bf16 v[4:7], v[224:227], v[192:195], v[4:7]
	v_mfma_f32_16x16x32_bf16 v[0:3], v[232:235], v[192:195], v[0:3]
	v_mfma_f32_16x16x32_bf16 v[52:55], v[228:231], v[148:151], v[52:55]
	v_mfma_f32_16x16x32_bf16 v[44:47], v[236:239], v[148:151], v[44:47]
	v_mfma_f32_16x16x32_bf16 v[36:39], v[228:231], v[156:159], v[36:39]
	v_mfma_f32_16x16x32_bf16 v[32:35], v[236:239], v[156:159], v[32:35]
	v_mfma_f32_16x16x32_bf16 v[20:23], v[228:231], v[188:191], v[20:23]
	v_mfma_f32_16x16x32_bf16 v[12:15], v[236:239], v[188:191], v[12:15]
	v_mfma_f32_16x16x32_bf16 v[4:7], v[228:231], v[220:223], v[4:7]
	v_mfma_f32_16x16x32_bf16 v[0:3], v[236:239], v[220:223], v[0:3]
	s_barrier
	s_add_i32 s55, 0, 0x18000
	v_add_u32_e32 v140, s55, v196
	ds_read_b128 v[128:131], v140
	ds_read_b128 v[132:135], v140 offset:1024
	ds_read_b128 v[136:139], v140 offset:2048
	ds_read_b128 v[140:143], v140 offset:3072
	s_add_u32 s28, s34, 0x160000
	s_addc_u32 s29, s35, 0
	s_mov_b32 m0, s43
	ds_read_b128 v[144:147], v219 offset:32768
	ds_read_b128 v[148:151], v219 offset:33792
	ds_read_b128 v[152:155], v219 offset:34816
	ds_read_b128 v[156:159], v219 offset:35840
	ds_read_b128 v[184:187], v219 offset:36864
	ds_read_b128 v[188:191], v219 offset:37888
	ds_read_b128 v[192:195], v219 offset:38912
	ds_read_b128 v[220:223], v219 offset:39936
	global_load_lds_dwordx4 v174, s[28:29]
	s_mov_b32 m0, s44
	s_nop 0
	global_load_lds_dwordx4 v176, s[28:29]
	s_waitcnt lgkmcnt(8)
	s_barrier
	s_waitcnt lgkmcnt(0)
	v_mfma_f32_16x16x32_bf16 v[124:127], v[128:131], v[144:147], v[124:127]
	v_mfma_f32_16x16x32_bf16 v[120:123], v[136:139], v[144:147], v[120:123]
	v_mfma_f32_16x16x32_bf16 v[112:115], v[128:131], v[152:155], v[112:115]
	v_mfma_f32_16x16x32_bf16 v[104:107], v[136:139], v[152:155], v[104:107]
	v_mfma_f32_16x16x32_bf16 v[92:95], v[128:131], v[184:187], v[92:95]
	v_mfma_f32_16x16x32_bf16 v[88:91], v[136:139], v[184:187], v[88:91]
	v_mfma_f32_16x16x32_bf16 v[80:83], v[128:131], v[192:195], v[80:83]
	v_mfma_f32_16x16x32_bf16 v[72:75], v[136:139], v[192:195], v[72:75]
	v_mfma_f32_16x16x32_bf16 v[124:127], v[132:135], v[148:151], v[124:127]
	v_mfma_f32_16x16x32_bf16 v[120:123], v[140:143], v[148:151], v[120:123]
	v_mfma_f32_16x16x32_bf16 v[112:115], v[132:135], v[156:159], v[112:115]
	v_mfma_f32_16x16x32_bf16 v[104:107], v[140:143], v[156:159], v[104:107]
	v_mfma_f32_16x16x32_bf16 v[92:95], v[132:135], v[188:191], v[92:95]
	v_mfma_f32_16x16x32_bf16 v[88:91], v[140:143], v[188:191], v[88:91]
	v_mfma_f32_16x16x32_bf16 v[80:83], v[132:135], v[220:223], v[80:83]
	v_mfma_f32_16x16x32_bf16 v[72:75], v[140:143], v[220:223], v[72:75]
	s_barrier
	s_add_i32 s34, 0, 0x1c000
	s_add_i32 s28, s55, s40
	v_add_u32_e32 v236, s34, v196
	v_lshl_add_u64 v[214:215], v[214:215], 0, s[2:3]
	s_mov_b32 m0, s28
	ds_read_b128 v[224:227], v236
	ds_read_b128 v[228:231], v236 offset:1024
	ds_read_b128 v[232:235], v236 offset:2048
	ds_read_b128 v[236:239], v236 offset:3072
	global_load_lds_dwordx4 v[214:215], off
	v_lshl_add_u64 v[214:215], v[216:217], 0, s[2:3]
	s_add_i32 m0, s28, 0x2000
	s_nop 0
	global_load_lds_dwordx4 v[214:215], off
	s_barrier
	s_waitcnt lgkmcnt(0)
	v_mfma_f32_16x16x32_bf16 v[116:119], v[224:227], v[144:147], v[116:119]
	v_mfma_f32_16x16x32_bf16 v[108:111], v[232:235], v[144:147], v[108:111]
	v_mfma_f32_16x16x32_bf16 v[100:103], v[224:227], v[152:155], v[100:103]
	v_mfma_f32_16x16x32_bf16 v[96:99], v[232:235], v[152:155], v[96:99]
	v_mfma_f32_16x16x32_bf16 v[84:87], v[224:227], v[184:187], v[84:87]
	v_mfma_f32_16x16x32_bf16 v[76:79], v[232:235], v[184:187], v[76:79]
	v_mfma_f32_16x16x32_bf16 v[68:71], v[224:227], v[192:195], v[68:71]
	v_mfma_f32_16x16x32_bf16 v[64:67], v[232:235], v[192:195], v[64:67]
	v_mfma_f32_16x16x32_bf16 v[116:119], v[228:231], v[148:151], v[116:119]
	v_mfma_f32_16x16x32_bf16 v[108:111], v[236:239], v[148:151], v[108:111]
	v_mfma_f32_16x16x32_bf16 v[100:103], v[228:231], v[156:159], v[100:103]
	v_mfma_f32_16x16x32_bf16 v[96:99], v[236:239], v[156:159], v[96:99]
	v_mfma_f32_16x16x32_bf16 v[84:87], v[228:231], v[188:191], v[84:87]
	v_mfma_f32_16x16x32_bf16 v[76:79], v[236:239], v[188:191], v[76:79]
	v_mfma_f32_16x16x32_bf16 v[68:71], v[228:231], v[220:223], v[68:71]
	v_mfma_f32_16x16x32_bf16 v[64:67], v[236:239], v[220:223], v[64:67]
	s_barrier
	s_mov_b32 m0, s45
	v_lshl_add_u64 v[214:215], v[240:241], 0, s[2:3]
	ds_read_b128 v[144:147], v219 offset:49152
	ds_read_b128 v[148:151], v219 offset:50176
	ds_read_b128 v[152:155], v219 offset:51200
	ds_read_b128 v[156:159], v219 offset:52224
	ds_read_b128 v[184:187], v219 offset:53248
	ds_read_b128 v[188:191], v219 offset:54272
	ds_read_b128 v[192:195], v219 offset:55296
	ds_read_b128 v[220:223], v219 offset:56320
	global_load_lds_dwordx4 v[214:215], off
	v_lshl_add_u64 v[214:215], v[242:243], 0, s[2:3]
	s_mov_b32 m0, s46
	s_nop 0
	global_load_lds_dwordx4 v[214:215], off
	s_barrier
; DEV bf16x8 pack8(f32x4 a, f32x4 b) { u32x4 w; w.x = cvt_pk_bf16(a[0], a[1]); w.y = cvt_pk_bf16(a[2], a[3]); w.z = cvt_pk_bf16(b[0], b[1]); w.w = cvt_pk_bf16(b[2], b[3]); return __builtin_bit_cast(bf16x8, w); }
; #define PG8_WAIT_V(n) asm volatile("s_waitcnt vmcnt(" #n ")" ::: "memory")
; template <class Epi>
; DEV void gemm_phase(LAS unsigned char* lds, const Gemm g, const StaticOrder& S, const Epi& E) {
;     ...
;             PG8_BAR; PG8_WAIT_L(0); PG8_MMA(0, 1, At, B1); PG8_BAR;
;             PG8_LDA(At, 1, 1); PG8_STAGE(PG8_SA(1, 0), a3, voffA);
;             PG8_BAR; PG8_WAIT_L(0); PG8_MMA(1, 0, At, B0); PG8_BAR; PG8_SCHED;
;             PG8_STAGE(PG8_SB(1, 1), b3 + hstep, voffB);
;             PG8_WAIT_V(6); PG8_BAR; PG8_MMA(1, 1, At, B1); PG8_BAR;
;     DEV void operator()(AccRef acc, const pg8::Unit& u, int wr, int wc, int fr, int fq) const {
;         const int row0 = u.pm * 256 + wr * 64 + fr, col0 = u.pn * 256 + wc * 32 + 8 * fq;
; #pragma unroll
;         for (int am = 0; am < 4; ++am) { const int ai = am >> 1, m0 = (am & 1) * 2;
;             f32x4 bv[4][2][2];
; #pragma unroll
;             for (int m = m0; m < m0 + 2; ++m)
; #pragma unroll
;                 for (int bj = 0; bj < 2; ++bj)
; #pragma unroll
;                     for (int n = 0; n < 2; ++n) bv[m][bj][n] = *(const f32x4*)(base + (size_t)(row0 + ai * 128 + m * 16) * 2048 + col0 + bj * 128 + n * 4);
; #pragma unroll
;             for (int m = m0; m < m0 + 2; ++m) { const size_t off = (size_t)(row0 + ai * 128 + m * 16) * 2048 + col0; float sq = 0.f;
; #pragma unroll
;                 for (int bj = 0; bj < 2; ++bj) { const f32x4 o0 = bv[m][bj][0] + scale * acc[ai][bj][m][0], o1 = bv[m][bj][1] + scale * acc[ai][bj][m][1];
;                     *(f32x4*)(out + off + bj * 128) = o0; *(f32x4*)(out + off + bj * 128 + 4) = o1;
;                     if (xb) { *(u32x4*)(xb + off + bj * 128) = __builtin_bit_cast(u32x4, pack8(o0, o1));
;                         sq += (o0[0] * o0[0] + o0[1] * o0[1] + o0[2] * o0[2] + o0[3] * o0[3]) + (o1[0] * o1[0] + o1[1] * o1[1] + o1[2] * o1[2] + o1[3] * o1[3]); } }
;                 if (ssout) { sq += __shfl_xor(sq, 16); sq += __shfl_xor(sq, 32);
;                     if (fq == 0) { if (red) red[(ai * 128 + wr * 64 + m * 16 + fr) * 4 + wc] = sq; else atomicAdd(ssout + (size_t)(row0 + ai * 128 + m * 16) * 8 + u.pn, sq); } } }
	s_waitcnt lgkmcnt(0)
	v_mfma_f32_16x16x32_bf16 v[60:63], v[128:131], v[144:147], v[60:63]
	v_mfma_f32_16x16x32_bf16 v[56:59], v[136:139], v[144:147], v[56:59]
	v_mfma_f32_16x16x32_bf16 v[48:51], v[128:131], v[152:155], v[48:51]
	v_mfma_f32_16x16x32_bf16 v[40:43], v[136:139], v[152:155], v[40:43]
	v_mfma_f32_16x16x32_bf16 v[28:31], v[128:131], v[184:187], v[28:31]
	v_mfma_f32_16x16x32_bf16 v[24:27], v[136:139], v[184:187], v[24:27]
	v_mfma_f32_16x16x32_bf16 v[16:19], v[128:131], v[192:195], v[16:19]
	v_mfma_f32_16x16x32_bf16 v[8:11], v[136:139], v[192:195], v[8:11]
	v_mfma_f32_16x16x32_bf16 v[60:63], v[132:135], v[148:151], v[60:63]
	v_mfma_f32_16x16x32_bf16 v[56:59], v[140:143], v[148:151], v[56:59]
	v_mfma_f32_16x16x32_bf16 v[48:51], v[132:135], v[156:159], v[48:51]
	v_mfma_f32_16x16x32_bf16 v[40:43], v[140:143], v[156:159], v[40:43]
	v_mfma_f32_16x16x32_bf16 v[28:31], v[132:135], v[188:191], v[28:31]
	v_mfma_f32_16x16x32_bf16 v[24:27], v[140:143], v[188:191], v[24:27]
	v_mfma_f32_16x16x32_bf16 v[16:19], v[132:135], v[220:223], v[16:19]
	v_mfma_f32_16x16x32_bf16 v[8:11], v[140:143], v[220:223], v[8:11]
	s_barrier
	s_add_u32 s28, s30, 0x160080
	s_addc_u32 s29, s31, 0
	s_add_i32 s30, s34, s40
	s_mov_b32 m0, s30
	s_nop 0
	global_load_lds_dwordx4 v160, s[28:29]
	s_add_i32 m0, s30, 0x2000
	s_nop 0
	global_load_lds_dwordx4 v178, s[28:29]
	s_waitcnt vmcnt(6)
	s_barrier
	v_mfma_f32_16x16x32_bf16 v[52:55], v[224:227], v[144:147], v[52:55]
	v_mfma_f32_16x16x32_bf16 v[44:47], v[232:235], v[144:147], v[44:47]
	v_mfma_f32_16x16x32_bf16 v[36:39], v[224:227], v[152:155], v[36:39]
	v_mfma_f32_16x16x32_bf16 v[32:35], v[232:235], v[152:155], v[32:35]
	v_mfma_f32_16x16x32_bf16 v[20:23], v[224:227], v[184:187], v[20:23]
	v_mfma_f32_16x16x32_bf16 v[12:15], v[232:235], v[184:187], v[12:15]
	v_mfma_f32_16x16x32_bf16 v[4:7], v[224:227], v[192:195], v[4:7]
	v_mfma_f32_16x16x32_bf16 v[0:3], v[232:235], v[192:195], v[0:3]
	v_mfma_f32_16x16x32_bf16 v[52:55], v[228:231], v[148:151], v[52:55]
	v_mfma_f32_16x16x32_bf16 v[44:47], v[236:239], v[148:151], v[44:47]
	v_mfma_f32_16x16x32_bf16 v[36:39], v[228:231], v[156:159], v[36:39]
	v_mfma_f32_16x16x32_bf16 v[32:35], v[236:239], v[156:159], v[32:35]
	v_mfma_f32_16x16x32_bf16 v[20:23], v[228:231], v[188:191], v[20:23]
	v_mfma_f32_16x16x32_bf16 v[12:15], v[236:239], v[188:191], v[12:15]
	v_mfma_f32_16x16x32_bf16 v[4:7], v[228:231], v[220:223], v[4:7]
	v_mfma_f32_16x16x32_bf16 v[0:3], v[236:239], v[220:223], v[0:3]
	s_add_i32 s54, s54, 2
	s_add_u32 s52, s52, 0x100
	s_addc_u32 s53, s53, 0
	s_cmpk_gt_u32 s54, 0x55
	s_mov_b64 s[28:29], s[6:7]
	s_barrier
	s_cbranch_scc0 .LBB0_657
	v_lshl_add_u32 v186, s23, 8, v167
	v_lshl_or_b32 v184, s22, 8, v197
	v_ashrrev_i32_e32 v185, 31, v184
	v_ashrrev_i32_e32 v187, 31, v186
	v_lshl_add_u64 v[188:189], v[184:185], 2, s[24:25]
	v_lshlrev_b64 v[128:129], 13, v[186:187]
	v_or_b32_e32 v190, 16, v186
	v_lshl_add_u64 v[128:129], v[188:189], 0, v[128:129]
	v_ashrrev_i32_e32 v191, 31, v190
	global_load_dwordx4 v[152:155], v[128:129], off offset:16
	global_load_dwordx4 v[156:159], v[128:129], off
	global_load_dwordx4 v[144:147], v[128:129], off offset:528
	global_load_dwordx4 v[148:151], v[128:129], off offset:512
	v_lshlrev_b64 v[128:129], 13, v[190:191]
	v_lshl_add_u64 v[132:133], v[188:189], 0, v[128:129]
	global_load_dwordx4 v[136:139], v[132:133], off offset:16
	global_load_dwordx4 v[140:143], v[132:133], off
	global_load_dwordx4 v[128:131], v[132:133], off offset:528
	s_nop 0
	global_load_dwordx4 v[132:135], v[132:133], off offset:512
	v_lshlrev_b64 v[192:193], 11, v[186:187]
	v_lshl_add_u64 v[194:195], v[192:193], 0, v[184:185]
	s_ashr_i32 s23, s22, 31
	v_lshl_add_u64 v[192:193], v[194:195], 2, s[68:69]
	s_mov_b64 s[28:29], -1
	s_andn2_b64 vcc, exec, s[18:19]
	s_waitcnt vmcnt(0)
	v_pk_fma_f32 v[152:153], v[120:121], 0.5, v[152:153] op_sel_hi:[1,0,1]
	v_cndmask_b32_e64 v120, 0, 1, s[18:19]
	v_pk_fma_f32 v[158:159], v[126:127], 0.5, v[158:159] op_sel_hi:[1,0,1]
	v_pk_fma_f32 v[156:157], v[124:125], 0.5, v[156:157] op_sel_hi:[1,0,1]
	v_pk_fma_f32 v[154:155], v[122:123], 0.5, v[154:155] op_sel_hi:[1,0,1]
	v_cmp_ne_u32_e64 s[6:7], 1, v120
	v_pk_fma_f32 v[120:121], v[116:117], 0.5, v[148:149] op_sel_hi:[1,0,1]
	v_pk_fma_f32 v[124:125], v[108:109], 0.5, v[144:145] op_sel_hi:[1,0,1]
	global_store_dwordx4 v[192:193], v[156:159], off
	global_store_dwordx4 v[192:193], v[152:155], off offset:16
	s_cbranch_vccnz .LBB0_665
	v_mul_f32_e32 v108, v157, v157
	v_mul_f32_e32 v109, v153, v153
	v_fmac_f32_e32 v108, v156, v156
	v_fmac_f32_e32 v109, v152, v152
	v_fmac_f32_e32 v108, v158, v158
	v_fmac_f32_e32 v109, v154, v154
	v_fmac_f32_e32 v108, v159, v159
	v_fmac_f32_e32 v109, v155, v155
	v_add_f32_e32 v108, v108, v109
	v_mul_f32_e32 v109, v121, v121
	v_mul_f32_e32 v144, v125, v125
	v_pk_fma_f32 v[122:123], v[118:119], 0.5, v[150:151] op_sel_hi:[1,0,1]
	v_pk_fma_f32 v[126:127], v[110:111], 0.5, v[146:147] op_sel_hi:[1,0,1]
	v_fmac_f32_e32 v109, v120, v120
	v_fmac_f32_e32 v144, v124, v124
	v_fmac_f32_e32 v109, v122, v122
	v_fmac_f32_e32 v144, v126, v126
	v_fmac_f32_e32 v109, v123, v123
	v_fmac_f32_e32 v144, v127, v127
	v_add_f32_e32 v109, v109, v144
	v_cmp_lt_i32_e32 vcc, v208, v206
	v_add_f32_e32 v108, v108, v109
	v_readlane_b32 s28, v250, 9
	v_cndmask_b32_e32 v109, v204, v208, vcc
	v_lshlrev_b32_e32 v109, 2, v109
	ds_bpermute_b32 v109, v109, v108
	v_cmp_lt_i32_e32 vcc, v207, v206
	v_readlane_b32 s29, v250, 10
	v_cvt_pk_bf16_f32 v220, v156, v157
	v_cvt_pk_bf16_f32 v221, v158, v159
	s_waitcnt lgkmcnt(0)
	v_add_f32_e32 v108, v108, v109
	v_cndmask_b32_e32 v109, v204, v207, vcc
	v_lshlrev_b32_e32 v109, 2, v109
	ds_bpermute_b32 v109, v109, v108
	v_cvt_pk_bf16_f32 v222, v152, v153
	v_cvt_pk_bf16_f32 v223, v154, v155
	v_lshl_add_u64 v[116:117], v[194:195], 1, s[28:29]
	v_cvt_pk_bf16_f32 v152, v120, v121
	v_cvt_pk_bf16_f32 v153, v122, v123
	v_cvt_pk_bf16_f32 v154, v124, v125
	v_cvt_pk_bf16_f32 v155, v126, v127
	global_store_dwordx4 v[116:117], v[220:223], off
	global_store_dwordx4 v[192:193], v[120:123], off offset:512
	global_store_dwordx4 v[192:193], v[124:127], off offset:528
	global_store_dwordx4 v[116:117], v[152:155], off offset:256
	s_and_saveexec_b64 s[28:29], s[10:11]
	s_cbranch_execz .LBB0_664
	s_waitcnt lgkmcnt(0)
	v_add_f32_e32 v108, v108, v109
	s_andn2_b64 vcc, exec, s[20:21]
	s_mov_b64 s[30:31], -1
	s_cbranch_vccnz .LBB0_662
	s_mov_b64 s[30:31], 0
	ds_write_b32 v218, v108

; #define PG8_STAGE(bufoff, gbase, voff) do { _Pragma("unroll") for (int _i = 0; _i < 2; ++_i) \
;         __builtin_amdgcn_global_load_lds((const unsigned*)((const char*)(gbase) + (voff)[_i]), (LAS unsigned*)(lds + (bufoff) + ldsw + _i * 8192), 16, 0, 0); } while (0)
; #define PG8_LDA(dst, b, h) do { _Pragma("unroll") for (int m = 0; m < 4; ++m) _Pragma("unroll") for (int k = 0; k < 2; ++k) dst[m][k] = *(const LAS bf16x8*)(lds + PG8_SA(b, h) + aoff + m * 2048 + k * 1024); } while (0)
; #define PG8_LDB(dst, b, h) do { _Pragma("unroll") for (int n = 0; n < 2; ++n) _Pragma("unroll") for (int k = 0; k < 2; ++k) dst[n][k] = *(const LAS bf16x8*)(lds + PG8_SB(b, h) + boff + n * 2048 + k * 1024); } while (0)
; #define PG8_MMA(ai, bj, At, Bt) do { __builtin_amdgcn_s_setprio(1); _Pragma("unroll") for (int m = 0; m < 4; ++m) _Pragma("unroll") for (int n = 0; n < 2; ++n) _Pragma("unroll") for (int k = 0; k < 2; ++k) \
;         acc[ai][bj][m][n] = __builtin_amdgcn_mfma_f32_16x16x32_bf16(Bt[n][k], At[m][k], acc[ai][bj][m][n], 0, 0, 0); __builtin_amdgcn_s_setprio(0); } while (0)
; #define PG8_WAIT_V(n) asm volatile("s_waitcnt vmcnt(" #n ")" ::: "memory")
; #define PG8_WAIT_L(n) asm volatile("s_waitcnt lgkmcnt(" #n ")" ::: "memory")
; template <class Epi>
; DEV void gemm_phase(LAS unsigned char* lds, const Gemm g, const StaticOrder& S, const Epi& E) {
;     ...
;             const bool last = (t == nt - 2);
;             const char* a1 = cA + (size_t)(t + 1) * kstep;
;             const char* a2 = last ? nA : cA + (size_t)(t + 2) * kstep; const char* b2 = last ? nB : cB + (size_t)(t + 2) * kstep;
;             const char* a3 = a2 + kstep; const char* b3 = b2 + kstep;
;             PG8_LDB(B0, 0, 0); PG8_SCHED; PG8_LDA(At, 0, 0); PG8_STAGE(PG8_SA(1, 1), a1 + hstep, voffA);
;             PG8_WAIT_L(8); PG8_BAR; PG8_WAIT_L(0); PG8_MMA(0, 0, At, B0); PG8_BAR; PG8_SCHED;
;             PG8_LDB(B1, 0, 1); PG8_STAGE(PG8_SB(0, 0), b2, voffB);
;             PG8_BAR; PG8_WAIT_L(0); PG8_MMA(0, 1, At, B1); PG8_BAR;
;             PG8_LDA(At, 0, 1); PG8_STAGE(PG8_SA(0, 0), a2, voffA);
;             PG8_BAR; PG8_WAIT_L(0); PG8_MMA(1, 0, At, B0); PG8_BAR; PG8_SCHED;
;             PG8_STAGE(PG8_SB(0, 1), b2 + hstep, voffB);
;             PG8_WAIT_V(6); PG8_BAR; PG8_MMA(1, 1, At, B1); PG8_BAR;
;             PG8_LDB(B0, 1, 0); PG8_SCHED; PG8_LDA(At, 1, 0); PG8_STAGE(PG8_SA(0, 1), a2 + hstep, voffA);
.LBB0_755:
	s_add_u32 s22, s20, 0xfff80080
	s_addc_u32 s23, s21, -1
	s_add_i32 s47, 0, 0x10000
	v_add_u32_e32 v146, s47, v155
	ds_read_b128 v[128:131], v146
	ds_read_b128 v[132:135], v146 offset:1024
	ds_read_b128 v[150:153], v146 offset:2048
	ds_read_b128 v[174:177], v146 offset:3072
	s_cmp_eq_u32 s46, 28
	s_cselect_b32 s25, s5, s23
	s_cselect_b32 s24, s15, s22
	s_cselect_b32 s23, s11, s45
	s_cselect_b32 s22, s43, s44
	s_add_i32 m0, s34, 0xc000
	ds_read_b128 v[178:181], v167
	ds_read_b128 v[182:185], v167 offset:1024
	ds_read_b128 v[186:189], v167 offset:2048
	ds_read_b128 v[190:193], v167 offset:3072
	ds_read_b128 v[194:197], v167 offset:4096
	ds_read_b128 v[218:221], v167 offset:5120
	ds_read_b128 v[222:225], v167 offset:6144
	ds_read_b128 v[226:229], v167 offset:7168
	global_load_lds_dwordx4 v142, s[20:21]
	s_add_i32 m0, s34, 0xe000
	s_nop 0
	global_load_lds_dwordx4 v144, s[20:21]
	s_waitcnt lgkmcnt(8)
	s_barrier
	s_waitcnt lgkmcnt(0)
	v_mfma_f32_16x16x32_bf16 v[124:127], v[128:131], v[178:181], v[124:127]
	v_mfma_f32_16x16x32_bf16 v[116:119], v[150:153], v[178:181], v[116:119]
	v_mfma_f32_16x16x32_bf16 v[108:111], v[128:131], v[186:189], v[108:111]
	v_mfma_f32_16x16x32_bf16 v[100:103], v[150:153], v[186:189], v[100:103]
	v_mfma_f32_16x16x32_bf16 v[92:95], v[128:131], v[194:197], v[92:95]
	v_mfma_f32_16x16x32_bf16 v[84:87], v[150:153], v[194:197], v[84:87]
	v_mfma_f32_16x16x32_bf16 v[76:79], v[128:131], v[222:225], v[76:79]
	v_mfma_f32_16x16x32_bf16 v[68:71], v[150:153], v[222:225], v[68:71]
	v_mfma_f32_16x16x32_bf16 v[124:127], v[132:135], v[182:185], v[124:127]
	v_mfma_f32_16x16x32_bf16 v[116:119], v[174:177], v[182:185], v[116:119]
	v_mfma_f32_16x16x32_bf16 v[108:111], v[132:135], v[190:193], v[108:111]
	v_mfma_f32_16x16x32_bf16 v[100:103], v[174:177], v[190:193], v[100:103]
	v_mfma_f32_16x16x32_bf16 v[92:95], v[132:135], v[218:221], v[92:95]
	v_mfma_f32_16x16x32_bf16 v[84:87], v[174:177], v[218:221], v[84:87]
	v_mfma_f32_16x16x32_bf16 v[76:79], v[132:135], v[226:229], v[76:79]
	v_mfma_f32_16x16x32_bf16 v[68:71], v[174:177], v[226:229], v[68:71]
	s_barrier
	s_add_i32 s50, 0, 0x14000
	v_add_u32_e32 v146, s50, v155
	s_add_i32 s47, s47, s30
	ds_read_b128 v[230:233], v146
	ds_read_b128 v[234:237], v146 offset:1024
	ds_read_b128 v[238:241], v146 offset:2048
	ds_read_b128 v[242:245], v146 offset:3072
	v_lshl_add_u64 v[146:147], s[22:23], 0, v[160:161]
	s_mov_b32 m0, s47
	v_lshl_add_u64 v[158:159], s[22:23], 0, v[136:137]
	global_load_lds_dwordx4 v160, s[22:23]
	s_add_i32 m0, s47, 0x2000
	s_nop 0
	global_load_lds_dwordx4 v136, s[22:23]
	s_barrier
	s_waitcnt lgkmcnt(0)
	v_mfma_f32_16x16x32_bf16 v[120:123], v[230:233], v[178:181], v[120:123]
	v_mfma_f32_16x16x32_bf16 v[112:115], v[238:241], v[178:181], v[112:115]
	v_mfma_f32_16x16x32_bf16 v[104:107], v[230:233], v[186:189], v[104:107]
	v_mfma_f32_16x16x32_bf16 v[96:99], v[238:241], v[186:189], v[96:99]
	v_mfma_f32_16x16x32_bf16 v[88:91], v[230:233], v[194:197], v[88:91]
	v_mfma_f32_16x16x32_bf16 v[80:83], v[238:241], v[194:197], v[80:83]
	v_mfma_f32_16x16x32_bf16 v[72:75], v[230:233], v[222:225], v[72:75]
	v_mfma_f32_16x16x32_bf16 v[64:67], v[238:241], v[222:225], v[64:67]
	v_mfma_f32_16x16x32_bf16 v[120:123], v[234:237], v[182:185], v[120:123]
	v_mfma_f32_16x16x32_bf16 v[112:115], v[242:245], v[182:185], v[112:115]
	v_mfma_f32_16x16x32_bf16 v[104:107], v[234:237], v[190:193], v[104:107]
	v_mfma_f32_16x16x32_bf16 v[96:99], v[242:245], v[190:193], v[96:99]
	v_mfma_f32_16x16x32_bf16 v[88:91], v[234:237], v[218:221], v[88:91]
	v_mfma_f32_16x16x32_bf16 v[80:83], v[242:245], v[218:221], v[80:83]
	v_mfma_f32_16x16x32_bf16 v[72:75], v[234:237], v[226:229], v[72:75]
	v_mfma_f32_16x16x32_bf16 v[64:67], v[242:245], v[226:229], v[64:67]
	s_barrier
	s_mov_b32 m0, s34
	v_lshl_add_u64 v[214:215], s[24:25], 0, v[140:141]
	ds_read_b128 v[178:181], v167 offset:16384
	ds_read_b128 v[182:185], v167 offset:17408
	ds_read_b128 v[186:189], v167 offset:18432
	ds_read_b128 v[190:193], v167 offset:19456
	ds_read_b128 v[194:197], v167 offset:20480
	ds_read_b128 v[218:221], v167 offset:21504
	ds_read_b128 v[222:225], v167 offset:22528
	ds_read_b128 v[226:229], v167 offset:23552
	global_load_lds_dwordx4 v140, s[24:25]
	v_lshl_add_u64 v[216:217], s[24:25], 0, v[138:139]
	s_mov_b32 m0, s35
	s_nop 0
	global_load_lds_dwordx4 v138, s[24:25]
	s_barrier
	s_waitcnt lgkmcnt(0)
	v_mfma_f32_16x16x32_bf16 v[60:63], v[128:131], v[178:181], v[60:63]
	v_mfma_f32_16x16x32_bf16 v[52:55], v[150:153], v[178:181], v[52:55]
	v_mfma_f32_16x16x32_bf16 v[44:47], v[128:131], v[186:189], v[44:47]
	v_mfma_f32_16x16x32_bf16 v[36:39], v[150:153], v[186:189], v[36:39]
	v_mfma_f32_16x16x32_bf16 v[28:31], v[128:131], v[194:197], v[28:31]
	v_mfma_f32_16x16x32_bf16 v[20:23], v[150:153], v[194:197], v[20:23]
	v_mfma_f32_16x16x32_bf16 v[12:15], v[128:131], v[222:225], v[12:15]
	v_mfma_f32_16x16x32_bf16 v[4:7], v[150:153], v[222:225], v[4:7]
	v_mfma_f32_16x16x32_bf16 v[60:63], v[132:135], v[182:185], v[60:63]
	v_mfma_f32_16x16x32_bf16 v[52:55], v[174:177], v[182:185], v[52:55]
	v_mfma_f32_16x16x32_bf16 v[44:47], v[132:135], v[190:193], v[44:47]
	v_mfma_f32_16x16x32_bf16 v[36:39], v[174:177], v[190:193], v[36:39]
	v_mfma_f32_16x16x32_bf16 v[28:31], v[132:135], v[218:221], v[28:31]
	v_mfma_f32_16x16x32_bf16 v[20:23], v[174:177], v[218:221], v[20:23]
	v_mfma_f32_16x16x32_bf16 v[12:15], v[132:135], v[226:229], v[12:15]
	v_mfma_f32_16x16x32_bf16 v[4:7], v[174:177], v[226:229], v[4:7]
	s_barrier
	s_add_u32 s48, s22, 0x80000
	s_addc_u32 s49, s23, 0
	s_add_i32 s47, s50, s30
	s_mov_b32 m0, s47
	s_nop 0
	global_load_lds_dwordx4 v160, s[48:49]
	s_add_i32 m0, s47, 0x2000
	s_nop 0
	global_load_lds_dwordx4 v136, s[48:49]
	s_waitcnt vmcnt(6)
	s_barrier
; #define PG8_STAGE(bufoff, gbase, voff) do { _Pragma("unroll") for (int _i = 0; _i < 2; ++_i) \
;         __builtin_amdgcn_global_load_lds((const unsigned*)((const char*)(gbase) + (voff)[_i]), (LAS unsigned*)(lds + (bufoff) + ldsw + _i * 8192), 16, 0, 0); } while (0)
; #define PG8_LDA(dst, b, h) do { _Pragma("unroll") for (int m = 0; m < 4; ++m) _Pragma("unroll") for (int k = 0; k < 2; ++k) dst[m][k] = *(const LAS bf16x8*)(lds + PG8_SA(b, h) + aoff + m * 2048 + k * 1024); } while (0)
; #define PG8_LDB(dst, b, h) do { _Pragma("unroll") for (int n = 0; n < 2; ++n) _Pragma("unroll") for (int k = 0; k < 2; ++k) dst[n][k] = *(const LAS bf16x8*)(lds + PG8_SB(b, h) + boff + n * 2048 + k * 1024); } while (0)
; #define PG8_MMA(ai, bj, At, Bt) do { __builtin_amdgcn_s_setprio(1); _Pragma("unroll") for (int m = 0; m < 4; ++m) _Pragma("unroll") for (int n = 0; n < 2; ++n) _Pragma("unroll") for (int k = 0; k < 2; ++k) \
;         acc[ai][bj][m][n] = __builtin_amdgcn_mfma_f32_16x16x32_bf16(Bt[n][k], At[m][k], acc[ai][bj][m][n], 0, 0, 0); __builtin_amdgcn_s_setprio(0); } while (0)
; #define PG8_WAIT_V(n) asm volatile("s_waitcnt vmcnt(" #n ")" ::: "memory")
; #define PG8_WAIT_L(n) asm volatile("s_waitcnt lgkmcnt(" #n ")" ::: "memory")
; #define PG8_BAR __builtin_amdgcn_s_barrier()
; #define PG8_SCHED __builtin_amdgcn_sched_barrier(0)
; template <class Epi>
; DEV void gemm_phase(LAS unsigned char* lds, const Gemm g, const StaticOrder& S, const Epi& E) {
;     ...
;             PG8_WAIT_V(6); PG8_BAR; PG8_MMA(1, 1, At, B1); PG8_BAR;
;             PG8_LDB(B0, 1, 0); PG8_SCHED; PG8_LDA(At, 1, 0); PG8_STAGE(PG8_SA(0, 1), a2 + hstep, voffA);
;             PG8_WAIT_L(8); PG8_BAR; PG8_WAIT_L(0); PG8_MMA(0, 0, At, B0); PG8_BAR; PG8_SCHED;
;             PG8_LDB(B1, 1, 1); PG8_STAGE(PG8_SB(1, 0), b3, voffB);
;             PG8_BAR; PG8_WAIT_L(0); PG8_MMA(0, 1, At, B1); PG8_BAR;
;             PG8_LDA(At, 1, 1); PG8_STAGE(PG8_SA(1, 0), a3, voffA);
	v_mfma_f32_16x16x32_bf16 v[56:59], v[230:233], v[178:181], v[56:59]
	v_mfma_f32_16x16x32_bf16 v[48:51], v[238:241], v[178:181], v[48:51]
	v_mfma_f32_16x16x32_bf16 v[40:43], v[230:233], v[186:189], v[40:43]
	v_mfma_f32_16x16x32_bf16 v[32:35], v[238:241], v[186:189], v[32:35]
	v_mfma_f32_16x16x32_bf16 v[24:27], v[230:233], v[194:197], v[24:27]
	v_mfma_f32_16x16x32_bf16 v[16:19], v[238:241], v[194:197], v[16:19]
	v_mfma_f32_16x16x32_bf16 v[8:11], v[230:233], v[222:225], v[8:11]
	v_mfma_f32_16x16x32_bf16 v[0:3], v[238:241], v[222:225], v[0:3]
	v_mfma_f32_16x16x32_bf16 v[56:59], v[234:237], v[182:185], v[56:59]
	v_mfma_f32_16x16x32_bf16 v[48:51], v[242:245], v[182:185], v[48:51]
	v_mfma_f32_16x16x32_bf16 v[40:43], v[234:237], v[190:193], v[40:43]
	v_mfma_f32_16x16x32_bf16 v[32:35], v[242:245], v[190:193], v[32:35]
	v_mfma_f32_16x16x32_bf16 v[24:27], v[234:237], v[218:221], v[24:27]
	v_mfma_f32_16x16x32_bf16 v[16:19], v[242:245], v[218:221], v[16:19]
	v_mfma_f32_16x16x32_bf16 v[8:11], v[234:237], v[226:229], v[8:11]
	v_mfma_f32_16x16x32_bf16 v[0:3], v[242:245], v[226:229], v[0:3]
	s_barrier
	s_add_i32 s47, 0, 0x18000
	v_add_u32_e32 v148, s47, v155
	ds_read_b128 v[128:131], v148
	ds_read_b128 v[132:135], v148 offset:1024
	ds_read_b128 v[150:153], v148 offset:2048
	ds_read_b128 v[174:177], v148 offset:3072
	s_add_u32 s24, s24, 0x80000
	s_addc_u32 s25, s25, 0
	s_mov_b32 m0, s36
	ds_read_b128 v[178:181], v167 offset:32768
	ds_read_b128 v[182:185], v167 offset:33792
	ds_read_b128 v[186:189], v167 offset:34816
	ds_read_b128 v[190:193], v167 offset:35840
	ds_read_b128 v[194:197], v167 offset:36864
	ds_read_b128 v[218:221], v167 offset:37888
	ds_read_b128 v[222:225], v167 offset:38912
	ds_read_b128 v[226:229], v167 offset:39936
	global_load_lds_dwordx4 v140, s[24:25]
	s_mov_b32 m0, s37
	s_nop 0
	global_load_lds_dwordx4 v138, s[24:25]
	s_waitcnt lgkmcnt(8)
	s_barrier
	s_waitcnt lgkmcnt(0)
	v_mfma_f32_16x16x32_bf16 v[124:127], v[128:131], v[178:181], v[124:127]
	v_mfma_f32_16x16x32_bf16 v[116:119], v[150:153], v[178:181], v[116:119]
	v_mfma_f32_16x16x32_bf16 v[108:111], v[128:131], v[186:189], v[108:111]
	v_mfma_f32_16x16x32_bf16 v[100:103], v[150:153], v[186:189], v[100:103]
	v_mfma_f32_16x16x32_bf16 v[92:95], v[128:131], v[194:197], v[92:95]
	v_mfma_f32_16x16x32_bf16 v[84:87], v[150:153], v[194:197], v[84:87]
	v_mfma_f32_16x16x32_bf16 v[76:79], v[128:131], v[222:225], v[76:79]
	v_mfma_f32_16x16x32_bf16 v[68:71], v[150:153], v[222:225], v[68:71]
	v_mfma_f32_16x16x32_bf16 v[124:127], v[132:135], v[182:185], v[124:127]
	v_mfma_f32_16x16x32_bf16 v[116:119], v[174:177], v[182:185], v[116:119]
	v_mfma_f32_16x16x32_bf16 v[108:111], v[132:135], v[190:193], v[108:111]
	v_mfma_f32_16x16x32_bf16 v[100:103], v[174:177], v[190:193], v[100:103]
	v_mfma_f32_16x16x32_bf16 v[92:95], v[132:135], v[218:221], v[92:95]
	v_mfma_f32_16x16x32_bf16 v[84:87], v[174:177], v[218:221], v[84:87]
	v_mfma_f32_16x16x32_bf16 v[76:79], v[132:135], v[226:229], v[76:79]
	v_mfma_f32_16x16x32_bf16 v[68:71], v[174:177], v[226:229], v[68:71]
	s_barrier
	s_add_i32 s24, 0, 0x1c000
	s_add_i32 s25, s47, s30
	v_add_u32_e32 v148, s24, v155
	v_lshl_add_u64 v[146:147], v[146:147], 0, s[2:3]
	s_mov_b32 m0, s25
	ds_read_b128 v[230:233], v148
	ds_read_b128 v[234:237], v148 offset:1024
	ds_read_b128 v[238:241], v148 offset:2048
	ds_read_b128 v[242:245], v148 offset:3072
	global_load_lds_dwordx4 v[146:147], off
	v_lshl_add_u64 v[146:147], v[158:159], 0, s[2:3]
	s_add_i32 m0, s25, 0x2000
	s_nop 0
	global_load_lds_dwordx4 v[146:147], off
	s_barrier
	s_waitcnt lgkmcnt(0)
	v_mfma_f32_16x16x32_bf16 v[120:123], v[230:233], v[178:181], v[120:123]
	v_mfma_f32_16x16x32_bf16 v[112:115], v[238:241], v[178:181], v[112:115]
	v_mfma_f32_16x16x32_bf16 v[104:107], v[230:233], v[186:189], v[104:107]
	v_mfma_f32_16x16x32_bf16 v[96:99], v[238:241], v[186:189], v[96:99]
	v_mfma_f32_16x16x32_bf16 v[88:91], v[230:233], v[194:197], v[88:91]
	v_mfma_f32_16x16x32_bf16 v[80:83], v[238:241], v[194:197], v[80:83]
	v_mfma_f32_16x16x32_bf16 v[72:75], v[230:233], v[222:225], v[72:75]
	v_mfma_f32_16x16x32_bf16 v[64:67], v[238:241], v[222:225], v[64:67]
	v_mfma_f32_16x16x32_bf16 v[120:123], v[234:237], v[182:185], v[120:123]
	v_mfma_f32_16x16x32_bf16 v[112:115], v[242:245], v[182:185], v[112:115]
	v_mfma_f32_16x16x32_bf16 v[104:107], v[234:237], v[190:193], v[104:107]
	v_mfma_f32_16x16x32_bf16 v[96:99], v[242:245], v[190:193], v[96:99]
	v_mfma_f32_16x16x32_bf16 v[88:91], v[234:237], v[218:221], v[88:91]
	v_mfma_f32_16x16x32_bf16 v[80:83], v[242:245], v[218:221], v[80:83]
	v_mfma_f32_16x16x32_bf16 v[72:75], v[234:237], v[226:229], v[72:75]
	v_mfma_f32_16x16x32_bf16 v[64:67], v[242:245], v[226:229], v[64:67]
	s_barrier
	s_mov_b32 m0, s38
	v_lshl_add_u64 v[146:147], v[214:215], 0, s[2:3]
	ds_read_b128 v[178:181], v167 offset:49152
	ds_read_b128 v[182:185], v167 offset:50176
	ds_read_b128 v[186:189], v167 offset:51200
	ds_read_b128 v[190:193], v167 offset:52224
	ds_read_b128 v[194:197], v167 offset:53248
	ds_read_b128 v[218:221], v167 offset:54272
	ds_read_b128 v[222:225], v167 offset:55296
	ds_read_b128 v[226:229], v167 offset:56320
	global_load_lds_dwordx4 v[146:147], off
	v_lshl_add_u64 v[146:147], v[216:217], 0, s[2:3]
	s_mov_b32 m0, s39
	s_nop 0
	global_load_lds_dwordx4 v[146:147], off
	s_barrier
; #define PG8_STAGE(bufoff, gbase, voff) do { _Pragma("unroll") for (int _i = 0; _i < 2; ++_i) \
;         __builtin_amdgcn_global_load_lds((const unsigned*)((const char*)(gbase) + (voff)[_i]), (LAS unsigned*)(lds + (bufoff) + ldsw + _i * 8192), 16, 0, 0); } while (0)
; #define PG8_MMA(ai, bj, At, Bt) do { __builtin_amdgcn_s_setprio(1); _Pragma("unroll") for (int m = 0; m < 4; ++m) _Pragma("unroll") for (int n = 0; n < 2; ++n) _Pragma("unroll") for (int k = 0; k < 2; ++k) \
;         acc[ai][bj][m][n] = __builtin_amdgcn_mfma_f32_16x16x32_bf16(Bt[n][k], At[m][k], acc[ai][bj][m][n], 0, 0, 0); __builtin_amdgcn_s_setprio(0); } while (0)
; #define PG8_WAIT_V(n) asm volatile("s_waitcnt vmcnt(" #n ")" ::: "memory")
; #define PG8_WAIT_L(n) asm volatile("s_waitcnt lgkmcnt(" #n ")" ::: "memory")
; #define PG8_BAR __builtin_amdgcn_s_barrier()
; #define PG8_SCHED __builtin_amdgcn_sched_barrier(0)
; template <class Epi>
; DEV void gemm_phase(LAS unsigned char* lds, const Gemm g, const StaticOrder& S, const Epi& E) {
;     ...
;             PG8_BAR; PG8_WAIT_L(0); PG8_MMA(1, 0, At, B0); PG8_BAR; PG8_SCHED;
;             PG8_STAGE(PG8_SB(1, 1), b3 + hstep, voffB);
;             PG8_WAIT_V(6); PG8_BAR; PG8_MMA(1, 1, At, B1); PG8_BAR;
;         }
;         E(acc, cur, wr, wc, fr, fq);
;     DEV void operator()(AccRef acc, const pg8::Unit& u, int wr, int wc, int fr, int fq) const {
;         const int row0 = u.pm * 256 + wr * 64 + fr, col0 = u.pn * 128 + wc * 32 + 8 * fq;
;         float rsv[2][4];
; #pragma unroll
;         for (int ai = 0; ai < 2; ++ai)
; #pragma unroll
;             for (int m = 0; m < 4; ++m) rsv[ai][m] = rowscale(ss, row0 + ai * 128 + m * 16);
; #pragma unroll
;         for (int ai = 0; ai < 2; ++ai)
; #pragma unroll
;             for (int m = 0; m < 4; ++m) { u16* rowp = O + (size_t)(row0 + ai * 128 + m * 16) * 5632 + col0; const float rs = rsv[ai][m]; f32x4 r[2];
; #pragma unroll
;                 for (int n = 0; n < 2; ++n) { const f32x4 g = acc[ai][0][m][n] * rs, uu = acc[ai][1][m][n] * rs;
	s_waitcnt lgkmcnt(0)
	v_mfma_f32_16x16x32_bf16 v[60:63], v[128:131], v[178:181], v[60:63]
	v_mfma_f32_16x16x32_bf16 v[52:55], v[150:153], v[178:181], v[52:55]
	v_mfma_f32_16x16x32_bf16 v[44:47], v[128:131], v[186:189], v[44:47]
	v_mfma_f32_16x16x32_bf16 v[36:39], v[150:153], v[186:189], v[36:39]
	v_mfma_f32_16x16x32_bf16 v[28:31], v[128:131], v[194:197], v[28:31]
	v_mfma_f32_16x16x32_bf16 v[20:23], v[150:153], v[194:197], v[20:23]
	v_mfma_f32_16x16x32_bf16 v[12:15], v[128:131], v[222:225], v[12:15]
	v_mfma_f32_16x16x32_bf16 v[4:7], v[150:153], v[222:225], v[4:7]
	v_mfma_f32_16x16x32_bf16 v[60:63], v[132:135], v[182:185], v[60:63]
	v_mfma_f32_16x16x32_bf16 v[52:55], v[174:177], v[182:185], v[52:55]
	v_mfma_f32_16x16x32_bf16 v[44:47], v[132:135], v[190:193], v[44:47]
	v_mfma_f32_16x16x32_bf16 v[36:39], v[174:177], v[190:193], v[36:39]
	v_mfma_f32_16x16x32_bf16 v[28:31], v[132:135], v[218:221], v[28:31]
	v_mfma_f32_16x16x32_bf16 v[20:23], v[174:177], v[218:221], v[20:23]
	v_mfma_f32_16x16x32_bf16 v[12:15], v[132:135], v[226:229], v[12:15]
	v_mfma_f32_16x16x32_bf16 v[4:7], v[174:177], v[226:229], v[4:7]
	s_barrier
	s_add_u32 s22, s22, 0x80080
	s_addc_u32 s23, s23, 0
	s_add_i32 s24, s24, s30
	s_mov_b32 m0, s24
	s_nop 0
	global_load_lds_dwordx4 v160, s[22:23]
	s_add_i32 m0, s24, 0x2000
	s_nop 0
	global_load_lds_dwordx4 v136, s[22:23]
	s_waitcnt vmcnt(6)
	s_barrier
	v_mfma_f32_16x16x32_bf16 v[56:59], v[230:233], v[178:181], v[56:59]
	v_mfma_f32_16x16x32_bf16 v[48:51], v[238:241], v[178:181], v[48:51]
	v_mfma_f32_16x16x32_bf16 v[40:43], v[230:233], v[186:189], v[40:43]
	v_mfma_f32_16x16x32_bf16 v[32:35], v[238:241], v[186:189], v[32:35]
	v_mfma_f32_16x16x32_bf16 v[24:27], v[230:233], v[194:197], v[24:27]
	v_mfma_f32_16x16x32_bf16 v[16:19], v[238:241], v[194:197], v[16:19]
	v_mfma_f32_16x16x32_bf16 v[8:11], v[230:233], v[222:225], v[8:11]
	v_mfma_f32_16x16x32_bf16 v[0:3], v[238:241], v[222:225], v[0:3]
	v_mfma_f32_16x16x32_bf16 v[56:59], v[234:237], v[182:185], v[56:59]
	v_mfma_f32_16x16x32_bf16 v[48:51], v[242:245], v[182:185], v[48:51]
	v_mfma_f32_16x16x32_bf16 v[40:43], v[234:237], v[190:193], v[40:43]
	v_mfma_f32_16x16x32_bf16 v[32:35], v[242:245], v[190:193], v[32:35]
	v_mfma_f32_16x16x32_bf16 v[24:27], v[234:237], v[218:221], v[24:27]
	v_mfma_f32_16x16x32_bf16 v[16:19], v[242:245], v[218:221], v[16:19]
	v_mfma_f32_16x16x32_bf16 v[8:11], v[234:237], v[226:229], v[8:11]
	v_mfma_f32_16x16x32_bf16 v[0:3], v[242:245], v[226:229], v[0:3]
	s_add_i32 s46, s46, 2
	s_add_u32 s20, s20, 0x100
	s_addc_u32 s21, s21, 0
	s_add_u32 s44, s44, 0x100
	s_addc_u32 s45, s45, 0
	s_cmp_gt_u32 s46, 29
	s_barrier
	s_cbranch_scc0 .LBB0_755
	v_lshl_add_u32 v186, s4, 8, v149
	v_ashrrev_i32_e32 v187, 31, v186
	v_lshlrev_b64 v[146:147], 5, v[186:187]
	v_lshl_add_u64 v[146:147], s[8:9], 0, v[146:147]
	v_add_co_u32_e32 v158, vcc, 0x1000, v146
	global_load_dwordx4 v[218:221], v[146:147], off
	global_load_dwordx4 v[222:225], v[146:147], off offset:16
	v_addc_co_u32_e32 v159, vcc, 0, v147, vcc
	global_load_dwordx4 v[174:177], v[146:147], off offset:512
	global_load_dwordx4 v[230:233], v[146:147], off offset:528
	global_load_dwordx4 v[234:237], v[146:147], off offset:1024
	global_load_dwordx4 v[238:241], v[146:147], off offset:1040
	global_load_dwordx4 v[242:245], v[146:147], off offset:1536
	global_load_dwordx4 v[246:249], v[146:147], off offset:1552
	global_load_dwordx4 v[190:193], v[158:159], off
	global_load_dwordx4 v[194:197], v[158:159], off offset:16
	global_load_dwordx4 v[214:217], v[158:159], off offset:512
	global_load_dwordx4 v[132:135], v[158:159], off offset:528
	global_load_dwordx4 v[150:153], v[158:159], off offset:1024
	global_load_dwordx4 v[128:131], v[158:159], off offset:1040
	global_load_dwordx4 v[226:229], v[158:159], off offset:1536
	global_load_dwordx4 v[180:183], v[158:159], off offset:1552
	s_mov_b32 s12, 0x3a000000
	s_mov_b64 s[22:23], s[18:19]
	s_mov_b64 s[20:21], s[16:17]
	s_movk_i32 s11, 0x2c00
	v_readlane_b32 s4, v250, 11
	v_readlane_b32 s5, v250, 12
	s_waitcnt vmcnt(14)
	v_add_f32_e32 v218, v218, v219
	v_add_f32_e32 v220, v220, v221
	v_add_f32_e32 v222, v222, v223
	v_add_f32_e32 v224, v224, v225
	v_add_f32_e32 v218, v218, v220
	v_add_f32_e32 v218, v218, v222
	v_add_f32_e32 v218, v218, v224
	v_fmamk_f32 v218, v218, 0x3a000000, v199
	v_rsq_f32_e32 v184, v218
	s_waitcnt vmcnt(12)
	v_add_f32_e32 v174, v174, v175
	v_add_f32_e32 v176, v176, v177
	v_add_f32_e32 v230, v230, v231
	v_add_f32_e32 v232, v232, v233
	v_add_f32_e32 v174, v174, v176
	v_add_f32_e32 v174, v174, v230
	v_add_f32_e32 v174, v174, v232
	v_fmamk_f32 v174, v174, 0x3a000000, v199
	v_rsq_f32_e32 v176, v174
	v_pk_mul_f32 v[124:125], v[124:125], v[184:185] op_sel_hi:[1,0]
	v_pk_mul_f32 v[120:121], v[120:121], v[184:185] op_sel_hi:[1,0]
	v_pk_mul_f32 v[122:123], v[122:123], v[184:185] op_sel_hi:[1,0]
	v_pk_mul_f32 v[116:117], v[116:117], v[184:185] op_sel_hi:[1,0]
	v_pk_mul_f32 v[112:113], v[112:113], v[184:185] op_sel_hi:[1,0]
	v_pk_mul_f32 v[114:115], v[114:115], v[184:185] op_sel_hi:[1,0]
	s_waitcnt vmcnt(10)
	v_add_f32_e32 v234, v234, v235
	v_add_f32_e32 v236, v236, v237
	v_add_f32_e32 v238, v238, v239
	v_add_f32_e32 v240, v240, v241
	v_add_f32_e32 v234, v234, v236
	v_add_f32_e32 v234, v234, v238
	v_add_f32_e32 v234, v234, v240
	v_fmamk_f32 v234, v234, 0x3a000000, v199
	v_rsq_f32_e32 v178, v234
	v_pk_mul_f32 v[108:109], v[108:109], v[176:177] op_sel_hi:[1,0]
	v_pk_mul_f32 v[104:105], v[104:105], v[176:177] op_sel_hi:[1,0]
	v_pk_mul_f32 v[106:107], v[106:107], v[176:177] op_sel_hi:[1,0]
	v_pk_mul_f32 v[100:101], v[100:101], v[176:177] op_sel_hi:[1,0]
	v_pk_mul_f32 v[96:97], v[96:97], v[176:177] op_sel_hi:[1,0]
	v_pk_mul_f32 v[98:99], v[98:99], v[176:177] op_sel_hi:[1,0]
	s_waitcnt vmcnt(8)
; DEV float siluf(float x) { return x * __builtin_amdgcn_rcpf(1.0f + __builtin_amdgcn_exp2f(x * -1.4426950408889634f)); }
; DEV bf16x8 pack8(f32x4 a, f32x4 b) { u32x4 w; w.x = cvt_pk_bf16(a[0], a[1]); w.y = cvt_pk_bf16(a[2], a[3]); w.z = cvt_pk_bf16(b[0], b[1]); w.w = cvt_pk_bf16(b[2], b[3]); return __builtin_bit_cast(bf16x8, w); }
;     DEV void operator()(AccRef acc, const pg8::Unit& u, int wr, int wc, int fr, int fq) const {
;         const int row0 = u.pm * 256 + wr * 64 + fr, col0 = u.pn * 128 + wc * 32 + 8 * fq;
;         float rsv[2][4];
; #pragma unroll
;         for (int ai = 0; ai < 2; ++ai)
; #pragma unroll
;             for (int m = 0; m < 4; ++m) rsv[ai][m] = rowscale(ss, row0 + ai * 128 + m * 16);
; #pragma unroll
;         for (int ai = 0; ai < 2; ++ai)
; #pragma unroll
;             for (int m = 0; m < 4; ++m) { u16* rowp = O + (size_t)(row0 + ai * 128 + m * 16) * 5632 + col0; const float rs = rsv[ai][m]; f32x4 r[2];
; #pragma unroll
;                 for (int n = 0; n < 2; ++n) { const f32x4 g = acc[ai][0][m][n] * rs, uu = acc[ai][1][m][n] * rs;
; #pragma unroll
;                     for (int e = 0; e < 4; ++e) r[n][e] = siluf(g[e]) * uu[e]; }
;                 *(u32x4*)rowp = __builtin_bit_cast(u32x4, pack8(r[0], r[1])); }
	v_add_f32_e32 v242, v242, v243
	v_add_f32_e32 v244, v244, v245
	v_add_f32_e32 v246, v246, v247
	v_add_f32_e32 v248, v248, v249
	v_add_f32_e32 v242, v242, v244
	v_add_f32_e32 v242, v242, v246
	v_add_f32_e32 v242, v242, v248
	v_fmamk_f32 v242, v242, 0x3a000000, v199
	v_rsq_f32_e32 v154, v242
	v_pk_mul_f32 v[92:93], v[92:93], v[178:179] op_sel_hi:[1,0]
	v_pk_mul_f32 v[88:89], v[88:89], v[178:179] op_sel_hi:[1,0]
	v_pk_mul_f32 v[90:91], v[90:91], v[178:179] op_sel_hi:[1,0]
	v_pk_mul_f32 v[84:85], v[84:85], v[178:179] op_sel_hi:[1,0]
	v_pk_mul_f32 v[80:81], v[80:81], v[178:179] op_sel_hi:[1,0]
	v_pk_mul_f32 v[82:83], v[82:83], v[178:179] op_sel_hi:[1,0]
	s_waitcnt vmcnt(6)
	v_add_f32_e32 v190, v190, v191
	v_add_f32_e32 v192, v192, v193
	v_add_f32_e32 v194, v194, v195
	v_add_f32_e32 v196, v196, v197
	v_add_f32_e32 v190, v190, v192
	v_add_f32_e32 v190, v190, v194
	v_add_f32_e32 v190, v190, v196
	v_fmamk_f32 v190, v190, 0x3a000000, v199
	v_rsq_f32_e32 v156, v190
	v_pk_mul_f32 v[76:77], v[76:77], v[154:155] op_sel_hi:[1,0]
	v_pk_mul_f32 v[72:73], v[72:73], v[154:155] op_sel_hi:[1,0]
	v_pk_mul_f32 v[74:75], v[74:75], v[154:155] op_sel_hi:[1,0]
	v_pk_mul_f32 v[68:69], v[68:69], v[154:155] op_sel_hi:[1,0]
	v_pk_mul_f32 v[64:65], v[64:65], v[154:155] op_sel_hi:[1,0]
	v_pk_mul_f32 v[66:67], v[66:67], v[154:155] op_sel_hi:[1,0]
	s_waitcnt vmcnt(4)
	v_add_f32_e32 v214, v214, v215
	v_add_f32_e32 v216, v216, v217
	v_add_f32_e32 v132, v132, v133
	v_add_f32_e32 v134, v134, v135
	v_add_f32_e32 v214, v214, v216
	v_add_f32_e32 v214, v214, v132
	v_add_f32_e32 v214, v214, v134
	v_fmamk_f32 v214, v214, 0x3a000000, v199
	v_rsq_f32_e32 v148, v214
	v_pk_mul_f32 v[60:61], v[60:61], v[156:157] op_sel_hi:[1,0]
	v_pk_mul_f32 v[56:57], v[56:57], v[156:157] op_sel_hi:[1,0]
	v_pk_mul_f32 v[58:59], v[58:59], v[156:157] op_sel_hi:[1,0]
	v_pk_mul_f32 v[52:53], v[52:53], v[156:157] op_sel_hi:[1,0]
	v_pk_mul_f32 v[48:49], v[48:49], v[156:157] op_sel_hi:[1,0]
	v_pk_mul_f32 v[50:51], v[50:51], v[156:157] op_sel_hi:[1,0]
	s_waitcnt vmcnt(2)
	v_add_f32_e32 v150, v150, v151
	v_add_f32_e32 v152, v152, v153
	v_add_f32_e32 v128, v128, v129
	v_add_f32_e32 v130, v130, v131
	v_add_f32_e32 v150, v150, v152
	v_add_f32_e32 v150, v150, v128
	v_add_f32_e32 v150, v150, v130
	v_fmamk_f32 v150, v150, 0x3a000000, v199
	v_rsq_f32_e32 v130, v150
	v_pk_mul_f32 v[44:45], v[44:45], v[148:149] op_sel_hi:[1,0]
	v_pk_mul_f32 v[40:41], v[40:41], v[148:149] op_sel_hi:[1,0]
	v_pk_mul_f32 v[42:43], v[42:43], v[148:149] op_sel_hi:[1,0]
	v_pk_mul_f32 v[36:37], v[36:37], v[148:149] op_sel_hi:[1,0]
	v_pk_mul_f32 v[32:33], v[32:33], v[148:149] op_sel_hi:[1,0]
	v_pk_mul_f32 v[34:35], v[34:35], v[148:149] op_sel_hi:[1,0]
	s_waitcnt vmcnt(0)
	v_add_f32_e32 v226, v226, v227
	v_add_f32_e32 v228, v228, v229
	v_add_f32_e32 v180, v180, v181
	v_add_f32_e32 v182, v182, v183
	v_add_f32_e32 v226, v226, v228
	v_add_f32_e32 v226, v226, v180
	v_add_f32_e32 v226, v226, v182
	v_fmamk_f32 v226, v226, 0x3a000000, v199
	v_rsq_f32_e32 v128, v226
	v_pk_mul_f32 v[28:29], v[28:29], v[130:131] op_sel_hi:[1,0]
	v_or_b32_e32 v182, 16, v186
	v_ashrrev_i32_e32 v183, 31, v182
	v_or_b32_e32 v180, 32, v186
	v_ashrrev_i32_e32 v181, 31, v180
	v_or_b32_e32 v174, 48, v186
	v_ashrrev_i32_e32 v175, 31, v174
	v_add_u32_e32 v158, 0x80, v186
	v_ashrrev_i32_e32 v159, 31, v158
	v_add_u32_e32 v152, 0x90, v186
	v_ashrrev_i32_e32 v153, 31, v152
	v_add_u32_e32 v150, 0xa0, v186
	v_ashrrev_i32_e32 v151, 31, v150
	v_add_u32_e32 v146, 0xb0, v186
	v_ashrrev_i32_e32 v147, 31, v146
	v_lshl_or_b32 v134, s42, 7, v157
	v_ashrrev_i32_e32 v135, 31, v134
	s_mov_b32 s42, s10
	v_mul_f32_e32 v129, 0xbfb8aa3b, v124
	v_exp_f32_e32 v129, v129
	v_mov_b64_e32 v[132:133], s[4:5]
	v_mad_i64_i32 v[186:187], s[4:5], v186, s11, v[132:133]
	v_add_f32_e32 v129, 1.0, v129
	v_rcp_f32_e32 v188, v129
	v_mul_f32_e32 v129, 0xbfb8aa3b, v125
	v_exp_f32_e32 v129, v129
	v_pk_mul_f32 v[24:25], v[24:25], v[130:131] op_sel_hi:[1,0]
	v_pk_mul_f32 v[26:27], v[26:27], v[130:131] op_sel_hi:[1,0]
	v_pk_mul_f32 v[20:21], v[20:21], v[130:131] op_sel_hi:[1,0]
	v_add_f32_e32 v129, 1.0, v129
	v_rcp_f32_e32 v189, v129
	v_pk_mul_f32 v[16:17], v[16:17], v[130:131] op_sel_hi:[1,0]
	v_pk_mul_f32 v[18:19], v[18:19], v[130:131] op_sel_hi:[1,0]
	v_pk_mul_f32 v[12:13], v[12:13], v[128:129] op_sel_hi:[1,0]
	v_pk_mul_f32 v[124:125], v[124:125], v[188:189]
	v_pk_mul_f32 v[8:9], v[8:9], v[128:129] op_sel_hi:[1,0]
	v_pk_mul_f32 v[120:121], v[120:121], v[124:125]
	v_pk_mul_f32 v[124:125], v[126:127], v[184:185] op_sel_hi:[1,0]
	v_pk_mul_f32 v[10:11], v[10:11], v[128:129] op_sel_hi:[1,0]
	v_mul_f32_e32 v126, 0xbfb8aa3b, v124
	v_mul_f32_e32 v127, 0xbfb8aa3b, v125
	v_exp_f32_e32 v126, v126
	v_exp_f32_e32 v127, v127
	v_pk_mul_f32 v[4:5], v[4:5], v[128:129] op_sel_hi:[1,0]
	v_pk_mul_f32 v[0:1], v[0:1], v[128:129] op_sel_hi:[1,0]
	v_add_f32_e32 v126, 1.0, v126
	v_add_f32_e32 v127, 1.0, v127
	v_rcp_f32_e32 v126, v126
	v_rcp_f32_e32 v127, v127
	v_pk_mul_f32 v[2:3], v[2:3], v[128:129] op_sel_hi:[1,0]
	s_and_b64 vcc, exec, s[0:1]
	v_pk_mul_f32 v[124:125], v[124:125], v[126:127]
	s_nop 0
	v_pk_mul_f32 v[122:123], v[122:123], v[124:125]
	v_mul_f32_e32 v124, 0xbfb8aa3b, v116
	v_mul_f32_e32 v125, 0xbfb8aa3b, v117
	v_exp_f32_e32 v124, v124
	v_exp_f32_e32 v125, v125
	v_add_f32_e32 v124, 1.0, v124
	v_add_f32_e32 v125, 1.0, v125
	v_rcp_f32_e32 v124, v124
	v_rcp_f32_e32 v125, v125
	s_nop 0
	v_pk_mul_f32 v[116:117], v[116:117], v[124:125]
	s_nop 0
	v_pk_mul_f32 v[116:117], v[112:113], v[116:117]
	v_pk_mul_f32 v[112:113], v[118:119], v[184:185] op_sel_hi:[1,0]
	v_cvt_pk_bf16_f32 v116, v116, v117
	v_mul_f32_e32 v118, 0xbfb8aa3b, v112
; DEV float siluf(float x) { return x * __builtin_amdgcn_rcpf(1.0f + __builtin_amdgcn_exp2f(x * -1.4426950408889634f)); }
; DEV bf16x8 pack8(f32x4 a, f32x4 b) { u32x4 w; w.x = cvt_pk_bf16(a[0], a[1]); w.y = cvt_pk_bf16(a[2], a[3]); w.z = cvt_pk_bf16(b[0], b[1]); w.w = cvt_pk_bf16(b[2], b[3]); return __builtin_bit_cast(bf16x8, w); }
;     DEV void operator()(AccRef acc, const pg8::Unit& u, int wr, int wc, int fr, int fq) const {
;     ...
;             for (int m = 0; m < 4; ++m) { u16* rowp = O + (size_t)(row0 + ai * 128 + m * 16) * 5632 + col0; const float rs = rsv[ai][m]; f32x4 r[2];
; #pragma unroll
;                 for (int n = 0; n < 2; ++n) { const f32x4 g = acc[ai][0][m][n] * rs, uu = acc[ai][1][m][n] * rs;
; #pragma unroll
;                     for (int e = 0; e < 4; ++e) r[n][e] = siluf(g[e]) * uu[e]; }
;                 *(u32x4*)rowp = __builtin_bit_cast(u32x4, pack8(r[0], r[1])); }
	v_mul_f32_e32 v119, 0xbfb8aa3b, v113
	v_exp_f32_e32 v118, v118
	v_exp_f32_e32 v119, v119
	v_add_f32_e32 v118, 1.0, v118
	v_add_f32_e32 v119, 1.0, v119
	v_rcp_f32_e32 v118, v118
	v_rcp_f32_e32 v119, v119
	s_nop 0
	v_pk_mul_f32 v[112:113], v[112:113], v[118:119]
	s_nop 0
	v_pk_mul_f32 v[118:119], v[114:115], v[112:113]
	v_lshlrev_b64 v[112:113], 1, v[134:135]
	v_lshl_add_u64 v[124:125], v[186:187], 0, v[112:113]
	v_cvt_pk_bf16_f32 v114, v120, v121
	v_cvt_pk_bf16_f32 v115, v122, v123
	v_cvt_pk_bf16_f32 v117, v118, v119
	global_store_dwordx4 v[124:125], v[114:117], off
	s_nop 1
	v_mul_f32_e32 v116, 0xbfb8aa3b, v108
	v_mul_f32_e32 v117, 0xbfb8aa3b, v109
	v_exp_f32_e32 v116, v116
	v_exp_f32_e32 v117, v117
	v_mad_i64_i32 v[114:115], s[4:5], v182, s11, v[132:133]
	v_add_f32_e32 v116, 1.0, v116
	v_add_f32_e32 v117, 1.0, v117
	v_rcp_f32_e32 v116, v116
	v_rcp_f32_e32 v117, v117
	s_nop 0
	v_pk_mul_f32 v[108:109], v[108:109], v[116:117]
	s_nop 0
	v_pk_mul_f32 v[104:105], v[104:105], v[108:109]
	v_pk_mul_f32 v[108:109], v[110:111], v[176:177] op_sel_hi:[1,0]
	s_nop 0
	v_mul_f32_e32 v110, 0xbfb8aa3b, v108
	v_mul_f32_e32 v111, 0xbfb8aa3b, v109
	v_exp_f32_e32 v110, v110
	v_exp_f32_e32 v111, v111
	v_add_f32_e32 v110, 1.0, v110
	v_add_f32_e32 v111, 1.0, v111
	v_rcp_f32_e32 v110, v110
	v_rcp_f32_e32 v111, v111
	s_nop 0
	v_pk_mul_f32 v[108:109], v[108:109], v[110:111]
	s_nop 0
	v_pk_mul_f32 v[106:107], v[106:107], v[108:109]
	v_mul_f32_e32 v108, 0xbfb8aa3b, v100
	v_mul_f32_e32 v109, 0xbfb8aa3b, v101
	v_exp_f32_e32 v108, v108
	v_exp_f32_e32 v109, v109
	v_add_f32_e32 v108, 1.0, v108
	v_add_f32_e32 v109, 1.0, v109
	v_rcp_f32_e32 v108, v108
	v_rcp_f32_e32 v109, v109
	s_nop 0
	v_pk_mul_f32 v[100:101], v[100:101], v[108:109]
	s_nop 0
	v_pk_mul_f32 v[100:101], v[96:97], v[100:101]
	v_pk_mul_f32 v[96:97], v[102:103], v[176:177] op_sel_hi:[1,0]
	v_lshl_add_u64 v[108:109], v[114:115], 0, v[112:113]
	v_mul_f32_e32 v102, 0xbfb8aa3b, v96
	v_mul_f32_e32 v103, 0xbfb8aa3b, v97
	v_exp_f32_e32 v102, v102
	v_exp_f32_e32 v103, v103
	v_add_f32_e32 v102, 1.0, v102
	v_add_f32_e32 v103, 1.0, v103
	v_rcp_f32_e32 v102, v102
	v_rcp_f32_e32 v103, v103
	s_nop 0
	v_pk_mul_f32 v[96:97], v[96:97], v[102:103]
	s_nop 0
	v_pk_mul_f32 v[102:103], v[98:99], v[96:97]
	v_cvt_pk_bf16_f32 v96, v104, v105
	v_cvt_pk_bf16_f32 v97, v106, v107
	v_cvt_pk_bf16_f32 v98, v100, v101
	v_cvt_pk_bf16_f32 v99, v102, v103
	global_store_dwordx4 v[108:109], v[96:99], off
	s_nop 1
	v_mul_f32_e32 v98, 0xbfb8aa3b, v92
	v_mul_f32_e32 v99, 0xbfb8aa3b, v93
	v_exp_f32_e32 v98, v98
	v_exp_f32_e32 v99, v99
	v_mad_i64_i32 v[96:97], s[4:5], v180, s11, v[132:133]
	v_add_f32_e32 v98, 1.0, v98
	v_add_f32_e32 v99, 1.0, v99
	v_rcp_f32_e32 v98, v98
	v_rcp_f32_e32 v99, v99
	s_nop 0
	v_pk_mul_f32 v[92:93], v[92:93], v[98:99]
	s_nop 0
	v_pk_mul_f32 v[88:89], v[88:89], v[92:93]
	v_pk_mul_f32 v[92:93], v[94:95], v[178:179] op_sel_hi:[1,0]
	s_nop 0
	v_mul_f32_e32 v94, 0xbfb8aa3b, v92
	v_mul_f32_e32 v95, 0xbfb8aa3b, v93
	v_exp_f32_e32 v94, v94
	v_exp_f32_e32 v95, v95
	v_add_f32_e32 v94, 1.0, v94
	v_add_f32_e32 v95, 1.0, v95
	v_rcp_f32_e32 v94, v94
	v_rcp_f32_e32 v95, v95
	s_nop 0
	v_pk_mul_f32 v[92:93], v[92:93], v[94:95]
	s_nop 0
	v_pk_mul_f32 v[90:91], v[90:91], v[92:93]
	v_mul_f32_e32 v92, 0xbfb8aa3b, v84
	v_mul_f32_e32 v93, 0xbfb8aa3b, v85
	v_exp_f32_e32 v92, v92
	v_exp_f32_e32 v93, v93
	v_add_f32_e32 v92, 1.0, v92
	v_add_f32_e32 v93, 1.0, v93
	v_rcp_f32_e32 v92, v92
	v_rcp_f32_e32 v93, v93
	s_nop 0
	v_pk_mul_f32 v[84:85], v[84:85], v[92:93]
	s_nop 0
	v_pk_mul_f32 v[84:85], v[80:81], v[84:85]
	v_pk_mul_f32 v[80:81], v[86:87], v[178:179] op_sel_hi:[1,0]
	v_lshl_add_u64 v[92:93], v[96:97], 0, v[112:113]
	v_mul_f32_e32 v86, 0xbfb8aa3b, v80
	v_mul_f32_e32 v87, 0xbfb8aa3b, v81
	v_exp_f32_e32 v86, v86
	v_exp_f32_e32 v87, v87
	v_add_f32_e32 v86, 1.0, v86
	v_add_f32_e32 v87, 1.0, v87
	v_rcp_f32_e32 v86, v86
	v_rcp_f32_e32 v87, v87
	s_nop 0
	v_pk_mul_f32 v[80:81], v[80:81], v[86:87]
	s_nop 0
	v_pk_mul_f32 v[86:87], v[82:83], v[80:81]
	v_cvt_pk_bf16_f32 v80, v88, v89
	v_cvt_pk_bf16_f32 v81, v90, v91
	v_cvt_pk_bf16_f32 v82, v84, v85
	v_cvt_pk_bf16_f32 v83, v86, v87
	global_store_dwordx4 v[92:93], v[80:83], off
	s_nop 1
	v_mul_f32_e32 v82, 0xbfb8aa3b, v76
	v_mul_f32_e32 v83, 0xbfb8aa3b, v77
	v_exp_f32_e32 v82, v82
	v_exp_f32_e32 v83, v83
	v_mad_i64_i32 v[80:81], s[4:5], v174, s11, v[132:133]
	v_add_f32_e32 v82, 1.0, v82
	v_add_f32_e32 v83, 1.0, v83
	v_rcp_f32_e32 v82, v82
	v_rcp_f32_e32 v83, v83
	s_nop 0
	v_pk_mul_f32 v[76:77], v[76:77], v[82:83]
	s_nop 0
	v_pk_mul_f32 v[72:73], v[72:73], v[76:77]
	v_pk_mul_f32 v[76:77], v[78:79], v[154:155] op_sel_hi:[1,0]
	s_nop 0
	v_mul_f32_e32 v78, 0xbfb8aa3b, v76
	v_mul_f32_e32 v79, 0xbfb8aa3b, v77
	v_exp_f32_e32 v78, v78
	v_exp_f32_e32 v79, v79
	v_add_f32_e32 v78, 1.0, v78
	v_add_f32_e32 v79, 1.0, v79
	v_rcp_f32_e32 v78, v78
	v_rcp_f32_e32 v79, v79
	s_nop 0
	v_pk_mul_f32 v[76:77], v[76:77], v[78:79]
	s_nop 0
	v_pk_mul_f32 v[74:75], v[74:75], v[76:77]
	v_mul_f32_e32 v76, 0xbfb8aa3b, v68
	v_mul_f32_e32 v77, 0xbfb8aa3b, v69
	v_exp_f32_e32 v76, v76
	v_exp_f32_e32 v77, v77
	v_add_f32_e32 v76, 1.0, v76
	v_add_f32_e32 v77, 1.0, v77
	v_rcp_f32_e32 v76, v76
	v_rcp_f32_e32 v77, v77
	s_nop 0
	v_pk_mul_f32 v[68:69], v[68:69], v[76:77]
	s_nop 0
	v_pk_mul_f32 v[68:69], v[64:65], v[68:69]
	v_pk_mul_f32 v[64:65], v[70:71], v[154:155] op_sel_hi:[1,0]
	v_lshl_add_u64 v[76:77], v[80:81], 0, v[112:113]
	v_mul_f32_e32 v70, 0xbfb8aa3b, v64
	v_mul_f32_e32 v71, 0xbfb8aa3b, v65
	v_exp_f32_e32 v70, v70
	v_exp_f32_e32 v71, v71
	v_add_f32_e32 v70, 1.0, v70
	v_add_f32_e32 v71, 1.0, v71
	v_rcp_f32_e32 v70, v70
	v_rcp_f32_e32 v71, v71
; DEV float siluf(float x) { return x * __builtin_amdgcn_rcpf(1.0f + __builtin_amdgcn_exp2f(x * -1.4426950408889634f)); }
; DEV bf16x8 pack8(f32x4 a, f32x4 b) { u32x4 w; w.x = cvt_pk_bf16(a[0], a[1]); w.y = cvt_pk_bf16(a[2], a[3]); w.z = cvt_pk_bf16(b[0], b[1]); w.w = cvt_pk_bf16(b[2], b[3]); return __builtin_bit_cast(bf16x8, w); }
;     DEV void operator()(AccRef acc, const pg8::Unit& u, int wr, int wc, int fr, int fq) const {
;     ...
;             for (int m = 0; m < 4; ++m) { u16* rowp = O + (size_t)(row0 + ai * 128 + m * 16) * 5632 + col0; const float rs = rsv[ai][m]; f32x4 r[2];
; #pragma unroll
;                 for (int n = 0; n < 2; ++n) { const f32x4 g = acc[ai][0][m][n] * rs, uu = acc[ai][1][m][n] * rs;
; #pragma unroll
;                     for (int e = 0; e < 4; ++e) r[n][e] = siluf(g[e]) * uu[e]; }
;                 *(u32x4*)rowp = __builtin_bit_cast(u32x4, pack8(r[0], r[1])); }
	s_nop 0
	v_pk_mul_f32 v[64:65], v[64:65], v[70:71]
	s_nop 0
	v_pk_mul_f32 v[70:71], v[66:67], v[64:65]
	v_cvt_pk_bf16_f32 v64, v72, v73
	v_cvt_pk_bf16_f32 v65, v74, v75
	v_cvt_pk_bf16_f32 v66, v68, v69
	v_cvt_pk_bf16_f32 v67, v70, v71
	global_store_dwordx4 v[76:77], v[64:67], off
	s_nop 1
	v_mul_f32_e32 v66, 0xbfb8aa3b, v60
	v_mul_f32_e32 v67, 0xbfb8aa3b, v61
	v_exp_f32_e32 v66, v66
	v_exp_f32_e32 v67, v67
	v_mad_i64_i32 v[64:65], s[4:5], v158, s11, v[132:133]
	v_add_f32_e32 v66, 1.0, v66
	v_add_f32_e32 v67, 1.0, v67
	v_rcp_f32_e32 v66, v66
	v_rcp_f32_e32 v67, v67
	s_nop 0
	v_pk_mul_f32 v[60:61], v[60:61], v[66:67]
	s_nop 0
	v_pk_mul_f32 v[56:57], v[56:57], v[60:61]
	v_pk_mul_f32 v[60:61], v[62:63], v[156:157] op_sel_hi:[1,0]
	s_nop 0
	v_mul_f32_e32 v62, 0xbfb8aa3b, v60
	v_mul_f32_e32 v63, 0xbfb8aa3b, v61
	v_exp_f32_e32 v62, v62
	v_exp_f32_e32 v63, v63
	v_add_f32_e32 v62, 1.0, v62
	v_add_f32_e32 v63, 1.0, v63
	v_rcp_f32_e32 v62, v62
	v_rcp_f32_e32 v63, v63
	s_nop 0
	v_pk_mul_f32 v[60:61], v[60:61], v[62:63]
	s_nop 0
	v_pk_mul_f32 v[58:59], v[58:59], v[60:61]
	v_mul_f32_e32 v60, 0xbfb8aa3b, v52
	v_mul_f32_e32 v61, 0xbfb8aa3b, v53
	v_exp_f32_e32 v60, v60
	v_exp_f32_e32 v61, v61
	v_add_f32_e32 v60, 1.0, v60
	v_add_f32_e32 v61, 1.0, v61
	v_rcp_f32_e32 v60, v60
	v_rcp_f32_e32 v61, v61
	s_nop 0
	v_pk_mul_f32 v[52:53], v[52:53], v[60:61]
	s_nop 0
	v_pk_mul_f32 v[52:53], v[48:49], v[52:53]
	v_pk_mul_f32 v[48:49], v[54:55], v[156:157] op_sel_hi:[1,0]
	v_lshl_add_u64 v[60:61], v[64:65], 0, v[112:113]
	v_mul_f32_e32 v54, 0xbfb8aa3b, v48
	v_mul_f32_e32 v55, 0xbfb8aa3b, v49
	v_exp_f32_e32 v54, v54
	v_exp_f32_e32 v55, v55
	v_add_f32_e32 v54, 1.0, v54
	v_add_f32_e32 v55, 1.0, v55
	v_rcp_f32_e32 v54, v54
	v_rcp_f32_e32 v55, v55
	s_nop 0
	v_pk_mul_f32 v[48:49], v[48:49], v[54:55]
	s_nop 0
	v_pk_mul_f32 v[54:55], v[50:51], v[48:49]
	v_cvt_pk_bf16_f32 v48, v56, v57
	v_cvt_pk_bf16_f32 v49, v58, v59
	v_cvt_pk_bf16_f32 v50, v52, v53
	v_cvt_pk_bf16_f32 v51, v54, v55
	global_store_dwordx4 v[60:61], v[48:51], off
	s_nop 1
	v_mul_f32_e32 v50, 0xbfb8aa3b, v44
	v_mul_f32_e32 v51, 0xbfb8aa3b, v45
	v_exp_f32_e32 v50, v50
	v_exp_f32_e32 v51, v51
	v_mad_i64_i32 v[48:49], s[4:5], v152, s11, v[132:133]
	v_add_f32_e32 v50, 1.0, v50
	v_add_f32_e32 v51, 1.0, v51
	v_rcp_f32_e32 v50, v50
	v_rcp_f32_e32 v51, v51
	s_nop 0
	v_pk_mul_f32 v[44:45], v[44:45], v[50:51]
	s_nop 0
	v_pk_mul_f32 v[40:41], v[40:41], v[44:45]
	v_pk_mul_f32 v[44:45], v[46:47], v[148:149] op_sel_hi:[1,0]
	s_nop 0
	v_mul_f32_e32 v46, 0xbfb8aa3b, v44
	v_mul_f32_e32 v47, 0xbfb8aa3b, v45
	v_exp_f32_e32 v46, v46
	v_exp_f32_e32 v47, v47
	v_add_f32_e32 v46, 1.0, v46
	v_add_f32_e32 v47, 1.0, v47
	v_rcp_f32_e32 v46, v46
	v_rcp_f32_e32 v47, v47
	s_nop 0
	v_pk_mul_f32 v[44:45], v[44:45], v[46:47]
	s_nop 0
	v_pk_mul_f32 v[42:43], v[42:43], v[44:45]
	v_mul_f32_e32 v44, 0xbfb8aa3b, v36
	v_mul_f32_e32 v45, 0xbfb8aa3b, v37
	v_exp_f32_e32 v44, v44
	v_exp_f32_e32 v45, v45
	v_add_f32_e32 v44, 1.0, v44
	v_add_f32_e32 v45, 1.0, v45
	v_rcp_f32_e32 v44, v44
	v_rcp_f32_e32 v45, v45
	s_nop 0
	v_pk_mul_f32 v[36:37], v[36:37], v[44:45]
	s_nop 0
	v_pk_mul_f32 v[36:37], v[32:33], v[36:37]
	v_pk_mul_f32 v[32:33], v[38:39], v[148:149] op_sel_hi:[1,0]
	v_lshl_add_u64 v[44:45], v[48:49], 0, v[112:113]
	v_mul_f32_e32 v38, 0xbfb8aa3b, v32
	v_mul_f32_e32 v39, 0xbfb8aa3b, v33
	v_exp_f32_e32 v38, v38
	v_exp_f32_e32 v39, v39
	v_add_f32_e32 v38, 1.0, v38
	v_add_f32_e32 v39, 1.0, v39
	v_rcp_f32_e32 v38, v38
	v_rcp_f32_e32 v39, v39
	s_nop 0
	v_pk_mul_f32 v[32:33], v[32:33], v[38:39]
	s_nop 0
	v_pk_mul_f32 v[38:39], v[34:35], v[32:33]
	v_cvt_pk_bf16_f32 v32, v40, v41
	v_cvt_pk_bf16_f32 v33, v42, v43
; DEV float siluf(float x) { return x * __builtin_amdgcn_rcpf(1.0f + __builtin_amdgcn_exp2f(x * -1.4426950408889634f)); }
; DEV bf16x8 pack8(f32x4 a, f32x4 b) { u32x4 w; w.x = cvt_pk_bf16(a[0], a[1]); w.y = cvt_pk_bf16(a[2], a[3]); w.z = cvt_pk_bf16(b[0], b[1]); w.w = cvt_pk_bf16(b[2], b[3]); return __builtin_bit_cast(bf16x8, w); }
; #define PG8_WAIT_V(n) asm volatile("s_waitcnt vmcnt(" #n ")" ::: "memory")
; #define PG8_BAR __builtin_amdgcn_s_barrier()
; template <class Epi>
; DEV void gemm_phase(LAS unsigned char* lds, const Gemm g, const StaticOrder& S, const Epi& E) {
;     ...
;         cur = nxt; cA = nA; cB = nB; ++ui;
;     }
;     PG8_WAIT_V(0);
;     if (wr == 0) PG8_BAR;
;     DEV void operator()(AccRef acc, const pg8::Unit& u, int wr, int wc, int fr, int fq) const {
;     ...
;             for (int m = 0; m < 4; ++m) { u16* rowp = O + (size_t)(row0 + ai * 128 + m * 16) * 5632 + col0; const float rs = rsv[ai][m]; f32x4 r[2];
; #pragma unroll
;                 for (int n = 0; n < 2; ++n) { const f32x4 g = acc[ai][0][m][n] * rs, uu = acc[ai][1][m][n] * rs;
; #pragma unroll
;                     for (int e = 0; e < 4; ++e) r[n][e] = siluf(g[e]) * uu[e]; }
;                 *(u32x4*)rowp = __builtin_bit_cast(u32x4, pack8(r[0], r[1])); }
	v_cvt_pk_bf16_f32 v34, v36, v37
	v_cvt_pk_bf16_f32 v35, v38, v39
	global_store_dwordx4 v[44:45], v[32:35], off
	s_nop 1
	v_mul_f32_e32 v34, 0xbfb8aa3b, v28
	v_mul_f32_e32 v35, 0xbfb8aa3b, v29
	v_exp_f32_e32 v34, v34
	v_exp_f32_e32 v35, v35
	v_mad_i64_i32 v[32:33], s[4:5], v150, s11, v[132:133]
	v_add_f32_e32 v34, 1.0, v34
	v_add_f32_e32 v35, 1.0, v35
	v_rcp_f32_e32 v34, v34
	v_rcp_f32_e32 v35, v35
	s_nop 0
	v_pk_mul_f32 v[28:29], v[28:29], v[34:35]
	s_nop 0
	v_pk_mul_f32 v[24:25], v[24:25], v[28:29]
	v_pk_mul_f32 v[28:29], v[30:31], v[130:131] op_sel_hi:[1,0]
	s_nop 0
	v_mul_f32_e32 v30, 0xbfb8aa3b, v28
	v_mul_f32_e32 v31, 0xbfb8aa3b, v29
	v_exp_f32_e32 v30, v30
	v_exp_f32_e32 v31, v31
	v_add_f32_e32 v30, 1.0, v30
	v_add_f32_e32 v31, 1.0, v31
	v_rcp_f32_e32 v30, v30
	v_rcp_f32_e32 v31, v31
	s_nop 0
	v_pk_mul_f32 v[28:29], v[28:29], v[30:31]
	s_nop 0
	v_pk_mul_f32 v[26:27], v[26:27], v[28:29]
	v_mul_f32_e32 v28, 0xbfb8aa3b, v20
	v_mul_f32_e32 v29, 0xbfb8aa3b, v21
	v_exp_f32_e32 v28, v28
	v_exp_f32_e32 v29, v29
	v_add_f32_e32 v28, 1.0, v28
	v_add_f32_e32 v29, 1.0, v29
	v_rcp_f32_e32 v28, v28
	v_rcp_f32_e32 v29, v29
	s_nop 0
	v_pk_mul_f32 v[20:21], v[20:21], v[28:29]
	s_nop 0
	v_pk_mul_f32 v[20:21], v[16:17], v[20:21]
	v_pk_mul_f32 v[16:17], v[22:23], v[130:131] op_sel_hi:[1,0]
	v_lshl_add_u64 v[28:29], v[32:33], 0, v[112:113]
	v_mul_f32_e32 v22, 0xbfb8aa3b, v16
	v_mul_f32_e32 v23, 0xbfb8aa3b, v17
	v_exp_f32_e32 v22, v22
	v_exp_f32_e32 v23, v23
	v_add_f32_e32 v22, 1.0, v22
	v_add_f32_e32 v23, 1.0, v23
	v_rcp_f32_e32 v22, v22
	v_rcp_f32_e32 v23, v23
	s_nop 0
	v_pk_mul_f32 v[16:17], v[16:17], v[22:23]
	s_nop 0
	v_pk_mul_f32 v[22:23], v[18:19], v[16:17]
	v_cvt_pk_bf16_f32 v16, v24, v25
	v_cvt_pk_bf16_f32 v17, v26, v27
	v_cvt_pk_bf16_f32 v18, v20, v21
	v_cvt_pk_bf16_f32 v19, v22, v23
	global_store_dwordx4 v[28:29], v[16:19], off
	s_nop 1
	v_mul_f32_e32 v18, 0xbfb8aa3b, v12
	v_mul_f32_e32 v19, 0xbfb8aa3b, v13
	v_exp_f32_e32 v18, v18
	v_exp_f32_e32 v19, v19
	v_mad_i64_i32 v[16:17], s[4:5], v146, s11, v[132:133]
	v_add_f32_e32 v18, 1.0, v18
	v_add_f32_e32 v19, 1.0, v19
	v_rcp_f32_e32 v18, v18
	v_rcp_f32_e32 v19, v19
	s_mov_b32 s4, s14
	v_pk_mul_f32 v[12:13], v[12:13], v[18:19]
	s_nop 0
	v_pk_mul_f32 v[8:9], v[8:9], v[12:13]
	v_pk_mul_f32 v[12:13], v[14:15], v[128:129] op_sel_hi:[1,0]
	s_nop 0
	v_mul_f32_e32 v14, 0xbfb8aa3b, v12
	v_mul_f32_e32 v15, 0xbfb8aa3b, v13
	v_exp_f32_e32 v14, v14
	v_exp_f32_e32 v15, v15
	v_add_f32_e32 v14, 1.0, v14
	v_add_f32_e32 v15, 1.0, v15
	v_rcp_f32_e32 v14, v14
	v_rcp_f32_e32 v15, v15
	s_nop 0
	v_pk_mul_f32 v[12:13], v[12:13], v[14:15]
	s_nop 0
	v_pk_mul_f32 v[10:11], v[10:11], v[12:13]
	v_mul_f32_e32 v12, 0xbfb8aa3b, v4
	v_mul_f32_e32 v13, 0xbfb8aa3b, v5
	v_exp_f32_e32 v12, v12
	v_exp_f32_e32 v13, v13
	v_add_f32_e32 v12, 1.0, v12
	v_add_f32_e32 v13, 1.0, v13
	v_rcp_f32_e32 v12, v12
	v_rcp_f32_e32 v13, v13
	s_nop 0
	v_pk_mul_f32 v[4:5], v[4:5], v[12:13]
	s_nop 0
	v_pk_mul_f32 v[4:5], v[0:1], v[4:5]
	v_pk_mul_f32 v[0:1], v[6:7], v[128:129] op_sel_hi:[1,0]
	v_lshl_add_u64 v[12:13], v[16:17], 0, v[112:113]
	v_mul_f32_e32 v6, 0xbfb8aa3b, v0
	v_mul_f32_e32 v7, 0xbfb8aa3b, v1
	v_exp_f32_e32 v6, v6
	v_exp_f32_e32 v7, v7
	v_add_f32_e32 v6, 1.0, v6
	v_add_f32_e32 v7, 1.0, v7
	v_rcp_f32_e32 v6, v6
	v_rcp_f32_e32 v7, v7
	s_nop 0
	v_pk_mul_f32 v[0:1], v[0:1], v[6:7]
	s_nop 0
	v_pk_mul_f32 v[6:7], v[2:3], v[0:1]
	v_cvt_pk_bf16_f32 v0, v8, v9
	v_cvt_pk_bf16_f32 v1, v10, v11
	v_cvt_pk_bf16_f32 v2, v4, v5
	v_cvt_pk_bf16_f32 v3, v6, v7
	global_store_dwordx4 v[12:13], v[0:3], off
	s_cbranch_vccz .LBB0_752
	s_waitcnt vmcnt(0)
	s_cmpk_gt_u32 s27, 0xff
	s_cbranch_scc1 .LBB0_759
	s_barrier
